# v29 + GLU/RETQKV/GLA epilogues: all per-row scale/position loads of a tile prefetched at the first block (later blocks use register moves)
# speedup vs baseline: 1.0262x; 1.0074x over previous
; DI unsigned pk(float lo, float hi) { f32x2 v = {lo, hi}; bf2_t b = __builtin_convertvector(v, bf2_t); return __builtin_bit_cast(unsigned, b); }
; DI float sigmoidf_(float x) { return 1.0f / (1.0f + __expf(-x)); }
; DI void gemm_epilogue(const GemmDesc& g, f32x4 (&acc)[2][2][4][2], int brow, int bcol, int wr, int wc, int fr, int fq) {
;     ...
;   } else if (epi == EPI_GLU) {
;     const int ca = 128 * (bcol >> 8) + wc * 32 + 8 * fq;
;     const f32x4 ba0 = gld<f32x4>(g.bias + ca), ba1 = gld<f32x4>(g.bias + ca + 4);
;     const f32x4 bg0 = gld<f32x4>(g.bias + 1024 + ca), bg1 = gld<f32x4>(g.bias + 1024 + ca + 4);
; #pragma unroll
;     for (int ai = 0; ai < 2; ++ai)
; #pragma unroll
;       for (int m = 0; m < 4; ++m) {
;         const int row = rowb + ai * HALF + m * 16;
;         const float ru = gld<float>(g.rowscale + row);
;         const f32x4 a0 = acc[ai][0][m][0] * ru + ba0, a1 = acc[ai][0][m][1] * ru + ba1, t0 = acc[ai][1][m][0] * ru + bg0, t1 = acc[ai][1][m][1] * ru + bg1;
;         float o[8];
; #pragma unroll
;         for (int j = 0; j < 4; ++j) { o[j] = a0[j] * sigmoidf_(t0[j]); o[4 + j] = a1[j] * sigmoidf_(t1[j]); }
;         u32x4 w; w.x = pk(o[0], o[1]); w.y = pk(o[2], o[3]); w.z = pk(o[4], o[5]); w.w = pk(o[6], o[7]);
;         gst<u32x4>(g.o0 + (size_t)row * 1024 + ca, w);
;       }
.LBB0_135:
	s_lshl_b32 s86, s5, 8
	v_lshl_add_u32 v166, s50, 8, v218
	v_or_b32_e32 v164, s86, v158
	s_mov_b64 s[26:27], -1
	s_and_b64 vcc, exec, s[54:55]
	s_cbranch_vccz .LBB0_144
	s_mov_b64 s[48:49], 0
	s_cmp_lt_i32 s92, 3
	s_mov_b64 s[50:51], 0
	s_cbranch_scc1 .LBB0_147
	s_cmp_gt_i32 s92, 3
	s_cbranch_scc0 .LBB0_141
	s_cmp_eq_u32 s92, 4
	s_mov_b64 s[50:51], -1
	s_cbranch_scc0 .LBB0_140
	v_lshl_or_b32 v170, s5, 7, v158
	v_ashrrev_i32_e32 v171, 31, v170
	v_readlane_b32 s26, v255, 39
	v_lshlrev_b64 v[132:133], 2, v[170:171]
	v_readlane_b32 s27, v255, 40
	v_ashrrev_i32_e32 v167, 31, v166
	v_lshl_add_u64 v[134:135], s[76:77], 0, v[132:133]
	v_lshl_add_u64 v[140:141], s[26:27], 0, v[132:133]
	v_lshl_add_u64 v[168:169], v[166:167], 2, s[22:23]
	global_load_dwordx4 v[128:131], v[134:135], off offset:16
	global_load_dwordx4 v[136:139], v[134:135], off
	s_nop 0
	global_load_dwordx4 v[132:135], v[140:141], off offset:16
	s_nop 0
	global_load_dwordx4 v[140:143], v[140:141], off
	s_mov_b64 s[50:51], 0
	global_load_dword v236, v[168:169], off
	global_load_dword v237, v[168:169], off offset:64
	global_load_dword v238, v[168:169], off offset:128
	global_load_dword v239, v[168:169], off offset:192
	global_load_dword v240, v[168:169], off offset:512
	global_load_dword v241, v[168:169], off offset:576
	global_load_dword v242, v[168:169], off offset:640
	global_load_dword v243, v[168:169], off offset:704
	global_load_dword v148, v[168:169], off
	s_waitcnt vmcnt(0)
	v_fma_f32 v165, v60, v148, v140
	v_mul_f32_e32 v165, 0xbfb8aa3b, v165
	v_exp_f32_e32 v172, v165
	v_fma_f32 v165, v56, v148, v132
	v_mul_f32_e32 v165, 0xbfb8aa3b, v165
	v_exp_f32_e32 v174, v165
	v_fma_f32 v165, v61, v148, v141
	v_mul_f32_e32 v165, 0xbfb8aa3b, v165
	v_exp_f32_e32 v173, v165
	v_pk_fma_f32 v[176:177], v[124:125], v[148:149], v[136:137] op_sel_hi:[1,0,1]
	v_pk_add_f32 v[172:173], v[172:173], 1.0 op_sel_hi:[1,0]
	s_nop 0
	v_div_scale_f32 v165, s[26:27], v173, v173, 1.0
	v_rcp_f32_e32 v175, v165
	s_nop 0
	v_fma_f32 v178, -v165, v175, 1.0
	v_fmac_f32_e32 v175, v178, v175
	v_div_scale_f32 v178, vcc, 1.0, v173, 1.0
	v_mul_f32_e32 v179, v178, v175
	v_fma_f32 v180, -v165, v179, v178
	v_fmac_f32_e32 v179, v180, v175
	v_fma_f32 v165, -v165, v179, v178
	v_div_fmas_f32 v165, v165, v175, v179
	v_div_fixup_f32 v173, v165, v173, 1.0
	v_div_scale_f32 v165, s[26:27], v172, v172, 1.0
	v_rcp_f32_e32 v175, v165
	s_nop 0
	v_fma_f32 v178, -v165, v175, 1.0
	v_fmac_f32_e32 v175, v178, v175
	v_div_scale_f32 v178, vcc, 1.0, v172, 1.0
	v_mul_f32_e32 v179, v178, v175
	v_fma_f32 v180, -v165, v179, v178
	v_fmac_f32_e32 v179, v180, v175
	v_fma_f32 v165, -v165, v179, v178
	v_div_fmas_f32 v165, v165, v175, v179
	v_div_fixup_f32 v172, v165, v172, 1.0
	v_fma_f32 v165, v57, v148, v133
	v_mul_f32_e32 v165, 0xbfb8aa3b, v165
	v_exp_f32_e32 v175, v165
	v_pk_mul_f32 v[172:173], v[176:177], v[172:173]
	v_pk_fma_f32 v[176:177], v[120:121], v[148:149], v[128:129] op_sel_hi:[1,0,1]
	v_pk_add_f32 v[174:175], v[174:175], 1.0 op_sel_hi:[1,0]
	s_nop 0
	v_div_scale_f32 v165, s[26:27], v175, v175, 1.0
	v_rcp_f32_e32 v178, v165
	s_nop 0
	v_fma_f32 v179, -v165, v178, 1.0
	v_fmac_f32_e32 v178, v179, v178
	v_div_scale_f32 v179, vcc, 1.0, v175, 1.0
	v_mul_f32_e32 v180, v179, v178
	v_fma_f32 v181, -v165, v180, v179
	v_fmac_f32_e32 v180, v181, v178
	v_fma_f32 v165, -v165, v180, v179
	v_div_fmas_f32 v165, v165, v178, v180
	v_div_fixup_f32 v175, v165, v175, 1.0
	v_div_scale_f32 v165, s[26:27], v174, v174, 1.0
	v_rcp_f32_e32 v178, v165
	s_nop 0
	v_fma_f32 v179, -v165, v178, 1.0
	v_fmac_f32_e32 v178, v179, v178
	v_div_scale_f32 v179, vcc, 1.0, v174, 1.0
	v_mul_f32_e32 v180, v179, v178
	v_fma_f32 v181, -v165, v180, v179
	v_fmac_f32_e32 v180, v181, v178
	v_fma_f32 v165, -v165, v180, v179
	v_div_fmas_f32 v165, v165, v178, v180
	v_div_fixup_f32 v174, v165, v174, 1.0
	v_fma_f32 v165, v62, v148, v142
	v_mul_f32_e32 v165, 0xbfb8aa3b, v165
	v_exp_f32_e32 v180, v165
	v_fma_f32 v165, v58, v148, v134
	v_mul_f32_e32 v165, 0xbfb8aa3b, v165
	v_pk_mul_f32 v[174:175], v[176:177], v[174:175]
	v_exp_f32_e32 v176, v165
	v_fma_f32 v165, v63, v148, v143
	v_mul_f32_e32 v165, 0xbfb8aa3b, v165
	v_exp_f32_e32 v181, v165
	v_pk_fma_f32 v[178:179], v[126:127], v[148:149], v[138:139] op_sel_hi:[1,0,1]
	v_pk_add_f32 v[180:181], v[180:181], 1.0 op_sel_hi:[1,0]
	s_nop 0
	v_div_scale_f32 v165, s[26:27], v181, v181, 1.0
	v_rcp_f32_e32 v177, v165
	s_nop 0
	v_fma_f32 v182, -v165, v177, 1.0
	v_fmac_f32_e32 v177, v182, v177
	v_div_scale_f32 v182, vcc, 1.0, v181, 1.0
	v_mul_f32_e32 v183, v182, v177
	v_fma_f32 v184, -v165, v183, v182
	v_fmac_f32_e32 v183, v184, v177
	v_fma_f32 v165, -v165, v183, v182
	v_div_fmas_f32 v165, v165, v177, v183
	v_div_fixup_f32 v181, v165, v181, 1.0
	v_div_scale_f32 v165, s[26:27], v180, v180, 1.0
	v_rcp_f32_e32 v177, v165
	s_nop 0
	v_fma_f32 v182, -v165, v177, 1.0
	v_fmac_f32_e32 v177, v182, v177
	v_div_scale_f32 v182, vcc, 1.0, v180, 1.0
	v_mul_f32_e32 v183, v182, v177
	v_fma_f32 v184, -v165, v183, v182
	v_fmac_f32_e32 v183, v184, v177
	v_fma_f32 v165, -v165, v183, v182
	v_div_fmas_f32 v165, v165, v177, v183
	v_div_fixup_f32 v180, v165, v180, 1.0
	v_fma_f32 v165, v59, v148, v135
	v_mul_f32_e32 v165, 0xbfb8aa3b, v165
	v_exp_f32_e32 v177, v165
	v_pk_mul_f32 v[178:179], v[178:179], v[180:181]
	v_pk_fma_f32 v[180:181], v[122:123], v[148:149], v[130:131] op_sel_hi:[1,0,1]
	v_pk_add_f32 v[176:177], v[176:177], 1.0 op_sel_hi:[1,0]
	s_nop 0
	v_div_scale_f32 v148, s[26:27], v177, v177, 1.0
	v_rcp_f32_e32 v165, v148
	s_nop 0
	v_fma_f32 v182, -v148, v165, 1.0
	v_fmac_f32_e32 v165, v182, v165
	v_div_scale_f32 v182, vcc, 1.0, v177, 1.0
	v_mul_f32_e32 v183, v182, v165
	v_fma_f32 v184, -v148, v183, v182
	v_fmac_f32_e32 v183, v184, v165
	v_fma_f32 v148, -v148, v183, v182
	v_div_fmas_f32 v148, v148, v165, v183
	v_div_fixup_f32 v177, v148, v177, 1.0
	v_div_scale_f32 v148, s[26:27], v176, v176, 1.0
	v_rcp_f32_e32 v165, v148
	s_nop 0
	v_fma_f32 v182, -v148, v165, 1.0
	v_fmac_f32_e32 v165, v182, v165
	v_div_scale_f32 v182, vcc, 1.0, v176, 1.0
	v_mul_f32_e32 v183, v182, v165
	v_fma_f32 v184, -v148, v183, v182
	v_fmac_f32_e32 v183, v184, v165
	v_fma_f32 v148, -v148, v183, v182
	v_div_fmas_f32 v148, v148, v165, v183
	v_div_fixup_f32 v176, v148, v176, 1.0
	v_pk_mul_f32 v[180:181], v[180:181], v[176:177]
	v_cvt_pk_bf16_f32 v176, v172, v173
	v_lshlrev_b64 v[172:173], 11, v[166:167]
	v_cvt_pk_bf16_f32 v177, v178, v179
	v_cvt_pk_bf16_f32 v178, v174, v175
	v_lshl_add_u64 v[174:175], s[64:65], 0, v[172:173]
	v_lshlrev_b64 v[172:173], 1, v[170:171]
	v_cvt_pk_bf16_f32 v179, v180, v181
	v_lshl_add_u64 v[170:171], v[174:175], 0, v[172:173]
	global_store_dwordx4 v[170:171], v[176:179], off
	s_nop 1
	v_mov_b32_e32 v148, v237
	v_or_b32_e32 v174, 16, v166
	v_ashrrev_i32_e32 v175, 31, v174
	v_lshlrev_b64 v[174:175], 11, v[174:175]
	v_lshl_add_u64 v[174:175], s[64:65], 0, v[174:175]
	v_lshl_add_u64 v[174:175], v[174:175], 0, v[172:173]
	s_waitcnt vmcnt(0)
; DI unsigned pk(float lo, float hi) { f32x2 v = {lo, hi}; bf2_t b = __builtin_convertvector(v, bf2_t); return __builtin_bit_cast(unsigned, b); }
; DI float sigmoidf_(float x) { return 1.0f / (1.0f + __expf(-x)); }
; DI void gemm_epilogue(const GemmDesc& g, f32x4 (&acc)[2][2][4][2], int brow, int bcol, int wr, int wc, int fr, int fq) {
;     ...
;       for (int m = 0; m < 4; ++m) {
;         const int row = rowb + ai * HALF + m * 16;
;         const float ru = gld<float>(g.rowscale + row);
;         const f32x4 a0 = acc[ai][0][m][0] * ru + ba0, a1 = acc[ai][0][m][1] * ru + ba1, t0 = acc[ai][1][m][0] * ru + bg0, t1 = acc[ai][1][m][1] * ru + bg1;
;         float o[8];
; #pragma unroll
;         for (int j = 0; j < 4; ++j) { o[j] = a0[j] * sigmoidf_(t0[j]); o[4 + j] = a1[j] * sigmoidf_(t1[j]); }
;         u32x4 w; w.x = pk(o[0], o[1]); w.y = pk(o[2], o[3]); w.z = pk(o[4], o[5]); w.w = pk(o[6], o[7]);
;         gst<u32x4>(g.o0 + (size_t)row * 1024 + ca, w);
	v_fma_f32 v165, v52, v148, v140
	v_mul_f32_e32 v165, 0xbfb8aa3b, v165
	v_exp_f32_e32 v176, v165
	v_fma_f32 v165, v48, v148, v132
	v_mul_f32_e32 v165, 0xbfb8aa3b, v165
	v_exp_f32_e32 v178, v165
	v_fma_f32 v165, v53, v148, v141
	v_mul_f32_e32 v165, 0xbfb8aa3b, v165
	v_exp_f32_e32 v177, v165
	v_pk_fma_f32 v[180:181], v[116:117], v[148:149], v[136:137] op_sel_hi:[1,0,1]
	v_pk_add_f32 v[176:177], v[176:177], 1.0 op_sel_hi:[1,0]
	s_nop 0
	v_div_scale_f32 v165, s[26:27], v177, v177, 1.0
	v_rcp_f32_e32 v167, v165
	s_nop 0
	v_fma_f32 v179, -v165, v167, 1.0
	v_fmac_f32_e32 v167, v179, v167
	v_div_scale_f32 v179, vcc, 1.0, v177, 1.0
	v_mul_f32_e32 v182, v179, v167
	v_fma_f32 v183, -v165, v182, v179
	v_fmac_f32_e32 v182, v183, v167
	v_fma_f32 v165, -v165, v182, v179
	v_div_fmas_f32 v165, v165, v167, v182
	v_div_fixup_f32 v177, v165, v177, 1.0
	v_div_scale_f32 v165, s[26:27], v176, v176, 1.0
	v_rcp_f32_e32 v167, v165
	s_nop 0
	v_fma_f32 v179, -v165, v167, 1.0
	v_fmac_f32_e32 v167, v179, v167
	v_div_scale_f32 v179, vcc, 1.0, v176, 1.0
	v_mul_f32_e32 v182, v179, v167
	v_fma_f32 v183, -v165, v182, v179
	v_fmac_f32_e32 v182, v183, v167
	v_fma_f32 v165, -v165, v182, v179
	v_div_fmas_f32 v165, v165, v167, v182
	v_div_fixup_f32 v176, v165, v176, 1.0
	v_fma_f32 v165, v49, v148, v133
	v_mul_f32_e32 v165, 0xbfb8aa3b, v165
	v_exp_f32_e32 v179, v165
	v_pk_mul_f32 v[176:177], v[180:181], v[176:177]
	v_pk_fma_f32 v[180:181], v[112:113], v[148:149], v[128:129] op_sel_hi:[1,0,1]
	v_cvt_pk_bf16_f32 v176, v176, v177
	v_pk_add_f32 v[178:179], v[178:179], 1.0 op_sel_hi:[1,0]
	s_nop 0
	v_div_scale_f32 v165, s[26:27], v179, v179, 1.0
	v_rcp_f32_e32 v167, v165
	s_nop 0
	v_fma_f32 v182, -v165, v167, 1.0
	v_fmac_f32_e32 v167, v182, v167
	v_div_scale_f32 v182, vcc, 1.0, v179, 1.0
	v_mul_f32_e32 v183, v182, v167
	v_fma_f32 v184, -v165, v183, v182
	v_fmac_f32_e32 v183, v184, v167
	v_fma_f32 v165, -v165, v183, v182
	v_div_fmas_f32 v165, v165, v167, v183
	v_div_fixup_f32 v179, v165, v179, 1.0
	v_div_scale_f32 v165, s[26:27], v178, v178, 1.0
	v_rcp_f32_e32 v167, v165
	s_nop 0
	v_fma_f32 v182, -v165, v167, 1.0
	v_fmac_f32_e32 v167, v182, v167
	v_div_scale_f32 v182, vcc, 1.0, v178, 1.0
	v_mul_f32_e32 v183, v182, v167
	v_fma_f32 v184, -v165, v183, v182
	v_fmac_f32_e32 v183, v184, v167
	v_fma_f32 v165, -v165, v183, v182
	v_div_fmas_f32 v165, v165, v167, v183
	v_div_fixup_f32 v178, v165, v178, 1.0
	v_fma_f32 v165, v54, v148, v142
	v_mul_f32_e32 v165, 0xbfb8aa3b, v165
	v_pk_mul_f32 v[178:179], v[180:181], v[178:179]
	v_exp_f32_e32 v180, v165
	v_fma_f32 v165, v50, v148, v134
	v_mul_f32_e32 v165, 0xbfb8aa3b, v165
	v_exp_f32_e32 v182, v165
	v_fma_f32 v165, v55, v148, v143
	v_mul_f32_e32 v165, 0xbfb8aa3b, v165
	v_exp_f32_e32 v181, v165
	v_pk_fma_f32 v[184:185], v[118:119], v[148:149], v[138:139] op_sel_hi:[1,0,1]
	v_cvt_pk_bf16_f32 v178, v178, v179
	v_pk_add_f32 v[180:181], v[180:181], 1.0 op_sel_hi:[1,0]
	s_nop 0
	v_div_scale_f32 v165, s[26:27], v181, v181, 1.0
	v_rcp_f32_e32 v167, v165
	s_nop 0
	v_fma_f32 v183, -v165, v167, 1.0
	v_fmac_f32_e32 v167, v183, v167
	v_div_scale_f32 v183, vcc, 1.0, v181, 1.0
	v_mul_f32_e32 v186, v183, v167
	v_fma_f32 v187, -v165, v186, v183
	v_fmac_f32_e32 v186, v187, v167
	v_fma_f32 v165, -v165, v186, v183
	v_div_fmas_f32 v165, v165, v167, v186
	v_div_fixup_f32 v181, v165, v181, 1.0
	v_div_scale_f32 v165, s[26:27], v180, v180, 1.0
	v_rcp_f32_e32 v167, v165
	s_nop 0
	v_fma_f32 v183, -v165, v167, 1.0
	v_fmac_f32_e32 v167, v183, v167
	v_div_scale_f32 v183, vcc, 1.0, v180, 1.0
	v_mul_f32_e32 v186, v183, v167
	v_fma_f32 v187, -v165, v186, v183
	v_fmac_f32_e32 v186, v187, v167
	v_fma_f32 v165, -v165, v186, v183
	v_div_fmas_f32 v165, v165, v167, v186
	v_div_fixup_f32 v180, v165, v180, 1.0
	v_fma_f32 v165, v51, v148, v135
	v_mul_f32_e32 v165, 0xbfb8aa3b, v165
	v_exp_f32_e32 v183, v165
	v_pk_mul_f32 v[180:181], v[184:185], v[180:181]
	v_pk_fma_f32 v[184:185], v[114:115], v[148:149], v[130:131] op_sel_hi:[1,0,1]
	v_cvt_pk_bf16_f32 v177, v180, v181
	v_pk_add_f32 v[182:183], v[182:183], 1.0 op_sel_hi:[1,0]
	s_nop 0
	v_div_scale_f32 v148, s[26:27], v183, v183, 1.0
	v_rcp_f32_e32 v165, v148
	s_nop 0
	v_fma_f32 v167, -v148, v165, 1.0
	v_fmac_f32_e32 v165, v167, v165
	v_div_scale_f32 v167, vcc, 1.0, v183, 1.0
	v_mul_f32_e32 v186, v167, v165
	v_fma_f32 v187, -v148, v186, v167
	v_fmac_f32_e32 v186, v187, v165
	v_fma_f32 v148, -v148, v186, v167
	v_div_fmas_f32 v148, v148, v165, v186
	v_div_fixup_f32 v183, v148, v183, 1.0
	v_div_scale_f32 v148, s[26:27], v182, v182, 1.0
	v_rcp_f32_e32 v165, v148
	s_nop 0
	v_fma_f32 v167, -v148, v165, 1.0
	v_fmac_f32_e32 v165, v167, v165
	v_div_scale_f32 v167, vcc, 1.0, v182, 1.0
	v_mul_f32_e32 v186, v167, v165
	v_fma_f32 v187, -v148, v186, v167
	v_fmac_f32_e32 v186, v187, v165
	v_fma_f32 v148, -v148, v186, v167
	v_div_fmas_f32 v148, v148, v165, v186
	v_div_fixup_f32 v182, v148, v182, 1.0
	v_pk_mul_f32 v[182:183], v[184:185], v[182:183]
	s_nop 0
	v_cvt_pk_bf16_f32 v179, v182, v183
	global_store_dwordx4 v[174:175], v[176:179], off
	s_nop 1
	v_mov_b32_e32 v148, v238
	v_or_b32_e32 v174, 32, v166
	v_ashrrev_i32_e32 v175, 31, v174
	v_lshlrev_b64 v[174:175], 11, v[174:175]
	v_lshl_add_u64 v[174:175], s[64:65], 0, v[174:175]
	v_lshl_add_u64 v[174:175], v[174:175], 0, v[172:173]
	s_waitcnt vmcnt(0)
; DI unsigned pk(float lo, float hi) { f32x2 v = {lo, hi}; bf2_t b = __builtin_convertvector(v, bf2_t); return __builtin_bit_cast(unsigned, b); }
; DI float sigmoidf_(float x) { return 1.0f / (1.0f + __expf(-x)); }
; DI void gemm_epilogue(const GemmDesc& g, f32x4 (&acc)[2][2][4][2], int brow, int bcol, int wr, int wc, int fr, int fq) {
;     ...
;       for (int m = 0; m < 4; ++m) {
;         const int row = rowb + ai * HALF + m * 16;
;         const float ru = gld<float>(g.rowscale + row);
;         const f32x4 a0 = acc[ai][0][m][0] * ru + ba0, a1 = acc[ai][0][m][1] * ru + ba1, t0 = acc[ai][1][m][0] * ru + bg0, t1 = acc[ai][1][m][1] * ru + bg1;
;         float o[8];
; #pragma unroll
;         for (int j = 0; j < 4; ++j) { o[j] = a0[j] * sigmoidf_(t0[j]); o[4 + j] = a1[j] * sigmoidf_(t1[j]); }
;         u32x4 w; w.x = pk(o[0], o[1]); w.y = pk(o[2], o[3]); w.z = pk(o[4], o[5]); w.w = pk(o[6], o[7]);
;         gst<u32x4>(g.o0 + (size_t)row * 1024 + ca, w);
	v_fma_f32 v165, v44, v148, v140
	v_mul_f32_e32 v165, 0xbfb8aa3b, v165
	v_exp_f32_e32 v176, v165
	v_fma_f32 v165, v40, v148, v132
	v_mul_f32_e32 v165, 0xbfb8aa3b, v165
	v_exp_f32_e32 v178, v165
	v_fma_f32 v165, v45, v148, v141
	v_mul_f32_e32 v165, 0xbfb8aa3b, v165
	v_exp_f32_e32 v177, v165
	v_pk_fma_f32 v[180:181], v[108:109], v[148:149], v[136:137] op_sel_hi:[1,0,1]
	v_pk_add_f32 v[176:177], v[176:177], 1.0 op_sel_hi:[1,0]
	s_nop 0
	v_div_scale_f32 v165, s[26:27], v177, v177, 1.0
	v_rcp_f32_e32 v167, v165
	s_nop 0
	v_fma_f32 v179, -v165, v167, 1.0
	v_fmac_f32_e32 v167, v179, v167
	v_div_scale_f32 v179, vcc, 1.0, v177, 1.0
	v_mul_f32_e32 v182, v179, v167
	v_fma_f32 v183, -v165, v182, v179
	v_fmac_f32_e32 v182, v183, v167
	v_fma_f32 v165, -v165, v182, v179
	v_div_fmas_f32 v165, v165, v167, v182
	v_div_fixup_f32 v177, v165, v177, 1.0
	v_div_scale_f32 v165, s[26:27], v176, v176, 1.0
	v_rcp_f32_e32 v167, v165
	s_nop 0
	v_fma_f32 v179, -v165, v167, 1.0
	v_fmac_f32_e32 v167, v179, v167
	v_div_scale_f32 v179, vcc, 1.0, v176, 1.0
	v_mul_f32_e32 v182, v179, v167
	v_fma_f32 v183, -v165, v182, v179
	v_fmac_f32_e32 v182, v183, v167
	v_fma_f32 v165, -v165, v182, v179
	v_div_fmas_f32 v165, v165, v167, v182
	v_div_fixup_f32 v176, v165, v176, 1.0
	v_fma_f32 v165, v41, v148, v133
	v_mul_f32_e32 v165, 0xbfb8aa3b, v165
	v_exp_f32_e32 v179, v165
	v_pk_mul_f32 v[176:177], v[180:181], v[176:177]
	v_pk_fma_f32 v[180:181], v[104:105], v[148:149], v[128:129] op_sel_hi:[1,0,1]
	v_cvt_pk_bf16_f32 v176, v176, v177
	v_pk_add_f32 v[178:179], v[178:179], 1.0 op_sel_hi:[1,0]
	s_nop 0
	v_div_scale_f32 v165, s[26:27], v179, v179, 1.0
	v_rcp_f32_e32 v167, v165
	s_nop 0
	v_fma_f32 v182, -v165, v167, 1.0
	v_fmac_f32_e32 v167, v182, v167
	v_div_scale_f32 v182, vcc, 1.0, v179, 1.0
	v_mul_f32_e32 v183, v182, v167
	v_fma_f32 v184, -v165, v183, v182
	v_fmac_f32_e32 v183, v184, v167
	v_fma_f32 v165, -v165, v183, v182
	v_div_fmas_f32 v165, v165, v167, v183
	v_div_fixup_f32 v179, v165, v179, 1.0
	v_div_scale_f32 v165, s[26:27], v178, v178, 1.0
	v_rcp_f32_e32 v167, v165
	s_nop 0
	v_fma_f32 v182, -v165, v167, 1.0
	v_fmac_f32_e32 v167, v182, v167
	v_div_scale_f32 v182, vcc, 1.0, v178, 1.0
	v_mul_f32_e32 v183, v182, v167
	v_fma_f32 v184, -v165, v183, v182
	v_fmac_f32_e32 v183, v184, v167
	v_fma_f32 v165, -v165, v183, v182
	v_div_fmas_f32 v165, v165, v167, v183
	v_div_fixup_f32 v178, v165, v178, 1.0
	v_fma_f32 v165, v46, v148, v142
	v_mul_f32_e32 v165, 0xbfb8aa3b, v165
	v_pk_mul_f32 v[178:179], v[180:181], v[178:179]
	v_exp_f32_e32 v180, v165
	v_fma_f32 v165, v42, v148, v134
	v_mul_f32_e32 v165, 0xbfb8aa3b, v165
	v_exp_f32_e32 v182, v165
	v_fma_f32 v165, v47, v148, v143
	v_mul_f32_e32 v165, 0xbfb8aa3b, v165
	v_exp_f32_e32 v181, v165
	v_pk_fma_f32 v[184:185], v[110:111], v[148:149], v[138:139] op_sel_hi:[1,0,1]
	v_cvt_pk_bf16_f32 v178, v178, v179
	v_pk_add_f32 v[180:181], v[180:181], 1.0 op_sel_hi:[1,0]
	s_nop 0
	v_div_scale_f32 v165, s[26:27], v181, v181, 1.0
	v_rcp_f32_e32 v167, v165
	s_nop 0
	v_fma_f32 v183, -v165, v167, 1.0
	v_fmac_f32_e32 v167, v183, v167
	v_div_scale_f32 v183, vcc, 1.0, v181, 1.0
	v_mul_f32_e32 v186, v183, v167
	v_fma_f32 v187, -v165, v186, v183
	v_fmac_f32_e32 v186, v187, v167
	v_fma_f32 v165, -v165, v186, v183
	v_div_fmas_f32 v165, v165, v167, v186
	v_div_fixup_f32 v181, v165, v181, 1.0
	v_div_scale_f32 v165, s[26:27], v180, v180, 1.0
	v_rcp_f32_e32 v167, v165
	s_nop 0
	v_fma_f32 v183, -v165, v167, 1.0
	v_fmac_f32_e32 v167, v183, v167
	v_div_scale_f32 v183, vcc, 1.0, v180, 1.0
	v_mul_f32_e32 v186, v183, v167
	v_fma_f32 v187, -v165, v186, v183
	v_fmac_f32_e32 v186, v187, v167
	v_fma_f32 v165, -v165, v186, v183
	v_div_fmas_f32 v165, v165, v167, v186
	v_div_fixup_f32 v180, v165, v180, 1.0
	v_fma_f32 v165, v43, v148, v135
	v_mul_f32_e32 v165, 0xbfb8aa3b, v165
	v_exp_f32_e32 v183, v165
	v_pk_mul_f32 v[180:181], v[184:185], v[180:181]
	v_pk_fma_f32 v[184:185], v[106:107], v[148:149], v[130:131] op_sel_hi:[1,0,1]
	v_cvt_pk_bf16_f32 v177, v180, v181
	v_pk_add_f32 v[182:183], v[182:183], 1.0 op_sel_hi:[1,0]
	s_nop 0
	v_div_scale_f32 v148, s[26:27], v183, v183, 1.0
	v_rcp_f32_e32 v165, v148
	s_nop 0
	v_fma_f32 v167, -v148, v165, 1.0
	v_fmac_f32_e32 v165, v167, v165
	v_div_scale_f32 v167, vcc, 1.0, v183, 1.0
	v_mul_f32_e32 v186, v167, v165
	v_fma_f32 v187, -v148, v186, v167
	v_fmac_f32_e32 v186, v187, v165
	v_fma_f32 v148, -v148, v186, v167
	v_div_fmas_f32 v148, v148, v165, v186
	v_div_fixup_f32 v183, v148, v183, 1.0
	v_div_scale_f32 v148, s[26:27], v182, v182, 1.0
	v_rcp_f32_e32 v165, v148
	s_nop 0
	v_fma_f32 v167, -v148, v165, 1.0
	v_fmac_f32_e32 v165, v167, v165
	v_div_scale_f32 v167, vcc, 1.0, v182, 1.0
	v_mul_f32_e32 v186, v167, v165
	v_fma_f32 v187, -v148, v186, v167
	v_fmac_f32_e32 v186, v187, v165
	v_fma_f32 v148, -v148, v186, v167
	v_div_fmas_f32 v148, v148, v165, v186
	v_div_fixup_f32 v182, v148, v182, 1.0
	v_pk_mul_f32 v[182:183], v[184:185], v[182:183]
	s_nop 0
	v_cvt_pk_bf16_f32 v179, v182, v183
	global_store_dwordx4 v[174:175], v[176:179], off
	s_nop 1
	v_mov_b32_e32 v148, v239
	v_or_b32_e32 v174, 48, v166
	v_ashrrev_i32_e32 v175, 31, v174
	v_lshlrev_b64 v[174:175], 11, v[174:175]
	v_lshl_add_u64 v[174:175], s[64:65], 0, v[174:175]
	v_lshl_add_u64 v[172:173], v[174:175], 0, v[172:173]
	s_waitcnt vmcnt(0)
; DI unsigned pk(float lo, float hi) { f32x2 v = {lo, hi}; bf2_t b = __builtin_convertvector(v, bf2_t); return __builtin_bit_cast(unsigned, b); }
; DI float sigmoidf_(float x) { return 1.0f / (1.0f + __expf(-x)); }
; DI void gemm_epilogue(const GemmDesc& g, f32x4 (&acc)[2][2][4][2], int brow, int bcol, int wr, int wc, int fr, int fq) {
;     ...
;       for (int m = 0; m < 4; ++m) {
;         const int row = rowb + ai * HALF + m * 16;
;         const float ru = gld<float>(g.rowscale + row);
;         const f32x4 a0 = acc[ai][0][m][0] * ru + ba0, a1 = acc[ai][0][m][1] * ru + ba1, t0 = acc[ai][1][m][0] * ru + bg0, t1 = acc[ai][1][m][1] * ru + bg1;
;         float o[8];
; #pragma unroll
;         for (int j = 0; j < 4; ++j) { o[j] = a0[j] * sigmoidf_(t0[j]); o[4 + j] = a1[j] * sigmoidf_(t1[j]); }
;         u32x4 w; w.x = pk(o[0], o[1]); w.y = pk(o[2], o[3]); w.z = pk(o[4], o[5]); w.w = pk(o[6], o[7]);
;         gst<u32x4>(g.o0 + (size_t)row * 1024 + ca, w);
	v_fma_f32 v165, v36, v148, v140
	v_mul_f32_e32 v165, 0xbfb8aa3b, v165
	v_exp_f32_e32 v176, v165
	v_fma_f32 v165, v32, v148, v132
	v_mul_f32_e32 v165, 0xbfb8aa3b, v165
	v_exp_f32_e32 v178, v165
	v_fma_f32 v165, v37, v148, v141
	v_mul_f32_e32 v165, 0xbfb8aa3b, v165
	v_exp_f32_e32 v177, v165
	v_pk_fma_f32 v[180:181], v[100:101], v[148:149], v[136:137] op_sel_hi:[1,0,1]
	v_pk_add_f32 v[176:177], v[176:177], 1.0 op_sel_hi:[1,0]
	s_nop 0
	v_div_scale_f32 v165, s[26:27], v177, v177, 1.0
	v_rcp_f32_e32 v167, v165
	s_nop 0
	v_fma_f32 v179, -v165, v167, 1.0
	v_fmac_f32_e32 v167, v179, v167
	v_div_scale_f32 v179, vcc, 1.0, v177, 1.0
	v_mul_f32_e32 v182, v179, v167
	v_fma_f32 v183, -v165, v182, v179
	v_fmac_f32_e32 v182, v183, v167
	v_fma_f32 v165, -v165, v182, v179
	v_div_fmas_f32 v165, v165, v167, v182
	v_div_fixup_f32 v177, v165, v177, 1.0
	v_div_scale_f32 v165, s[26:27], v176, v176, 1.0
	v_rcp_f32_e32 v167, v165
	s_nop 0
	v_fma_f32 v179, -v165, v167, 1.0
	v_fmac_f32_e32 v167, v179, v167
	v_div_scale_f32 v179, vcc, 1.0, v176, 1.0
	v_mul_f32_e32 v182, v179, v167
	v_fma_f32 v183, -v165, v182, v179
	v_fmac_f32_e32 v182, v183, v167
	v_fma_f32 v165, -v165, v182, v179
	v_div_fmas_f32 v165, v165, v167, v182
	v_div_fixup_f32 v176, v165, v176, 1.0
	v_fma_f32 v165, v33, v148, v133
	v_mul_f32_e32 v165, 0xbfb8aa3b, v165
	v_exp_f32_e32 v179, v165
	v_pk_mul_f32 v[176:177], v[180:181], v[176:177]
	v_pk_fma_f32 v[180:181], v[96:97], v[148:149], v[128:129] op_sel_hi:[1,0,1]
	v_cvt_pk_bf16_f32 v176, v176, v177
	v_pk_add_f32 v[178:179], v[178:179], 1.0 op_sel_hi:[1,0]
	s_nop 0
	v_div_scale_f32 v165, s[26:27], v179, v179, 1.0
	v_rcp_f32_e32 v167, v165
	s_nop 0
	v_fma_f32 v182, -v165, v167, 1.0
	v_fmac_f32_e32 v167, v182, v167
	v_div_scale_f32 v182, vcc, 1.0, v179, 1.0
	v_mul_f32_e32 v183, v182, v167
	v_fma_f32 v184, -v165, v183, v182
	v_fmac_f32_e32 v183, v184, v167
	v_fma_f32 v165, -v165, v183, v182
	v_div_fmas_f32 v165, v165, v167, v183
	v_div_fixup_f32 v179, v165, v179, 1.0
	v_div_scale_f32 v165, s[26:27], v178, v178, 1.0
	v_rcp_f32_e32 v167, v165
	s_nop 0
	v_fma_f32 v182, -v165, v167, 1.0
	v_fmac_f32_e32 v167, v182, v167
	v_div_scale_f32 v182, vcc, 1.0, v178, 1.0
	v_mul_f32_e32 v183, v182, v167
	v_fma_f32 v184, -v165, v183, v182
	v_fmac_f32_e32 v183, v184, v167
	v_fma_f32 v165, -v165, v183, v182
	v_div_fmas_f32 v165, v165, v167, v183
	v_div_fixup_f32 v178, v165, v178, 1.0
	v_fma_f32 v165, v38, v148, v142
	v_mul_f32_e32 v165, 0xbfb8aa3b, v165
	v_pk_mul_f32 v[178:179], v[180:181], v[178:179]
	v_exp_f32_e32 v180, v165
	v_fma_f32 v165, v34, v148, v134
	v_mul_f32_e32 v165, 0xbfb8aa3b, v165
	v_exp_f32_e32 v182, v165
	v_fma_f32 v165, v39, v148, v143
	v_mul_f32_e32 v165, 0xbfb8aa3b, v165
	v_exp_f32_e32 v181, v165
	v_pk_fma_f32 v[184:185], v[102:103], v[148:149], v[138:139] op_sel_hi:[1,0,1]
	v_cvt_pk_bf16_f32 v178, v178, v179
	v_pk_add_f32 v[180:181], v[180:181], 1.0 op_sel_hi:[1,0]
	s_nop 0
	v_div_scale_f32 v165, s[26:27], v181, v181, 1.0
	v_rcp_f32_e32 v167, v165
	s_nop 0
	v_fma_f32 v183, -v165, v167, 1.0
	v_fmac_f32_e32 v167, v183, v167
	v_div_scale_f32 v183, vcc, 1.0, v181, 1.0
	v_mul_f32_e32 v186, v183, v167
	v_fma_f32 v187, -v165, v186, v183
	v_fmac_f32_e32 v186, v187, v167
	v_fma_f32 v165, -v165, v186, v183
	v_div_fmas_f32 v165, v165, v167, v186
	v_div_fixup_f32 v181, v165, v181, 1.0
	v_div_scale_f32 v165, s[26:27], v180, v180, 1.0
	v_rcp_f32_e32 v167, v165
	s_nop 0
	v_fma_f32 v183, -v165, v167, 1.0
	v_fmac_f32_e32 v167, v183, v167
	v_div_scale_f32 v183, vcc, 1.0, v180, 1.0
	v_mul_f32_e32 v186, v183, v167
	v_fma_f32 v187, -v165, v186, v183
	v_fmac_f32_e32 v186, v187, v167
	v_fma_f32 v165, -v165, v186, v183
	v_div_fmas_f32 v165, v165, v167, v186
	v_div_fixup_f32 v180, v165, v180, 1.0
	v_fma_f32 v165, v35, v148, v135
	v_mul_f32_e32 v165, 0xbfb8aa3b, v165
	v_exp_f32_e32 v183, v165
	v_pk_mul_f32 v[180:181], v[184:185], v[180:181]
	v_pk_fma_f32 v[184:185], v[98:99], v[148:149], v[130:131] op_sel_hi:[1,0,1]
	v_cvt_pk_bf16_f32 v177, v180, v181
	v_pk_add_f32 v[182:183], v[182:183], 1.0 op_sel_hi:[1,0]
	s_nop 0
	v_div_scale_f32 v148, s[26:27], v183, v183, 1.0
	v_rcp_f32_e32 v165, v148
	s_nop 0
	v_fma_f32 v167, -v148, v165, 1.0
	v_fmac_f32_e32 v165, v167, v165
	v_div_scale_f32 v167, vcc, 1.0, v183, 1.0
	v_mul_f32_e32 v186, v167, v165
	v_fma_f32 v187, -v148, v186, v167
	v_fmac_f32_e32 v186, v187, v165
	v_fma_f32 v148, -v148, v186, v167
	v_div_fmas_f32 v148, v148, v165, v186
	v_div_fixup_f32 v183, v148, v183, 1.0
	v_div_scale_f32 v148, s[26:27], v182, v182, 1.0
	v_rcp_f32_e32 v165, v148
	s_nop 0
	v_fma_f32 v167, -v148, v165, 1.0
	v_fmac_f32_e32 v165, v167, v165
	v_div_scale_f32 v167, vcc, 1.0, v182, 1.0
	v_mul_f32_e32 v186, v167, v165
	v_fma_f32 v187, -v148, v186, v167
	v_fmac_f32_e32 v186, v187, v165
	v_fma_f32 v148, -v148, v186, v167
	v_div_fmas_f32 v148, v148, v165, v186
	v_div_fixup_f32 v182, v148, v182, 1.0
	v_pk_mul_f32 v[182:183], v[184:185], v[182:183]
	s_nop 0
	v_cvt_pk_bf16_f32 v179, v182, v183
	global_store_dwordx4 v[172:173], v[176:179], off
	s_nop 1
	v_mov_b32_e32 v148, v240
	s_waitcnt vmcnt(0)
; DI unsigned pk(float lo, float hi) { f32x2 v = {lo, hi}; bf2_t b = __builtin_convertvector(v, bf2_t); return __builtin_bit_cast(unsigned, b); }
; DI float sigmoidf_(float x) { return 1.0f / (1.0f + __expf(-x)); }
; DI void gemm_epilogue(const GemmDesc& g, f32x4 (&acc)[2][2][4][2], int brow, int bcol, int wr, int wc, int fr, int fq) {
;     ...
;     for (int ai = 0; ai < 2; ++ai)
; #pragma unroll
;       for (int m = 0; m < 4; ++m) {
;         const int row = rowb + ai * HALF + m * 16;
;         const float ru = gld<float>(g.rowscale + row);
;         const f32x4 a0 = acc[ai][0][m][0] * ru + ba0, a1 = acc[ai][0][m][1] * ru + ba1, t0 = acc[ai][1][m][0] * ru + bg0, t1 = acc[ai][1][m][1] * ru + bg1;
;         float o[8];
; #pragma unroll
;         for (int j = 0; j < 4; ++j) { o[j] = a0[j] * sigmoidf_(t0[j]); o[4 + j] = a1[j] * sigmoidf_(t1[j]); }
;         u32x4 w; w.x = pk(o[0], o[1]); w.y = pk(o[2], o[3]); w.z = pk(o[4], o[5]); w.w = pk(o[6], o[7]);
;         gst<u32x4>(g.o0 + (size_t)row * 1024 + ca, w);
	v_fma_f32 v165, v28, v148, v140
	v_mul_f32_e32 v165, 0xbfb8aa3b, v165
	v_exp_f32_e32 v172, v165
	v_fma_f32 v165, v24, v148, v132
	v_mul_f32_e32 v165, 0xbfb8aa3b, v165
	v_exp_f32_e32 v174, v165
	v_fma_f32 v165, v29, v148, v141
	v_mul_f32_e32 v165, 0xbfb8aa3b, v165
	v_exp_f32_e32 v173, v165
	v_pk_fma_f32 v[176:177], v[92:93], v[148:149], v[136:137] op_sel_hi:[1,0,1]
	v_pk_add_f32 v[172:173], v[172:173], 1.0 op_sel_hi:[1,0]
	s_nop 0
	v_div_scale_f32 v165, s[26:27], v173, v173, 1.0
	v_rcp_f32_e32 v167, v165
	s_nop 0
	v_fma_f32 v175, -v165, v167, 1.0
	v_fmac_f32_e32 v167, v175, v167
	v_div_scale_f32 v175, vcc, 1.0, v173, 1.0
	v_mul_f32_e32 v178, v175, v167
	v_fma_f32 v179, -v165, v178, v175
	v_fmac_f32_e32 v178, v179, v167
	v_fma_f32 v165, -v165, v178, v175
	v_div_fmas_f32 v165, v165, v167, v178
	v_div_fixup_f32 v173, v165, v173, 1.0
	v_div_scale_f32 v165, s[26:27], v172, v172, 1.0
	v_rcp_f32_e32 v167, v165
	s_nop 0
	v_fma_f32 v175, -v165, v167, 1.0
	v_fmac_f32_e32 v167, v175, v167
	v_div_scale_f32 v175, vcc, 1.0, v172, 1.0
	v_mul_f32_e32 v178, v175, v167
	v_fma_f32 v179, -v165, v178, v175
	v_fmac_f32_e32 v178, v179, v167
	v_fma_f32 v165, -v165, v178, v175
	v_div_fmas_f32 v165, v165, v167, v178
	v_div_fixup_f32 v172, v165, v172, 1.0
	v_fma_f32 v165, v25, v148, v133
	v_mul_f32_e32 v165, 0xbfb8aa3b, v165
	v_exp_f32_e32 v175, v165
	v_pk_mul_f32 v[172:173], v[176:177], v[172:173]
	v_pk_fma_f32 v[176:177], v[88:89], v[148:149], v[128:129] op_sel_hi:[1,0,1]
	v_cvt_pk_bf16_f32 v172, v172, v173
	v_pk_add_f32 v[174:175], v[174:175], 1.0 op_sel_hi:[1,0]
	s_nop 0
	v_div_scale_f32 v165, s[26:27], v175, v175, 1.0
	v_rcp_f32_e32 v167, v165
	s_nop 0
	v_fma_f32 v178, -v165, v167, 1.0
	v_fmac_f32_e32 v167, v178, v167
	v_div_scale_f32 v178, vcc, 1.0, v175, 1.0
	v_mul_f32_e32 v179, v178, v167
	v_fma_f32 v180, -v165, v179, v178
	v_fmac_f32_e32 v179, v180, v167
	v_fma_f32 v165, -v165, v179, v178
	v_div_fmas_f32 v165, v165, v167, v179
	v_div_fixup_f32 v175, v165, v175, 1.0
	v_div_scale_f32 v165, s[26:27], v174, v174, 1.0
	v_rcp_f32_e32 v167, v165
	s_nop 0
	v_fma_f32 v178, -v165, v167, 1.0
	v_fmac_f32_e32 v167, v178, v167
	v_div_scale_f32 v178, vcc, 1.0, v174, 1.0
	v_mul_f32_e32 v179, v178, v167
	v_fma_f32 v180, -v165, v179, v178
	v_fmac_f32_e32 v179, v180, v167
	v_fma_f32 v165, -v165, v179, v178
	v_div_fmas_f32 v165, v165, v167, v179
	v_div_fixup_f32 v174, v165, v174, 1.0
	v_fma_f32 v165, v30, v148, v142
	v_mul_f32_e32 v165, 0xbfb8aa3b, v165
	v_pk_mul_f32 v[174:175], v[176:177], v[174:175]
	v_exp_f32_e32 v176, v165
	v_fma_f32 v165, v26, v148, v134
	v_mul_f32_e32 v165, 0xbfb8aa3b, v165
	v_exp_f32_e32 v178, v165
	v_fma_f32 v165, v31, v148, v143
	v_mul_f32_e32 v165, 0xbfb8aa3b, v165
	v_exp_f32_e32 v177, v165
	v_pk_fma_f32 v[180:181], v[94:95], v[148:149], v[138:139] op_sel_hi:[1,0,1]
	v_cvt_pk_bf16_f32 v174, v174, v175
	v_pk_add_f32 v[176:177], v[176:177], 1.0 op_sel_hi:[1,0]
	s_nop 0
	v_div_scale_f32 v165, s[26:27], v177, v177, 1.0
	v_rcp_f32_e32 v167, v165
	s_nop 0
	v_fma_f32 v179, -v165, v167, 1.0
	v_fmac_f32_e32 v167, v179, v167
	v_div_scale_f32 v179, vcc, 1.0, v177, 1.0
	v_mul_f32_e32 v182, v179, v167
	v_fma_f32 v183, -v165, v182, v179
	v_fmac_f32_e32 v182, v183, v167
	v_fma_f32 v165, -v165, v182, v179
	v_div_fmas_f32 v165, v165, v167, v182
	v_div_fixup_f32 v177, v165, v177, 1.0
	v_div_scale_f32 v165, s[26:27], v176, v176, 1.0
	v_rcp_f32_e32 v167, v165
	s_nop 0
	v_fma_f32 v179, -v165, v167, 1.0
	v_fmac_f32_e32 v167, v179, v167
	v_div_scale_f32 v179, vcc, 1.0, v176, 1.0
	v_mul_f32_e32 v182, v179, v167
	v_fma_f32 v183, -v165, v182, v179
	v_fmac_f32_e32 v182, v183, v167
	v_fma_f32 v165, -v165, v182, v179
	v_div_fmas_f32 v165, v165, v167, v182
	v_div_fixup_f32 v176, v165, v176, 1.0
	v_fma_f32 v165, v27, v148, v135
	v_mul_f32_e32 v165, 0xbfb8aa3b, v165
	v_exp_f32_e32 v179, v165
	v_pk_mul_f32 v[176:177], v[180:181], v[176:177]
	v_pk_fma_f32 v[180:181], v[90:91], v[148:149], v[130:131] op_sel_hi:[1,0,1]
	v_cvt_pk_bf16_f32 v173, v176, v177
	v_pk_add_f32 v[178:179], v[178:179], 1.0 op_sel_hi:[1,0]
	s_nop 0
	v_div_scale_f32 v148, s[26:27], v179, v179, 1.0
	v_rcp_f32_e32 v165, v148
	s_nop 0
	v_fma_f32 v167, -v148, v165, 1.0
	v_fmac_f32_e32 v165, v167, v165
	v_div_scale_f32 v167, vcc, 1.0, v179, 1.0
	v_mul_f32_e32 v182, v167, v165
	v_fma_f32 v183, -v148, v182, v167
	v_fmac_f32_e32 v182, v183, v165
	v_fma_f32 v148, -v148, v182, v167
	v_div_fmas_f32 v148, v148, v165, v182
	v_div_fixup_f32 v179, v148, v179, 1.0
	v_div_scale_f32 v148, s[26:27], v178, v178, 1.0
	v_rcp_f32_e32 v165, v148
	s_mov_b32 s26, 0x40000
	v_fma_f32 v167, -v148, v165, 1.0
	v_fmac_f32_e32 v165, v167, v165
	v_div_scale_f32 v167, vcc, 1.0, v178, 1.0
	v_mul_f32_e32 v182, v167, v165
	v_fma_f32 v183, -v148, v182, v167
	v_fmac_f32_e32 v182, v183, v165
	v_fma_f32 v148, -v148, v182, v167
	v_div_fmas_f32 v148, v148, v165, v182
	v_div_fixup_f32 v178, v148, v178, 1.0
	v_pk_mul_f32 v[178:179], v[180:181], v[178:179]
	v_add_co_u32_e32 v176, vcc, s26, v170
	v_cvt_pk_bf16_f32 v175, v178, v179
	s_nop 0
	v_addc_co_u32_e32 v177, vcc, 0, v171, vcc
	global_store_dwordx4 v[176:177], v[172:175], off
	s_nop 1
	v_mov_b32_e32 v148, v241
	s_waitcnt vmcnt(0)
; DI unsigned pk(float lo, float hi) { f32x2 v = {lo, hi}; bf2_t b = __builtin_convertvector(v, bf2_t); return __builtin_bit_cast(unsigned, b); }
; DI float sigmoidf_(float x) { return 1.0f / (1.0f + __expf(-x)); }
; DI void gemm_epilogue(const GemmDesc& g, f32x4 (&acc)[2][2][4][2], int brow, int bcol, int wr, int wc, int fr, int fq) {
;     ...
;     for (int ai = 0; ai < 2; ++ai)
; #pragma unroll
;       for (int m = 0; m < 4; ++m) {
;         const int row = rowb + ai * HALF + m * 16;
;         const float ru = gld<float>(g.rowscale + row);
;         const f32x4 a0 = acc[ai][0][m][0] * ru + ba0, a1 = acc[ai][0][m][1] * ru + ba1, t0 = acc[ai][1][m][0] * ru + bg0, t1 = acc[ai][1][m][1] * ru + bg1;
;         float o[8];
; #pragma unroll
;         for (int j = 0; j < 4; ++j) { o[j] = a0[j] * sigmoidf_(t0[j]); o[4 + j] = a1[j] * sigmoidf_(t1[j]); }
;         u32x4 w; w.x = pk(o[0], o[1]); w.y = pk(o[2], o[3]); w.z = pk(o[4], o[5]); w.w = pk(o[6], o[7]);
;         gst<u32x4>(g.o0 + (size_t)row * 1024 + ca, w);
	v_fma_f32 v165, v20, v148, v140
	v_mul_f32_e32 v165, 0xbfb8aa3b, v165
	v_exp_f32_e32 v172, v165
	v_fma_f32 v165, v16, v148, v132
	v_mul_f32_e32 v165, 0xbfb8aa3b, v165
	v_exp_f32_e32 v174, v165
	v_fma_f32 v165, v21, v148, v141
	v_mul_f32_e32 v165, 0xbfb8aa3b, v165
	v_exp_f32_e32 v173, v165
	v_pk_fma_f32 v[176:177], v[84:85], v[148:149], v[136:137] op_sel_hi:[1,0,1]
	v_pk_add_f32 v[172:173], v[172:173], 1.0 op_sel_hi:[1,0]
	s_nop 0
	v_div_scale_f32 v165, s[26:27], v173, v173, 1.0
	v_rcp_f32_e32 v167, v165
	s_nop 0
	v_fma_f32 v175, -v165, v167, 1.0
	v_fmac_f32_e32 v167, v175, v167
	v_div_scale_f32 v175, vcc, 1.0, v173, 1.0
	v_mul_f32_e32 v178, v175, v167
	v_fma_f32 v179, -v165, v178, v175
	v_fmac_f32_e32 v178, v179, v167
	v_fma_f32 v165, -v165, v178, v175
	v_div_fmas_f32 v165, v165, v167, v178
	v_div_fixup_f32 v173, v165, v173, 1.0
	v_div_scale_f32 v165, s[26:27], v172, v172, 1.0
	v_rcp_f32_e32 v167, v165
	s_nop 0
	v_fma_f32 v175, -v165, v167, 1.0
	v_fmac_f32_e32 v167, v175, v167
	v_div_scale_f32 v175, vcc, 1.0, v172, 1.0
	v_mul_f32_e32 v178, v175, v167
	v_fma_f32 v179, -v165, v178, v175
	v_fmac_f32_e32 v178, v179, v167
	v_fma_f32 v165, -v165, v178, v175
	v_div_fmas_f32 v165, v165, v167, v178
	v_div_fixup_f32 v172, v165, v172, 1.0
	v_fma_f32 v165, v17, v148, v133
	v_mul_f32_e32 v165, 0xbfb8aa3b, v165
	v_exp_f32_e32 v175, v165
	v_pk_mul_f32 v[172:173], v[176:177], v[172:173]
	v_pk_fma_f32 v[176:177], v[80:81], v[148:149], v[128:129] op_sel_hi:[1,0,1]
	v_cvt_pk_bf16_f32 v172, v172, v173
	v_pk_add_f32 v[174:175], v[174:175], 1.0 op_sel_hi:[1,0]
	s_nop 0
	v_div_scale_f32 v165, s[26:27], v175, v175, 1.0
	v_rcp_f32_e32 v167, v165
	s_nop 0
	v_fma_f32 v178, -v165, v167, 1.0
	v_fmac_f32_e32 v167, v178, v167
	v_div_scale_f32 v178, vcc, 1.0, v175, 1.0
	v_mul_f32_e32 v179, v178, v167
	v_fma_f32 v180, -v165, v179, v178
	v_fmac_f32_e32 v179, v180, v167
	v_fma_f32 v165, -v165, v179, v178
	v_div_fmas_f32 v165, v165, v167, v179
	v_div_fixup_f32 v175, v165, v175, 1.0
	v_div_scale_f32 v165, s[26:27], v174, v174, 1.0
	v_rcp_f32_e32 v167, v165
	s_nop 0
	v_fma_f32 v178, -v165, v167, 1.0
	v_fmac_f32_e32 v167, v178, v167
	v_div_scale_f32 v178, vcc, 1.0, v174, 1.0
	v_mul_f32_e32 v179, v178, v167
	v_fma_f32 v180, -v165, v179, v178
	v_fmac_f32_e32 v179, v180, v167
	v_fma_f32 v165, -v165, v179, v178
	v_div_fmas_f32 v165, v165, v167, v179
	v_div_fixup_f32 v174, v165, v174, 1.0
	v_fma_f32 v165, v22, v148, v142
	v_mul_f32_e32 v165, 0xbfb8aa3b, v165
	v_pk_mul_f32 v[174:175], v[176:177], v[174:175]
	v_exp_f32_e32 v176, v165
	v_fma_f32 v165, v18, v148, v134
	v_mul_f32_e32 v165, 0xbfb8aa3b, v165
	v_exp_f32_e32 v178, v165
	v_fma_f32 v165, v23, v148, v143
	v_mul_f32_e32 v165, 0xbfb8aa3b, v165
	v_exp_f32_e32 v177, v165
	v_pk_fma_f32 v[180:181], v[86:87], v[148:149], v[138:139] op_sel_hi:[1,0,1]
	v_cvt_pk_bf16_f32 v174, v174, v175
	v_pk_add_f32 v[176:177], v[176:177], 1.0 op_sel_hi:[1,0]
	s_nop 0
	v_div_scale_f32 v165, s[26:27], v177, v177, 1.0
	v_rcp_f32_e32 v167, v165
	s_nop 0
	v_fma_f32 v179, -v165, v167, 1.0
	v_fmac_f32_e32 v167, v179, v167
	v_div_scale_f32 v179, vcc, 1.0, v177, 1.0
	v_mul_f32_e32 v182, v179, v167
	v_fma_f32 v183, -v165, v182, v179
	v_fmac_f32_e32 v182, v183, v167
	v_fma_f32 v165, -v165, v182, v179
	v_div_fmas_f32 v165, v165, v167, v182
	v_div_fixup_f32 v177, v165, v177, 1.0
	v_div_scale_f32 v165, s[26:27], v176, v176, 1.0
	v_rcp_f32_e32 v167, v165
	s_nop 0
	v_fma_f32 v179, -v165, v167, 1.0
	v_fmac_f32_e32 v167, v179, v167
	v_div_scale_f32 v179, vcc, 1.0, v176, 1.0
	v_mul_f32_e32 v182, v179, v167
	v_fma_f32 v183, -v165, v182, v179
	v_fmac_f32_e32 v182, v183, v167
	v_fma_f32 v165, -v165, v182, v179
	v_div_fmas_f32 v165, v165, v167, v182
	v_div_fixup_f32 v176, v165, v176, 1.0
	v_fma_f32 v165, v19, v148, v135
	v_mul_f32_e32 v165, 0xbfb8aa3b, v165
	v_exp_f32_e32 v179, v165
	v_pk_mul_f32 v[176:177], v[180:181], v[176:177]
	v_pk_fma_f32 v[180:181], v[82:83], v[148:149], v[130:131] op_sel_hi:[1,0,1]
	v_cvt_pk_bf16_f32 v173, v176, v177
	v_pk_add_f32 v[178:179], v[178:179], 1.0 op_sel_hi:[1,0]
	s_nop 0
	v_div_scale_f32 v148, s[26:27], v179, v179, 1.0
	v_rcp_f32_e32 v165, v148
	s_nop 0
	v_fma_f32 v167, -v148, v165, 1.0
	v_fmac_f32_e32 v165, v167, v165
	v_div_scale_f32 v167, vcc, 1.0, v179, 1.0
	v_mul_f32_e32 v182, v167, v165
	v_fma_f32 v183, -v148, v182, v167
	v_fmac_f32_e32 v182, v183, v165
	v_fma_f32 v148, -v148, v182, v167
	v_div_fmas_f32 v148, v148, v165, v182
	v_div_fixup_f32 v179, v148, v179, 1.0
	v_div_scale_f32 v148, s[26:27], v178, v178, 1.0
	v_rcp_f32_e32 v165, v148
	s_mov_b32 s26, 0x48000
	v_fma_f32 v167, -v148, v165, 1.0
	v_fmac_f32_e32 v165, v167, v165
	v_div_scale_f32 v167, vcc, 1.0, v178, 1.0
	v_mul_f32_e32 v182, v167, v165
	v_fma_f32 v183, -v148, v182, v167
	v_fmac_f32_e32 v182, v183, v165
	v_fma_f32 v148, -v148, v182, v167
	v_div_fmas_f32 v148, v148, v165, v182
	v_div_fixup_f32 v178, v148, v178, 1.0
	v_pk_mul_f32 v[178:179], v[180:181], v[178:179]
	v_add_co_u32_e32 v176, vcc, s26, v170
	v_cvt_pk_bf16_f32 v175, v178, v179
	s_nop 0
	v_addc_co_u32_e32 v177, vcc, 0, v171, vcc
	global_store_dwordx4 v[176:177], v[172:175], off
	s_nop 1
	v_mov_b32_e32 v148, v242
	s_waitcnt vmcnt(0)
; DI unsigned pk(float lo, float hi) { f32x2 v = {lo, hi}; bf2_t b = __builtin_convertvector(v, bf2_t); return __builtin_bit_cast(unsigned, b); }
; DI float sigmoidf_(float x) { return 1.0f / (1.0f + __expf(-x)); }
; DI void gemm_epilogue(const GemmDesc& g, f32x4 (&acc)[2][2][4][2], int brow, int bcol, int wr, int wc, int fr, int fq) {
;     ...
;     for (int ai = 0; ai < 2; ++ai)
; #pragma unroll
;       for (int m = 0; m < 4; ++m) {
;         const int row = rowb + ai * HALF + m * 16;
;         const float ru = gld<float>(g.rowscale + row);
;         const f32x4 a0 = acc[ai][0][m][0] * ru + ba0, a1 = acc[ai][0][m][1] * ru + ba1, t0 = acc[ai][1][m][0] * ru + bg0, t1 = acc[ai][1][m][1] * ru + bg1;
;         float o[8];
; #pragma unroll
;         for (int j = 0; j < 4; ++j) { o[j] = a0[j] * sigmoidf_(t0[j]); o[4 + j] = a1[j] * sigmoidf_(t1[j]); }
;         u32x4 w; w.x = pk(o[0], o[1]); w.y = pk(o[2], o[3]); w.z = pk(o[4], o[5]); w.w = pk(o[6], o[7]);
;         gst<u32x4>(g.o0 + (size_t)row * 1024 + ca, w);
	v_fma_f32 v165, v12, v148, v140
	v_mul_f32_e32 v165, 0xbfb8aa3b, v165
	v_exp_f32_e32 v172, v165
	v_fma_f32 v165, v8, v148, v132
	v_mul_f32_e32 v165, 0xbfb8aa3b, v165
	v_exp_f32_e32 v174, v165
	v_fma_f32 v165, v13, v148, v141
	v_mul_f32_e32 v165, 0xbfb8aa3b, v165
	v_exp_f32_e32 v173, v165
	v_pk_fma_f32 v[176:177], v[76:77], v[148:149], v[136:137] op_sel_hi:[1,0,1]
	v_pk_add_f32 v[172:173], v[172:173], 1.0 op_sel_hi:[1,0]
	s_nop 0
	v_div_scale_f32 v165, s[26:27], v173, v173, 1.0
	v_rcp_f32_e32 v167, v165
	s_nop 0
	v_fma_f32 v175, -v165, v167, 1.0
	v_fmac_f32_e32 v167, v175, v167
	v_div_scale_f32 v175, vcc, 1.0, v173, 1.0
	v_mul_f32_e32 v178, v175, v167
	v_fma_f32 v179, -v165, v178, v175
	v_fmac_f32_e32 v178, v179, v167
	v_fma_f32 v165, -v165, v178, v175
	v_div_fmas_f32 v165, v165, v167, v178
	v_div_fixup_f32 v173, v165, v173, 1.0
	v_div_scale_f32 v165, s[26:27], v172, v172, 1.0
	v_rcp_f32_e32 v167, v165
	s_nop 0
	v_fma_f32 v175, -v165, v167, 1.0
	v_fmac_f32_e32 v167, v175, v167
	v_div_scale_f32 v175, vcc, 1.0, v172, 1.0
	v_mul_f32_e32 v178, v175, v167
	v_fma_f32 v179, -v165, v178, v175
	v_fmac_f32_e32 v178, v179, v167
	v_fma_f32 v165, -v165, v178, v175
	v_div_fmas_f32 v165, v165, v167, v178
	v_div_fixup_f32 v172, v165, v172, 1.0
	v_fma_f32 v165, v9, v148, v133
	v_mul_f32_e32 v165, 0xbfb8aa3b, v165
	v_exp_f32_e32 v175, v165
	v_pk_mul_f32 v[172:173], v[176:177], v[172:173]
	v_pk_fma_f32 v[176:177], v[72:73], v[148:149], v[128:129] op_sel_hi:[1,0,1]
	v_cvt_pk_bf16_f32 v172, v172, v173
	v_pk_add_f32 v[174:175], v[174:175], 1.0 op_sel_hi:[1,0]
	s_nop 0
	v_div_scale_f32 v165, s[26:27], v175, v175, 1.0
	v_rcp_f32_e32 v167, v165
	s_nop 0
	v_fma_f32 v178, -v165, v167, 1.0
	v_fmac_f32_e32 v167, v178, v167
	v_div_scale_f32 v178, vcc, 1.0, v175, 1.0
	v_mul_f32_e32 v179, v178, v167
	v_fma_f32 v180, -v165, v179, v178
	v_fmac_f32_e32 v179, v180, v167
	v_fma_f32 v165, -v165, v179, v178
	v_div_fmas_f32 v165, v165, v167, v179
	v_div_fixup_f32 v175, v165, v175, 1.0
	v_div_scale_f32 v165, s[26:27], v174, v174, 1.0
	v_rcp_f32_e32 v167, v165
	s_nop 0
	v_fma_f32 v178, -v165, v167, 1.0
	v_fmac_f32_e32 v167, v178, v167
	v_div_scale_f32 v178, vcc, 1.0, v174, 1.0
	v_mul_f32_e32 v179, v178, v167
	v_fma_f32 v180, -v165, v179, v178
	v_fmac_f32_e32 v179, v180, v167
	v_fma_f32 v165, -v165, v179, v178
	v_div_fmas_f32 v165, v165, v167, v179
	v_div_fixup_f32 v174, v165, v174, 1.0
	v_fma_f32 v165, v14, v148, v142
	v_mul_f32_e32 v165, 0xbfb8aa3b, v165
	v_pk_mul_f32 v[174:175], v[176:177], v[174:175]
	v_exp_f32_e32 v176, v165
	v_fma_f32 v165, v10, v148, v134
	v_mul_f32_e32 v165, 0xbfb8aa3b, v165
	v_exp_f32_e32 v178, v165
	v_fma_f32 v165, v15, v148, v143
	v_mul_f32_e32 v165, 0xbfb8aa3b, v165
	v_exp_f32_e32 v177, v165
	v_pk_fma_f32 v[180:181], v[78:79], v[148:149], v[138:139] op_sel_hi:[1,0,1]
	v_cvt_pk_bf16_f32 v174, v174, v175
	v_pk_add_f32 v[176:177], v[176:177], 1.0 op_sel_hi:[1,0]
	s_nop 0
	v_div_scale_f32 v165, s[26:27], v177, v177, 1.0
	v_rcp_f32_e32 v167, v165
	s_nop 0
	v_fma_f32 v179, -v165, v167, 1.0
	v_fmac_f32_e32 v167, v179, v167
	v_div_scale_f32 v179, vcc, 1.0, v177, 1.0
	v_mul_f32_e32 v182, v179, v167
	v_fma_f32 v183, -v165, v182, v179
	v_fmac_f32_e32 v182, v183, v167
	v_fma_f32 v165, -v165, v182, v179
	v_div_fmas_f32 v165, v165, v167, v182
	v_div_fixup_f32 v177, v165, v177, 1.0
	v_div_scale_f32 v165, s[26:27], v176, v176, 1.0
	v_rcp_f32_e32 v167, v165
	s_nop 0
	v_fma_f32 v179, -v165, v167, 1.0
	v_fmac_f32_e32 v167, v179, v167
	v_div_scale_f32 v179, vcc, 1.0, v176, 1.0
	v_mul_f32_e32 v182, v179, v167
	v_fma_f32 v183, -v165, v182, v179
	v_fmac_f32_e32 v182, v183, v167
	v_fma_f32 v165, -v165, v182, v179
	v_div_fmas_f32 v165, v165, v167, v182
	v_div_fixup_f32 v176, v165, v176, 1.0
	v_fma_f32 v165, v11, v148, v135
	v_mul_f32_e32 v165, 0xbfb8aa3b, v165
	v_exp_f32_e32 v179, v165
	v_pk_mul_f32 v[176:177], v[180:181], v[176:177]
	v_pk_fma_f32 v[180:181], v[74:75], v[148:149], v[130:131] op_sel_hi:[1,0,1]
	v_cvt_pk_bf16_f32 v173, v176, v177
	v_pk_add_f32 v[178:179], v[178:179], 1.0 op_sel_hi:[1,0]
	s_nop 0
	v_div_scale_f32 v148, s[26:27], v179, v179, 1.0
	v_rcp_f32_e32 v165, v148
	s_nop 0
	v_fma_f32 v167, -v148, v165, 1.0
	v_fmac_f32_e32 v165, v167, v165
	v_div_scale_f32 v167, vcc, 1.0, v179, 1.0
	v_mul_f32_e32 v182, v167, v165
	v_fma_f32 v183, -v148, v182, v167
	v_fmac_f32_e32 v182, v183, v165
	v_fma_f32 v148, -v148, v182, v167
	v_div_fmas_f32 v148, v148, v165, v182
	v_div_fixup_f32 v179, v148, v179, 1.0
	v_div_scale_f32 v148, s[26:27], v178, v178, 1.0
	v_rcp_f32_e32 v165, v148
	s_mov_b32 s26, 0x50000
	v_fma_f32 v167, -v148, v165, 1.0
	v_fmac_f32_e32 v165, v167, v165
	v_div_scale_f32 v167, vcc, 1.0, v178, 1.0
	v_mul_f32_e32 v182, v167, v165
	v_fma_f32 v183, -v148, v182, v167
	v_fmac_f32_e32 v182, v183, v165
	v_fma_f32 v148, -v148, v182, v167
	v_div_fmas_f32 v148, v148, v165, v182
	v_div_fixup_f32 v178, v148, v178, 1.0
	v_pk_mul_f32 v[178:179], v[180:181], v[178:179]
	v_add_co_u32_e32 v176, vcc, s26, v170
	v_cvt_pk_bf16_f32 v175, v178, v179
	s_nop 0
	v_addc_co_u32_e32 v177, vcc, 0, v171, vcc
	global_store_dwordx4 v[176:177], v[172:175], off
	s_nop 1
	v_mov_b32_e32 v148, v243
	s_waitcnt vmcnt(0)
; DI unsigned pk(float lo, float hi) { f32x2 v = {lo, hi}; bf2_t b = __builtin_convertvector(v, bf2_t); return __builtin_bit_cast(unsigned, b); }
; DI float sigmoidf_(float x) { return 1.0f / (1.0f + __expf(-x)); }
; DI void gemm_epilogue(const GemmDesc& g, f32x4 (&acc)[2][2][4][2], int brow, int bcol, int wr, int wc, int fr, int fq) {
;     ...
;     for (int ai = 0; ai < 2; ++ai)
; #pragma unroll
;       for (int m = 0; m < 4; ++m) {
;         const int row = rowb + ai * HALF + m * 16;
;         const float ru = gld<float>(g.rowscale + row);
;         const f32x4 a0 = acc[ai][0][m][0] * ru + ba0, a1 = acc[ai][0][m][1] * ru + ba1, t0 = acc[ai][1][m][0] * ru + bg0, t1 = acc[ai][1][m][1] * ru + bg1;
;         float o[8];
; #pragma unroll
;         for (int j = 0; j < 4; ++j) { o[j] = a0[j] * sigmoidf_(t0[j]); o[4 + j] = a1[j] * sigmoidf_(t1[j]); }
;         u32x4 w; w.x = pk(o[0], o[1]); w.y = pk(o[2], o[3]); w.z = pk(o[4], o[5]); w.w = pk(o[6], o[7]);
;         gst<u32x4>(g.o0 + (size_t)row * 1024 + ca, w);
	v_fma_f32 v140, v4, v148, v140
	v_fma_f32 v141, v5, v148, v141
	v_mul_f32_e32 v140, 0xbfb8aa3b, v140
	v_mul_f32_e32 v141, 0xbfb8aa3b, v141
	v_exp_f32_e32 v140, v140
	v_exp_f32_e32 v141, v141
	v_fma_f32 v132, v0, v148, v132
	v_fma_f32 v133, v1, v148, v133
	v_mul_f32_e32 v132, 0xbfb8aa3b, v132
	v_pk_add_f32 v[140:141], v[140:141], 1.0 op_sel_hi:[1,0]
	v_mul_f32_e32 v133, 0xbfb8aa3b, v133
	v_div_scale_f32 v165, s[26:27], v141, v141, 1.0
	v_rcp_f32_e32 v167, v165
	v_exp_f32_e32 v132, v132
	v_exp_f32_e32 v133, v133
	v_pk_fma_f32 v[136:137], v[68:69], v[148:149], v[136:137] op_sel_hi:[1,0,1]
	v_fma_f32 v168, -v165, v167, 1.0
	v_fmac_f32_e32 v167, v168, v167
	v_div_scale_f32 v168, vcc, 1.0, v141, 1.0
	v_mul_f32_e32 v169, v168, v167
	v_fma_f32 v172, -v165, v169, v168
	v_fmac_f32_e32 v169, v172, v167
	v_fma_f32 v165, -v165, v169, v168
	v_div_fmas_f32 v165, v165, v167, v169
	v_div_fixup_f32 v141, v165, v141, 1.0
	v_div_scale_f32 v165, s[26:27], v140, v140, 1.0
	v_rcp_f32_e32 v167, v165
	v_pk_add_f32 v[132:133], v[132:133], 1.0 op_sel_hi:[1,0]
	v_pk_fma_f32 v[128:129], v[64:65], v[148:149], v[128:129] op_sel_hi:[1,0,1]
	v_fmac_f32_e32 v143, v7, v148
	v_fma_f32 v168, -v165, v167, 1.0
	v_fmac_f32_e32 v167, v168, v167
	v_div_scale_f32 v168, vcc, 1.0, v140, 1.0
	v_mul_f32_e32 v169, v168, v167
	v_fma_f32 v172, -v165, v169, v168
	v_fmac_f32_e32 v169, v172, v167
	v_fma_f32 v165, -v165, v169, v168
	v_div_fmas_f32 v165, v165, v167, v169
	v_div_fixup_f32 v140, v165, v140, 1.0
	v_pk_mul_f32 v[136:137], v[136:137], v[140:141]
	v_div_scale_f32 v140, s[26:27], v133, v133, 1.0
	v_rcp_f32_e32 v141, v140
	v_pk_fma_f32 v[138:139], v[70:71], v[148:149], v[138:139] op_sel_hi:[1,0,1]
	v_fmac_f32_e32 v135, v3, v148
	v_fma_f32 v165, -v140, v141, 1.0
	v_fmac_f32_e32 v141, v165, v141
	v_div_scale_f32 v165, vcc, 1.0, v133, 1.0
	v_mul_f32_e32 v167, v165, v141
	v_fma_f32 v168, -v140, v167, v165
	v_fmac_f32_e32 v167, v168, v141
	v_fma_f32 v140, -v140, v167, v165
	v_div_fmas_f32 v140, v140, v141, v167
	v_div_fixup_f32 v133, v140, v133, 1.0
	v_div_scale_f32 v140, s[26:27], v132, v132, 1.0
	v_rcp_f32_e32 v141, v140
	s_nop 0
	v_fma_f32 v165, -v140, v141, 1.0
	v_fmac_f32_e32 v141, v165, v141
	v_div_scale_f32 v165, vcc, 1.0, v132, 1.0
	v_mul_f32_e32 v167, v165, v141
	v_fma_f32 v168, -v140, v167, v165
	v_fmac_f32_e32 v167, v168, v141
	v_fma_f32 v140, -v140, v167, v165
	v_div_fmas_f32 v140, v140, v141, v167
	v_div_fixup_f32 v132, v140, v132, 1.0
	v_pk_mul_f32 v[132:133], v[128:129], v[132:133]
	v_fma_f32 v129, v2, v148, v134
	v_fma_f32 v128, v6, v148, v142
	v_mul_f32_e32 v129, 0xbfb8aa3b, v129
	v_mul_f32_e32 v128, 0xbfb8aa3b, v128
	v_exp_f32_e32 v134, v129
	v_mul_f32_e32 v129, 0xbfb8aa3b, v143
	v_exp_f32_e32 v128, v128
	v_exp_f32_e32 v129, v129
	s_nop 0
	v_pk_add_f32 v[128:129], v[128:129], 1.0 op_sel_hi:[1,0]
	s_nop 0
	v_div_scale_f32 v140, s[26:27], v129, v129, 1.0
	v_rcp_f32_e32 v141, v140
	s_nop 0
	v_fma_f32 v142, -v140, v141, 1.0
	v_fmac_f32_e32 v141, v142, v141
	v_div_scale_f32 v142, vcc, 1.0, v129, 1.0
	v_mul_f32_e32 v143, v142, v141
	v_fma_f32 v165, -v140, v143, v142
	v_fmac_f32_e32 v143, v165, v141
	v_fma_f32 v140, -v140, v143, v142
	v_div_fmas_f32 v140, v140, v141, v143
	v_div_fixup_f32 v129, v140, v129, 1.0
	v_div_scale_f32 v140, s[26:27], v128, v128, 1.0
	v_rcp_f32_e32 v141, v140
	s_nop 0
	v_fma_f32 v142, -v140, v141, 1.0
	v_fmac_f32_e32 v141, v142, v141
	v_div_scale_f32 v142, vcc, 1.0, v128, 1.0
	v_mul_f32_e32 v143, v142, v141
	v_fma_f32 v165, -v140, v143, v142
	v_fmac_f32_e32 v143, v165, v141
	v_fma_f32 v140, -v140, v143, v142
	v_div_fmas_f32 v140, v140, v141, v143
	v_div_fixup_f32 v128, v140, v128, 1.0
	v_pk_mul_f32 v[138:139], v[138:139], v[128:129]
	v_mul_f32_e32 v128, 0xbfb8aa3b, v135
	v_exp_f32_e32 v135, v128
	v_pk_fma_f32 v[128:129], v[66:67], v[148:149], v[130:131] op_sel_hi:[1,0,1]
	v_pk_add_f32 v[130:131], v[134:135], 1.0 op_sel_hi:[1,0]
	s_nop 0
	v_div_scale_f32 v134, s[26:27], v131, v131, 1.0
	v_rcp_f32_e32 v135, v134
	s_nop 0
	v_fma_f32 v140, -v134, v135, 1.0
	v_fmac_f32_e32 v135, v140, v135
	v_div_scale_f32 v140, vcc, 1.0, v131, 1.0
	v_mul_f32_e32 v141, v140, v135
	v_fma_f32 v142, -v134, v141, v140
	v_fmac_f32_e32 v141, v142, v135
	v_fma_f32 v134, -v134, v141, v140
	v_div_fmas_f32 v134, v134, v135, v141
	v_div_fixup_f32 v131, v134, v131, 1.0
	v_div_scale_f32 v134, s[26:27], v130, v130, 1.0
	v_rcp_f32_e32 v135, v134
	s_nop 0
	v_fma_f32 v140, -v134, v135, 1.0
	v_fmac_f32_e32 v135, v140, v135
	v_div_scale_f32 v140, vcc, 1.0, v130, 1.0
	v_mul_f32_e32 v141, v140, v135
	v_fma_f32 v142, -v134, v141, v140
	v_fmac_f32_e32 v141, v142, v135
	v_fma_f32 v134, -v134, v141, v140
	v_div_fmas_f32 v134, v134, v135, v141
	v_div_fixup_f32 v130, v134, v130, 1.0
	v_pk_mul_f32 v[134:135], v[128:129], v[130:131]
	v_cvt_pk_bf16_f32 v130, v132, v133
	v_add_co_u32_e32 v132, vcc, 0x58000, v170
	v_cvt_pk_bf16_f32 v128, v136, v137
	v_cvt_pk_bf16_f32 v129, v138, v139
	v_cvt_pk_bf16_f32 v131, v134, v135
	v_addc_co_u32_e32 v133, vcc, 0, v171, vcc
	global_store_dwordx4 v[132:133], v[128:131], off

; DI unsigned pk(float lo, float hi) { f32x2 v = {lo, hi}; bf2_t b = __builtin_convertvector(v, bf2_t); return __builtin_bit_cast(unsigned, b); }
; DI void gemm_epilogue(const GemmDesc& g, f32x4 (&acc)[2][2][4][2], int brow, int bcol, int wr, int wc, int fr, int fq) {
;     ...
;           const int row = rowb + ai * HALF + m * 16;
;           f32x4 v0 = acc[ai][bj][m][0], v1 = acc[ai][bj][m][1];
;           if (g.rowscale) { const float ru = gld<float>(g.rowscale + row); v0 = v0 * ru; v1 = v1 * ru; }
;           v0 = v0 + b0; v1 = v1 + b1;
;           if (epi == EPI_RELU2) {
; #pragma unroll
;             for (int j = 0; j < 4; ++j) { float r0 = fmaxf(v0[j], 0.f), r1 = fmaxf(v1[j], 0.f); v0[j] = r0 * r0; v1[j] = r1 * r1; }
;           }
;           u32x4 w; w.x = pk(v0[0], v0[1]); w.y = pk(v0[2], v0[3]); w.z = pk(v1[0], v1[1]); w.w = pk(v1[2], v1[3]);
;           gst<u32x4>(g.o0 + (size_t)row * N + col, w);
.LBB0_155:
	v_cvt_pk_bf16_f32 v124, v124, v125
	v_cvt_pk_bf16_f32 v125, v126, v127
	v_cvt_pk_bf16_f32 v126, v120, v121
	v_mad_u64_u32 v[120:121], s[26:27], v166, s70, 0
	v_cvt_pk_bf16_f32 v127, v122, v123
	v_mov_b32_e32 v122, v121
	v_mad_u64_u32 v[122:123], s[26:27], v167, s70, v[122:123]
	v_mov_b32_e32 v121, v122
	v_lshl_add_u64 v[120:121], v[120:121], 1, s[64:65]
	v_lshl_add_u64 v[122:123], v[164:165], 1, v[120:121]
	s_and_b64 vcc, exec, s[44:45]
	v_lshl_add_u64 v[120:121], v[166:167], 2, s[22:23]
	global_store_dwordx4 v[122:123], v[124:127], off
	s_cbranch_vccnz .LBB0_157
	global_load_dword v236, v[120:121], off
	global_load_dword v237, v[120:121], off offset:64
	global_load_dword v238, v[120:121], off offset:128
	global_load_dword v239, v[120:121], off offset:192
	global_load_dword v240, v[120:121], off offset:512
	global_load_dword v241, v[120:121], off offset:576
	global_load_dword v242, v[120:121], off offset:640
	global_load_dword v243, v[120:121], off offset:704
	global_load_dword v124, v[120:121], off offset:64
	s_waitcnt vmcnt(0)
	v_pk_mul_f32 v[118:119], v[118:119], v[124:125] op_sel_hi:[1,0]
	v_pk_mul_f32 v[116:117], v[116:117], v[124:125] op_sel_hi:[1,0]
	v_pk_mul_f32 v[114:115], v[114:115], v[124:125] op_sel_hi:[1,0]
	v_pk_mul_f32 v[112:113], v[112:113], v[124:125] op_sel_hi:[1,0]

; DI unsigned pk(float lo, float hi) { f32x2 v = {lo, hi}; bf2_t b = __builtin_convertvector(v, bf2_t); return __builtin_bit_cast(unsigned, b); }
; DI void gemm_epilogue(const GemmDesc& g, f32x4 (&acc)[2][2][4][2], int brow, int bcol, int wr, int wc, int fr, int fq) {
;     ...
;           const int row = rowb + ai * HALF + m * 16;
;           f32x4 v0 = acc[ai][bj][m][0], v1 = acc[ai][bj][m][1];
;           if (g.rowscale) { const float ru = gld<float>(g.rowscale + row); v0 = v0 * ru; v1 = v1 * ru; }
;           v0 = v0 + b0; v1 = v1 + b1;
;           if (epi == EPI_RELU2) {
; #pragma unroll
;             for (int j = 0; j < 4; ++j) { float r0 = fmaxf(v0[j], 0.f), r1 = fmaxf(v1[j], 0.f); v0[j] = r0 * r0; v1[j] = r1 * r1; }
;           }
;           u32x4 w; w.x = pk(v0[0], v0[1]); w.y = pk(v0[2], v0[3]); w.z = pk(v1[0], v1[1]); w.w = pk(v1[2], v1[3]);
;           gst<u32x4>(g.o0 + (size_t)row * N + col, w);
.LBB0_159:
	v_or_b32_e32 v124, 16, v166
	v_cvt_pk_bf16_f32 v116, v116, v117
	v_cvt_pk_bf16_f32 v117, v118, v119
	v_cvt_pk_bf16_f32 v118, v112, v113
	v_mad_u64_u32 v[112:113], s[26:27], v124, s70, 0
	v_cvt_pk_bf16_f32 v119, v114, v115
	v_mov_b32_e32 v114, v113
	v_mad_u64_u32 v[114:115], s[26:27], v167, s70, v[114:115]
	v_mov_b32_e32 v113, v114
	v_lshl_add_u64 v[112:113], v[112:113], 1, s[64:65]
	v_lshl_add_u64 v[112:113], v[164:165], 1, v[112:113]
	s_and_b64 vcc, exec, s[44:45]
	global_store_dwordx4 v[112:113], v[116:119], off
	s_cbranch_vccnz .LBB0_161
	s_nop 1
	v_mov_b32_e32 v114, v238
	s_waitcnt vmcnt(0)
	v_pk_mul_f32 v[110:111], v[110:111], v[114:115] op_sel_hi:[1,0]
	v_pk_mul_f32 v[108:109], v[108:109], v[114:115] op_sel_hi:[1,0]
	v_pk_mul_f32 v[106:107], v[106:107], v[114:115] op_sel_hi:[1,0]
	v_pk_mul_f32 v[104:105], v[104:105], v[114:115] op_sel_hi:[1,0]

; DI unsigned pk(float lo, float hi) { f32x2 v = {lo, hi}; bf2_t b = __builtin_convertvector(v, bf2_t); return __builtin_bit_cast(unsigned, b); }
; DI void gemm_epilogue(const GemmDesc& g, f32x4 (&acc)[2][2][4][2], int brow, int bcol, int wr, int wc, int fr, int fq) {
;     ...
;           const int row = rowb + ai * HALF + m * 16;
;           f32x4 v0 = acc[ai][bj][m][0], v1 = acc[ai][bj][m][1];
;           if (g.rowscale) { const float ru = gld<float>(g.rowscale + row); v0 = v0 * ru; v1 = v1 * ru; }
;           v0 = v0 + b0; v1 = v1 + b1;
;           if (epi == EPI_RELU2) {
; #pragma unroll
;             for (int j = 0; j < 4; ++j) { float r0 = fmaxf(v0[j], 0.f), r1 = fmaxf(v1[j], 0.f); v0[j] = r0 * r0; v1[j] = r1 * r1; }
;           }
;           u32x4 w; w.x = pk(v0[0], v0[1]); w.y = pk(v0[2], v0[3]); w.z = pk(v1[0], v1[1]); w.w = pk(v1[2], v1[3]);
;           gst<u32x4>(g.o0 + (size_t)row * N + col, w);
.LBB0_163:
	v_or_b32_e32 v114, 32, v166
	v_cvt_pk_bf16_f32 v108, v108, v109
	v_cvt_pk_bf16_f32 v109, v110, v111
	v_cvt_pk_bf16_f32 v110, v104, v105
	v_mad_u64_u32 v[104:105], s[26:27], v114, s70, 0
	v_cvt_pk_bf16_f32 v111, v106, v107
	v_mov_b32_e32 v106, v105
	v_mad_u64_u32 v[106:107], s[26:27], v167, s70, v[106:107]
	v_mov_b32_e32 v105, v106
	v_lshl_add_u64 v[104:105], v[104:105], 1, s[64:65]
	v_lshl_add_u64 v[104:105], v[164:165], 1, v[104:105]
	s_and_b64 vcc, exec, s[44:45]
	global_store_dwordx4 v[104:105], v[108:111], off
	s_cbranch_vccnz .LBB0_165
	s_nop 1
	v_mov_b32_e32 v106, v239
	s_waitcnt vmcnt(0)
	v_pk_mul_f32 v[102:103], v[102:103], v[106:107] op_sel_hi:[1,0]
	v_pk_mul_f32 v[100:101], v[100:101], v[106:107] op_sel_hi:[1,0]
	v_pk_mul_f32 v[98:99], v[98:99], v[106:107] op_sel_hi:[1,0]
	v_pk_mul_f32 v[96:97], v[96:97], v[106:107] op_sel_hi:[1,0]

; DI unsigned pk(float lo, float hi) { f32x2 v = {lo, hi}; bf2_t b = __builtin_convertvector(v, bf2_t); return __builtin_bit_cast(unsigned, b); }
; DI void gemm_epilogue(const GemmDesc& g, f32x4 (&acc)[2][2][4][2], int brow, int bcol, int wr, int wc, int fr, int fq) {
;     ...
;           const int row = rowb + ai * HALF + m * 16;
;           f32x4 v0 = acc[ai][bj][m][0], v1 = acc[ai][bj][m][1];
;           if (g.rowscale) { const float ru = gld<float>(g.rowscale + row); v0 = v0 * ru; v1 = v1 * ru; }
;           v0 = v0 + b0; v1 = v1 + b1;
;           if (epi == EPI_RELU2) {
; #pragma unroll
;             for (int j = 0; j < 4; ++j) { float r0 = fmaxf(v0[j], 0.f), r1 = fmaxf(v1[j], 0.f); v0[j] = r0 * r0; v1[j] = r1 * r1; }
;           }
;           u32x4 w; w.x = pk(v0[0], v0[1]); w.y = pk(v0[2], v0[3]); w.z = pk(v1[0], v1[1]); w.w = pk(v1[2], v1[3]);
;           gst<u32x4>(g.o0 + (size_t)row * N + col, w);
.LBB0_167:
	v_or_b32_e32 v106, 48, v166
	v_cvt_pk_bf16_f32 v100, v100, v101
	v_cvt_pk_bf16_f32 v101, v102, v103
	v_cvt_pk_bf16_f32 v102, v96, v97
	v_mad_u64_u32 v[96:97], s[26:27], v106, s70, 0
	v_cvt_pk_bf16_f32 v103, v98, v99
	v_mov_b32_e32 v98, v97
	v_mad_u64_u32 v[98:99], s[26:27], v167, s70, v[98:99]
	v_mov_b32_e32 v97, v98
	v_lshl_add_u64 v[96:97], v[96:97], 1, s[64:65]
	v_lshl_add_u64 v[96:97], v[164:165], 1, v[96:97]
	s_and_b64 vcc, exec, s[44:45]
	global_store_dwordx4 v[96:97], v[100:103], off
	s_cbranch_vccnz .LBB0_169
	s_nop 1
	v_mov_b32_e32 v98, v240
	s_waitcnt vmcnt(0)
	v_pk_mul_f32 v[94:95], v[94:95], v[98:99] op_sel_hi:[1,0]
	v_pk_mul_f32 v[92:93], v[92:93], v[98:99] op_sel_hi:[1,0]
	v_pk_mul_f32 v[90:91], v[90:91], v[98:99] op_sel_hi:[1,0]
	v_pk_mul_f32 v[88:89], v[88:89], v[98:99] op_sel_hi:[1,0]

; DI unsigned pk(float lo, float hi) { f32x2 v = {lo, hi}; bf2_t b = __builtin_convertvector(v, bf2_t); return __builtin_bit_cast(unsigned, b); }
; DI void gemm_epilogue(const GemmDesc& g, f32x4 (&acc)[2][2][4][2], int brow, int bcol, int wr, int wc, int fr, int fq) {
;     ...
;           const int row = rowb + ai * HALF + m * 16;
;           f32x4 v0 = acc[ai][bj][m][0], v1 = acc[ai][bj][m][1];
;           if (g.rowscale) { const float ru = gld<float>(g.rowscale + row); v0 = v0 * ru; v1 = v1 * ru; }
;           v0 = v0 + b0; v1 = v1 + b1;
;           if (epi == EPI_RELU2) {
; #pragma unroll
;             for (int j = 0; j < 4; ++j) { float r0 = fmaxf(v0[j], 0.f), r1 = fmaxf(v1[j], 0.f); v0[j] = r0 * r0; v1[j] = r1 * r1; }
;           }
;           u32x4 w; w.x = pk(v0[0], v0[1]); w.y = pk(v0[2], v0[3]); w.z = pk(v1[0], v1[1]); w.w = pk(v1[2], v1[3]);
;           gst<u32x4>(g.o0 + (size_t)row * N + col, w);
.LBB0_171:
	v_add_u32_e32 v98, 0x80, v166
	v_cvt_pk_bf16_f32 v92, v92, v93
	v_cvt_pk_bf16_f32 v93, v94, v95
	v_cvt_pk_bf16_f32 v94, v88, v89
	v_mad_u64_u32 v[88:89], s[26:27], v98, s70, 0
	v_cvt_pk_bf16_f32 v95, v90, v91
	v_ashrrev_i32_e32 v91, 31, v98
	v_mov_b32_e32 v90, v89
	v_mad_u64_u32 v[90:91], s[26:27], v91, s70, v[90:91]
	v_mov_b32_e32 v89, v90
	v_lshl_add_u64 v[88:89], v[88:89], 1, s[64:65]
	v_lshl_add_u64 v[88:89], v[164:165], 1, v[88:89]
	s_and_b64 vcc, exec, s[44:45]
	global_store_dwordx4 v[88:89], v[92:95], off
	s_cbranch_vccnz .LBB0_173
	s_nop 1
	v_mov_b32_e32 v90, v241
	s_waitcnt vmcnt(0)
	v_pk_mul_f32 v[86:87], v[86:87], v[90:91] op_sel_hi:[1,0]
	v_pk_mul_f32 v[84:85], v[84:85], v[90:91] op_sel_hi:[1,0]
	v_pk_mul_f32 v[82:83], v[82:83], v[90:91] op_sel_hi:[1,0]
	v_pk_mul_f32 v[80:81], v[80:81], v[90:91] op_sel_hi:[1,0]

; DI unsigned pk(float lo, float hi) { f32x2 v = {lo, hi}; bf2_t b = __builtin_convertvector(v, bf2_t); return __builtin_bit_cast(unsigned, b); }
; DI void gemm_epilogue(const GemmDesc& g, f32x4 (&acc)[2][2][4][2], int brow, int bcol, int wr, int wc, int fr, int fq) {
;     ...
;           const int row = rowb + ai * HALF + m * 16;
;           f32x4 v0 = acc[ai][bj][m][0], v1 = acc[ai][bj][m][1];
;           if (g.rowscale) { const float ru = gld<float>(g.rowscale + row); v0 = v0 * ru; v1 = v1 * ru; }
;           v0 = v0 + b0; v1 = v1 + b1;
;           if (epi == EPI_RELU2) {
; #pragma unroll
;             for (int j = 0; j < 4; ++j) { float r0 = fmaxf(v0[j], 0.f), r1 = fmaxf(v1[j], 0.f); v0[j] = r0 * r0; v1[j] = r1 * r1; }
;           }
;           u32x4 w; w.x = pk(v0[0], v0[1]); w.y = pk(v0[2], v0[3]); w.z = pk(v1[0], v1[1]); w.w = pk(v1[2], v1[3]);
;           gst<u32x4>(g.o0 + (size_t)row * N + col, w);
.LBB0_175:
	v_add_u32_e32 v90, 0x90, v166
	v_cvt_pk_bf16_f32 v84, v84, v85
	v_cvt_pk_bf16_f32 v85, v86, v87
	v_cvt_pk_bf16_f32 v86, v80, v81
	v_mad_u64_u32 v[80:81], s[26:27], v90, s70, 0
	v_cvt_pk_bf16_f32 v87, v82, v83
	v_ashrrev_i32_e32 v83, 31, v90
	v_mov_b32_e32 v82, v81
	v_mad_u64_u32 v[82:83], s[26:27], v83, s70, v[82:83]
	v_mov_b32_e32 v81, v82
	v_lshl_add_u64 v[80:81], v[80:81], 1, s[64:65]
	v_lshl_add_u64 v[80:81], v[164:165], 1, v[80:81]
	s_and_b64 vcc, exec, s[44:45]
	global_store_dwordx4 v[80:81], v[84:87], off
	s_cbranch_vccnz .LBB0_177
	s_nop 1
	v_mov_b32_e32 v82, v242
	s_waitcnt vmcnt(0)
	v_pk_mul_f32 v[78:79], v[78:79], v[82:83] op_sel_hi:[1,0]
	v_pk_mul_f32 v[76:77], v[76:77], v[82:83] op_sel_hi:[1,0]
	v_pk_mul_f32 v[74:75], v[74:75], v[82:83] op_sel_hi:[1,0]
	v_pk_mul_f32 v[72:73], v[72:73], v[82:83] op_sel_hi:[1,0]

; DI unsigned pk(float lo, float hi) { f32x2 v = {lo, hi}; bf2_t b = __builtin_convertvector(v, bf2_t); return __builtin_bit_cast(unsigned, b); }
; DI void gemm_epilogue(const GemmDesc& g, f32x4 (&acc)[2][2][4][2], int brow, int bcol, int wr, int wc, int fr, int fq) {
;     ...
;           const int row = rowb + ai * HALF + m * 16;
;           f32x4 v0 = acc[ai][bj][m][0], v1 = acc[ai][bj][m][1];
;           if (g.rowscale) { const float ru = gld<float>(g.rowscale + row); v0 = v0 * ru; v1 = v1 * ru; }
;           v0 = v0 + b0; v1 = v1 + b1;
;           if (epi == EPI_RELU2) {
; #pragma unroll
;             for (int j = 0; j < 4; ++j) { float r0 = fmaxf(v0[j], 0.f), r1 = fmaxf(v1[j], 0.f); v0[j] = r0 * r0; v1[j] = r1 * r1; }
;           }
;           u32x4 w; w.x = pk(v0[0], v0[1]); w.y = pk(v0[2], v0[3]); w.z = pk(v1[0], v1[1]); w.w = pk(v1[2], v1[3]);
;           gst<u32x4>(g.o0 + (size_t)row * N + col, w);
.LBB0_179:
	v_add_u32_e32 v82, 0xa0, v166
	v_cvt_pk_bf16_f32 v76, v76, v77
	v_cvt_pk_bf16_f32 v77, v78, v79
	v_cvt_pk_bf16_f32 v78, v72, v73
	v_mad_u64_u32 v[72:73], s[26:27], v82, s70, 0
	v_cvt_pk_bf16_f32 v79, v74, v75
	v_ashrrev_i32_e32 v75, 31, v82
	v_mov_b32_e32 v74, v73
	v_mad_u64_u32 v[74:75], s[26:27], v75, s70, v[74:75]
	v_mov_b32_e32 v73, v74
	v_lshl_add_u64 v[72:73], v[72:73], 1, s[64:65]
	v_lshl_add_u64 v[72:73], v[164:165], 1, v[72:73]
	s_and_b64 vcc, exec, s[44:45]
	global_store_dwordx4 v[72:73], v[76:79], off
	s_cbranch_vccnz .LBB0_181
	s_nop 1
	v_mov_b32_e32 v74, v243
	s_waitcnt vmcnt(0)
	v_pk_mul_f32 v[70:71], v[70:71], v[74:75] op_sel_hi:[1,0]
	v_pk_mul_f32 v[68:69], v[68:69], v[74:75] op_sel_hi:[1,0]
	v_pk_mul_f32 v[66:67], v[66:67], v[74:75] op_sel_hi:[1,0]
	v_pk_mul_f32 v[64:65], v[64:65], v[74:75] op_sel_hi:[1,0]

; DI unsigned pk(float lo, float hi) { f32x2 v = {lo, hi}; bf2_t b = __builtin_convertvector(v, bf2_t); return __builtin_bit_cast(unsigned, b); }
; DI void gemm_epilogue(const GemmDesc& g, f32x4 (&acc)[2][2][4][2], int brow, int bcol, int wr, int wc, int fr, int fq) {
;     ...
;           const int row = rowb + ai * HALF + m * 16;
;           f32x4 v0 = acc[ai][bj][m][0], v1 = acc[ai][bj][m][1];
;           if (g.rowscale) { const float ru = gld<float>(g.rowscale + row); v0 = v0 * ru; v1 = v1 * ru; }
;           v0 = v0 + b0; v1 = v1 + b1;
;           if (epi == EPI_RELU2) {
; #pragma unroll
;             for (int j = 0; j < 4; ++j) { float r0 = fmaxf(v0[j], 0.f), r1 = fmaxf(v1[j], 0.f); v0[j] = r0 * r0; v1[j] = r1 * r1; }
;           }
;           u32x4 w; w.x = pk(v0[0], v0[1]); w.y = pk(v0[2], v0[3]); w.z = pk(v1[0], v1[1]); w.w = pk(v1[2], v1[3]);
;           gst<u32x4>(g.o0 + (size_t)row * N + col, w);
.LBB0_185:
	s_nop 1
	v_mov_b32_e32 v76, v236
	s_waitcnt vmcnt(0)
	v_pk_mul_f32 v[62:63], v[62:63], v[76:77] op_sel_hi:[1,0]
	v_pk_mul_f32 v[60:61], v[60:61], v[76:77] op_sel_hi:[1,0]
	v_pk_mul_f32 v[58:59], v[58:59], v[76:77] op_sel_hi:[1,0]
	v_pk_mul_f32 v[56:57], v[56:57], v[76:77] op_sel_hi:[1,0]

; DI unsigned pk(float lo, float hi) { f32x2 v = {lo, hi}; bf2_t b = __builtin_convertvector(v, bf2_t); return __builtin_bit_cast(unsigned, b); }
; DI void gemm_epilogue(const GemmDesc& g, f32x4 (&acc)[2][2][4][2], int brow, int bcol, int wr, int wc, int fr, int fq) {
;     ...
;           const int row = rowb + ai * HALF + m * 16;
;           f32x4 v0 = acc[ai][bj][m][0], v1 = acc[ai][bj][m][1];
;           if (g.rowscale) { const float ru = gld<float>(g.rowscale + row); v0 = v0 * ru; v1 = v1 * ru; }
;           v0 = v0 + b0; v1 = v1 + b1;
;           if (epi == EPI_RELU2) {
; #pragma unroll
;             for (int j = 0; j < 4; ++j) { float r0 = fmaxf(v0[j], 0.f), r1 = fmaxf(v1[j], 0.f); v0[j] = r0 * r0; v1[j] = r1 * r1; }
;           }
;           u32x4 w; w.x = pk(v0[0], v0[1]); w.y = pk(v0[2], v0[3]); w.z = pk(v1[0], v1[1]); w.w = pk(v1[2], v1[3]);
;           gst<u32x4>(g.o0 + (size_t)row * N + col, w);
.LBB0_188:
	v_cvt_pk_bf16_f32 v60, v60, v61
	v_cvt_pk_bf16_f32 v61, v62, v63
	v_cvt_pk_bf16_f32 v62, v56, v57
	v_cvt_pk_bf16_f32 v63, v58, v59
	s_and_b64 vcc, exec, s[44:45]
	global_store_dwordx4 v[122:123], v[60:63], off offset:256
	s_cbranch_vccnz .LBB0_190
	s_nop 1
	v_mov_b32_e32 v56, v237
	s_waitcnt vmcnt(0)
	v_pk_mul_f32 v[54:55], v[54:55], v[56:57] op_sel_hi:[1,0]
	v_pk_mul_f32 v[52:53], v[52:53], v[56:57] op_sel_hi:[1,0]
	v_pk_mul_f32 v[50:51], v[50:51], v[56:57] op_sel_hi:[1,0]
	v_pk_mul_f32 v[48:49], v[48:49], v[56:57] op_sel_hi:[1,0]

; DI unsigned pk(float lo, float hi) { f32x2 v = {lo, hi}; bf2_t b = __builtin_convertvector(v, bf2_t); return __builtin_bit_cast(unsigned, b); }
; DI void gemm_epilogue(const GemmDesc& g, f32x4 (&acc)[2][2][4][2], int brow, int bcol, int wr, int wc, int fr, int fq) {
;     ...
;           const int row = rowb + ai * HALF + m * 16;
;           f32x4 v0 = acc[ai][bj][m][0], v1 = acc[ai][bj][m][1];
;           if (g.rowscale) { const float ru = gld<float>(g.rowscale + row); v0 = v0 * ru; v1 = v1 * ru; }
;           v0 = v0 + b0; v1 = v1 + b1;
;           if (epi == EPI_RELU2) {
; #pragma unroll
;             for (int j = 0; j < 4; ++j) { float r0 = fmaxf(v0[j], 0.f), r1 = fmaxf(v1[j], 0.f); v0[j] = r0 * r0; v1[j] = r1 * r1; }
;           }
;           u32x4 w; w.x = pk(v0[0], v0[1]); w.y = pk(v0[2], v0[3]); w.z = pk(v1[0], v1[1]); w.w = pk(v1[2], v1[3]);
;           gst<u32x4>(g.o0 + (size_t)row * N + col, w);
.LBB0_192:
	v_cvt_pk_bf16_f32 v52, v52, v53
	v_cvt_pk_bf16_f32 v53, v54, v55
	v_cvt_pk_bf16_f32 v54, v48, v49
	v_cvt_pk_bf16_f32 v55, v50, v51
	s_and_b64 vcc, exec, s[44:45]
	global_store_dwordx4 v[112:113], v[52:55], off offset:256
	s_cbranch_vccnz .LBB0_194
	s_nop 1
	v_mov_b32_e32 v48, v238
	s_waitcnt vmcnt(0)
	v_pk_mul_f32 v[46:47], v[46:47], v[48:49] op_sel_hi:[1,0]
	v_pk_mul_f32 v[44:45], v[44:45], v[48:49] op_sel_hi:[1,0]
	v_pk_mul_f32 v[42:43], v[42:43], v[48:49] op_sel_hi:[1,0]
	v_pk_mul_f32 v[40:41], v[40:41], v[48:49] op_sel_hi:[1,0]

; DI unsigned pk(float lo, float hi) { f32x2 v = {lo, hi}; bf2_t b = __builtin_convertvector(v, bf2_t); return __builtin_bit_cast(unsigned, b); }
; DI void gemm_epilogue(const GemmDesc& g, f32x4 (&acc)[2][2][4][2], int brow, int bcol, int wr, int wc, int fr, int fq) {
;     ...
;           const int row = rowb + ai * HALF + m * 16;
;           f32x4 v0 = acc[ai][bj][m][0], v1 = acc[ai][bj][m][1];
;           if (g.rowscale) { const float ru = gld<float>(g.rowscale + row); v0 = v0 * ru; v1 = v1 * ru; }
;           v0 = v0 + b0; v1 = v1 + b1;
;           if (epi == EPI_RELU2) {
; #pragma unroll
;             for (int j = 0; j < 4; ++j) { float r0 = fmaxf(v0[j], 0.f), r1 = fmaxf(v1[j], 0.f); v0[j] = r0 * r0; v1[j] = r1 * r1; }
;           }
;           u32x4 w; w.x = pk(v0[0], v0[1]); w.y = pk(v0[2], v0[3]); w.z = pk(v1[0], v1[1]); w.w = pk(v1[2], v1[3]);
;           gst<u32x4>(g.o0 + (size_t)row * N + col, w);
.LBB0_196:
	v_cvt_pk_bf16_f32 v44, v44, v45
	v_cvt_pk_bf16_f32 v45, v46, v47
	v_cvt_pk_bf16_f32 v46, v40, v41
	v_cvt_pk_bf16_f32 v47, v42, v43
	s_and_b64 vcc, exec, s[44:45]
	global_store_dwordx4 v[104:105], v[44:47], off offset:256
	s_cbranch_vccnz .LBB0_198
	s_nop 1
	v_mov_b32_e32 v40, v239
	s_waitcnt vmcnt(0)
	v_pk_mul_f32 v[38:39], v[38:39], v[40:41] op_sel_hi:[1,0]
	v_pk_mul_f32 v[36:37], v[36:37], v[40:41] op_sel_hi:[1,0]
	v_pk_mul_f32 v[34:35], v[34:35], v[40:41] op_sel_hi:[1,0]
	v_pk_mul_f32 v[32:33], v[32:33], v[40:41] op_sel_hi:[1,0]

; DI unsigned pk(float lo, float hi) { f32x2 v = {lo, hi}; bf2_t b = __builtin_convertvector(v, bf2_t); return __builtin_bit_cast(unsigned, b); }
; DI void gemm_epilogue(const GemmDesc& g, f32x4 (&acc)[2][2][4][2], int brow, int bcol, int wr, int wc, int fr, int fq) {
;     ...
;           const int row = rowb + ai * HALF + m * 16;
;           f32x4 v0 = acc[ai][bj][m][0], v1 = acc[ai][bj][m][1];
;           if (g.rowscale) { const float ru = gld<float>(g.rowscale + row); v0 = v0 * ru; v1 = v1 * ru; }
;           v0 = v0 + b0; v1 = v1 + b1;
;           if (epi == EPI_RELU2) {
; #pragma unroll
;             for (int j = 0; j < 4; ++j) { float r0 = fmaxf(v0[j], 0.f), r1 = fmaxf(v1[j], 0.f); v0[j] = r0 * r0; v1[j] = r1 * r1; }
;           }
;           u32x4 w; w.x = pk(v0[0], v0[1]); w.y = pk(v0[2], v0[3]); w.z = pk(v1[0], v1[1]); w.w = pk(v1[2], v1[3]);
;           gst<u32x4>(g.o0 + (size_t)row * N + col, w);
.LBB0_200:
	v_cvt_pk_bf16_f32 v36, v36, v37
	v_cvt_pk_bf16_f32 v37, v38, v39
	v_cvt_pk_bf16_f32 v38, v32, v33
	v_cvt_pk_bf16_f32 v39, v34, v35
	s_and_b64 vcc, exec, s[44:45]
	global_store_dwordx4 v[96:97], v[36:39], off offset:256
	s_cbranch_vccnz .LBB0_202
	s_nop 1
	v_mov_b32_e32 v32, v240
	s_waitcnt vmcnt(0)
	v_pk_mul_f32 v[30:31], v[30:31], v[32:33] op_sel_hi:[1,0]
	v_pk_mul_f32 v[28:29], v[28:29], v[32:33] op_sel_hi:[1,0]
	v_pk_mul_f32 v[26:27], v[26:27], v[32:33] op_sel_hi:[1,0]
	v_pk_mul_f32 v[24:25], v[24:25], v[32:33] op_sel_hi:[1,0]

; DI unsigned pk(float lo, float hi) { f32x2 v = {lo, hi}; bf2_t b = __builtin_convertvector(v, bf2_t); return __builtin_bit_cast(unsigned, b); }
; DI void gemm_epilogue(const GemmDesc& g, f32x4 (&acc)[2][2][4][2], int brow, int bcol, int wr, int wc, int fr, int fq) {
;     ...
;           const int row = rowb + ai * HALF + m * 16;
;           f32x4 v0 = acc[ai][bj][m][0], v1 = acc[ai][bj][m][1];
;           if (g.rowscale) { const float ru = gld<float>(g.rowscale + row); v0 = v0 * ru; v1 = v1 * ru; }
;           v0 = v0 + b0; v1 = v1 + b1;
;           if (epi == EPI_RELU2) {
; #pragma unroll
;             for (int j = 0; j < 4; ++j) { float r0 = fmaxf(v0[j], 0.f), r1 = fmaxf(v1[j], 0.f); v0[j] = r0 * r0; v1[j] = r1 * r1; }
;           }
;           u32x4 w; w.x = pk(v0[0], v0[1]); w.y = pk(v0[2], v0[3]); w.z = pk(v1[0], v1[1]); w.w = pk(v1[2], v1[3]);
;           gst<u32x4>(g.o0 + (size_t)row * N + col, w);
.LBB0_204:
	v_cvt_pk_bf16_f32 v28, v28, v29
	v_cvt_pk_bf16_f32 v29, v30, v31
	v_cvt_pk_bf16_f32 v30, v24, v25
	v_cvt_pk_bf16_f32 v31, v26, v27
	s_and_b64 vcc, exec, s[44:45]
	global_store_dwordx4 v[88:89], v[28:31], off offset:256
	s_cbranch_vccnz .LBB0_206
	s_nop 1
	v_mov_b32_e32 v24, v241
	s_waitcnt vmcnt(0)
	v_pk_mul_f32 v[22:23], v[22:23], v[24:25] op_sel_hi:[1,0]
	v_pk_mul_f32 v[20:21], v[20:21], v[24:25] op_sel_hi:[1,0]
	v_pk_mul_f32 v[18:19], v[18:19], v[24:25] op_sel_hi:[1,0]
	v_pk_mul_f32 v[16:17], v[16:17], v[24:25] op_sel_hi:[1,0]

; DI unsigned pk(float lo, float hi) { f32x2 v = {lo, hi}; bf2_t b = __builtin_convertvector(v, bf2_t); return __builtin_bit_cast(unsigned, b); }
; DI void gemm_epilogue(const GemmDesc& g, f32x4 (&acc)[2][2][4][2], int brow, int bcol, int wr, int wc, int fr, int fq) {
;     ...
;           const int row = rowb + ai * HALF + m * 16;
;           f32x4 v0 = acc[ai][bj][m][0], v1 = acc[ai][bj][m][1];
;           if (g.rowscale) { const float ru = gld<float>(g.rowscale + row); v0 = v0 * ru; v1 = v1 * ru; }
;           v0 = v0 + b0; v1 = v1 + b1;
;           if (epi == EPI_RELU2) {
; #pragma unroll
;             for (int j = 0; j < 4; ++j) { float r0 = fmaxf(v0[j], 0.f), r1 = fmaxf(v1[j], 0.f); v0[j] = r0 * r0; v1[j] = r1 * r1; }
;           }
;           u32x4 w; w.x = pk(v0[0], v0[1]); w.y = pk(v0[2], v0[3]); w.z = pk(v1[0], v1[1]); w.w = pk(v1[2], v1[3]);
;           gst<u32x4>(g.o0 + (size_t)row * N + col, w);
.LBB0_208:
	v_cvt_pk_bf16_f32 v20, v20, v21
	v_cvt_pk_bf16_f32 v21, v22, v23
	v_cvt_pk_bf16_f32 v22, v16, v17
	v_cvt_pk_bf16_f32 v23, v18, v19
	s_and_b64 vcc, exec, s[44:45]
	global_store_dwordx4 v[80:81], v[20:23], off offset:256
	s_cbranch_vccnz .LBB0_210
	s_nop 1
	v_mov_b32_e32 v16, v242
	s_waitcnt vmcnt(0)
	v_pk_mul_f32 v[14:15], v[14:15], v[16:17] op_sel_hi:[1,0]
	v_pk_mul_f32 v[12:13], v[12:13], v[16:17] op_sel_hi:[1,0]
	v_pk_mul_f32 v[10:11], v[10:11], v[16:17] op_sel_hi:[1,0]
	v_pk_mul_f32 v[8:9], v[8:9], v[16:17] op_sel_hi:[1,0]

; DI unsigned pk(float lo, float hi) { f32x2 v = {lo, hi}; bf2_t b = __builtin_convertvector(v, bf2_t); return __builtin_bit_cast(unsigned, b); }
; DI void gemm_epilogue(const GemmDesc& g, f32x4 (&acc)[2][2][4][2], int brow, int bcol, int wr, int wc, int fr, int fq) {
;     ...
;           const int row = rowb + ai * HALF + m * 16;
;           f32x4 v0 = acc[ai][bj][m][0], v1 = acc[ai][bj][m][1];
;           if (g.rowscale) { const float ru = gld<float>(g.rowscale + row); v0 = v0 * ru; v1 = v1 * ru; }
;           v0 = v0 + b0; v1 = v1 + b1;
;           if (epi == EPI_RELU2) {
; #pragma unroll
;             for (int j = 0; j < 4; ++j) { float r0 = fmaxf(v0[j], 0.f), r1 = fmaxf(v1[j], 0.f); v0[j] = r0 * r0; v1[j] = r1 * r1; }
;           }
;           u32x4 w; w.x = pk(v0[0], v0[1]); w.y = pk(v0[2], v0[3]); w.z = pk(v1[0], v1[1]); w.w = pk(v1[2], v1[3]);
;           gst<u32x4>(g.o0 + (size_t)row * N + col, w);
.LBB0_212:
	v_cvt_pk_bf16_f32 v12, v12, v13
	v_cvt_pk_bf16_f32 v13, v14, v15
	v_cvt_pk_bf16_f32 v14, v8, v9
	v_cvt_pk_bf16_f32 v15, v10, v11
	s_and_b64 vcc, exec, s[44:45]
	global_store_dwordx4 v[72:73], v[12:15], off offset:256
	s_cbranch_vccnz .LBB0_214
	s_nop 1
	v_mov_b32_e32 v8, v243
	s_waitcnt vmcnt(0)
	v_pk_mul_f32 v[6:7], v[6:7], v[8:9] op_sel_hi:[1,0]
	v_pk_mul_f32 v[4:5], v[4:5], v[8:9] op_sel_hi:[1,0]
	v_pk_mul_f32 v[2:3], v[2:3], v[8:9] op_sel_hi:[1,0]
	v_pk_mul_f32 v[0:1], v[0:1], v[8:9] op_sel_hi:[1,0]

; DI unsigned pk(float lo, float hi) { f32x2 v = {lo, hi}; bf2_t b = __builtin_convertvector(v, bf2_t); return __builtin_bit_cast(unsigned, b); }
; DI void gemm_epilogue(const GemmDesc& g, f32x4 (&acc)[2][2][4][2], int brow, int bcol, int wr, int wc, int fr, int fq) {
;     ...
;           const int row = rowb + ai * HALF + m * 16;
;           const float ru = gld<float>(g.rowscale + row);
;           f32x4 v0 = acc[ai][bj][m][0] * ru, v1 = acc[ai][bj][m][1] * ru;
;           if (bcol < 2048) {
;             if (bcol < 512) { v0 = v0 * 0.08838834764831845f; v1 = v1 * 0.08838834764831845f; }
;             bf16_t* base = (bcol < 1024) ? (g.o0 + (size_t)row * 1024 + col) : (g.o1 + (size_t)row * 1024 + (col - 1024));
;             u32x4 w; w.x = pk(v0[0], v0[1]); w.y = pk(v0[2], v0[3]); w.z = pk(v1[0], v1[1]); w.w = pk(v1[2], v1[3]);
;             gst<u32x4>(base, w);
;           } else if (col < 2080) {
;             gst<f32x4>(g.f0 + (size_t)row * 32 + (col - 2048), v0); gst<f32x4>(g.f0 + (size_t)row * 32 + (col - 2048) + 4, v1);
;           }
.LBB0_257:
	v_ashrrev_i32_e32 v167, 31, v166
	v_lshl_add_u64 v[138:139], v[166:167], 2, s[22:23]
	global_load_dword v236, v[138:139], off
	global_load_dword v237, v[138:139], off offset:64
	global_load_dword v238, v[138:139], off offset:128
	global_load_dword v239, v[138:139], off offset:192
	global_load_dword v240, v[138:139], off offset:512
	global_load_dword v241, v[138:139], off offset:576
	global_load_dword v242, v[138:139], off offset:640
	global_load_dword v243, v[138:139], off offset:704
	global_load_dword v128, v[138:139], off
	s_cmp_gt_i32 s5, 7
	s_cselect_b64 s[46:47], -1, 0
	s_cmp_lt_i32 s5, 2
	s_movk_i32 s26, 0x820
	v_add_u32_e32 v192, 0xfffff800, v164
	s_cselect_b64 s[44:45], -1, 0
	s_cmp_gt_i32 s5, 3
	v_cmp_gt_i32_e64 s[50:51], s26, v164
	s_mov_b64 s[48:49], -1
	v_ashrrev_i32_e32 v193, 31, v192
	s_cselect_b64 s[26:27], -1, 0
	s_and_b64 vcc, exec, s[46:47]
	s_waitcnt vmcnt(0)
	v_pk_mul_f32 v[134:135], v[126:127], v[128:129] op_sel_hi:[1,0]
	v_pk_mul_f32 v[132:133], v[124:125], v[128:129] op_sel_hi:[1,0]
	v_pk_mul_f32 v[130:131], v[122:123], v[128:129] op_sel_hi:[1,0]
	v_pk_mul_f32 v[128:129], v[120:121], v[128:129] op_sel_hi:[1,0]
	s_cbranch_vccz .LBB0_261
	s_and_saveexec_b64 s[48:49], s[50:51]
	s_cbranch_execz .LBB0_260
	v_lshlrev_b64 v[136:137], 7, v[166:167]
	v_lshl_add_u64 v[136:137], s[66:67], 0, v[136:137]
	v_lshl_add_u64 v[136:137], v[192:193], 2, v[136:137]
	global_store_dwordx4 v[136:137], v[132:135], off
	global_store_dwordx4 v[136:137], v[128:131], off offset:16

; DI unsigned pk(float lo, float hi) { f32x2 v = {lo, hi}; bf2_t b = __builtin_convertvector(v, bf2_t); return __builtin_bit_cast(unsigned, b); }
; DI void gemm_epilogue(const GemmDesc& g, f32x4 (&acc)[2][2][4][2], int brow, int bcol, int wr, int wc, int fr, int fq) {
;     ...
;           const int row = rowb + ai * HALF + m * 16;
;           const float ru = gld<float>(g.rowscale + row);
;           f32x4 v0 = acc[ai][bj][m][0] * ru, v1 = acc[ai][bj][m][1] * ru;
;           if (bcol < 2048) {
;             if (bcol < 512) { v0 = v0 * 0.08838834764831845f; v1 = v1 * 0.08838834764831845f; }
;             bf16_t* base = (bcol < 1024) ? (g.o0 + (size_t)row * 1024 + col) : (g.o1 + (size_t)row * 1024 + (col - 1024));
;             u32x4 w; w.x = pk(v0[0], v0[1]); w.y = pk(v0[2], v0[3]); w.z = pk(v1[0], v1[1]); w.w = pk(v1[2], v1[3]);
;             gst<u32x4>(base, w);
;           } else if (col < 2080) {
;             gst<f32x4>(g.f0 + (size_t)row * 32 + (col - 2048), v0); gst<f32x4>(g.f0 + (size_t)row * 32 + (col - 2048) + 4, v1);
;           }
.LBB0_267:
	s_nop 1
	v_mov_b32_e32 v128, v237
	v_or_b32_e32 v140, 16, v166
	v_cndmask_b32_e64 v129, 0, 1, s[46:47]
	v_ashrrev_i32_e32 v141, 31, v140
	v_cmp_ne_u32_e64 s[48:49], 1, v129
	s_andn2_b64 vcc, exec, s[46:47]
	s_mov_b64 s[46:47], -1
	s_waitcnt vmcnt(0)
	v_pk_mul_f32 v[134:135], v[118:119], v[128:129] op_sel_hi:[1,0]
	v_pk_mul_f32 v[132:133], v[116:117], v[128:129] op_sel_hi:[1,0]
	v_pk_mul_f32 v[130:131], v[114:115], v[128:129] op_sel_hi:[1,0]
	v_pk_mul_f32 v[128:129], v[112:113], v[128:129] op_sel_hi:[1,0]
	s_cbranch_vccnz .LBB0_271
	s_and_saveexec_b64 s[46:47], s[50:51]
	s_cbranch_execz .LBB0_270
	v_lshlrev_b64 v[168:169], 7, v[140:141]
	v_lshl_add_u64 v[168:169], s[66:67], 0, v[168:169]
	v_lshl_add_u64 v[168:169], v[192:193], 2, v[168:169]
	global_store_dwordx4 v[168:169], v[132:135], off
	global_store_dwordx4 v[168:169], v[128:131], off offset:16

; DI unsigned pk(float lo, float hi) { f32x2 v = {lo, hi}; bf2_t b = __builtin_convertvector(v, bf2_t); return __builtin_bit_cast(unsigned, b); }
; DI void gemm_epilogue(const GemmDesc& g, f32x4 (&acc)[2][2][4][2], int brow, int bcol, int wr, int wc, int fr, int fq) {
;     ...
;           const int row = rowb + ai * HALF + m * 16;
;           const float ru = gld<float>(g.rowscale + row);
;           f32x4 v0 = acc[ai][bj][m][0] * ru, v1 = acc[ai][bj][m][1] * ru;
;           if (bcol < 2048) {
;             if (bcol < 512) { v0 = v0 * 0.08838834764831845f; v1 = v1 * 0.08838834764831845f; }
;             bf16_t* base = (bcol < 1024) ? (g.o0 + (size_t)row * 1024 + col) : (g.o1 + (size_t)row * 1024 + (col - 1024));
;             u32x4 w; w.x = pk(v0[0], v0[1]); w.y = pk(v0[2], v0[3]); w.z = pk(v1[0], v1[1]); w.w = pk(v1[2], v1[3]);
;             gst<u32x4>(base, w);
;           } else if (col < 2080) {
;             gst<f32x4>(g.f0 + (size_t)row * 32 + (col - 2048), v0); gst<f32x4>(g.f0 + (size_t)row * 32 + (col - 2048) + 4, v1);
;           }
.LBB0_277:
	s_nop 1
	v_mov_b32_e32 v128, v238
	v_or_b32_e32 v168, 32, v166
	s_and_b64 vcc, exec, s[48:49]
	v_ashrrev_i32_e32 v169, 31, v168
	s_mov_b64 s[26:27], -1
	s_waitcnt vmcnt(0)
	v_pk_mul_f32 v[134:135], v[110:111], v[128:129] op_sel_hi:[1,0]
	v_pk_mul_f32 v[132:133], v[108:109], v[128:129] op_sel_hi:[1,0]
	v_pk_mul_f32 v[130:131], v[106:107], v[128:129] op_sel_hi:[1,0]
	v_pk_mul_f32 v[128:129], v[104:105], v[128:129] op_sel_hi:[1,0]
	s_cbranch_vccnz .LBB0_281
	s_and_saveexec_b64 s[26:27], s[50:51]
	s_cbranch_execz .LBB0_280
	v_lshlrev_b64 v[172:173], 7, v[168:169]
	v_lshl_add_u64 v[172:173], s[66:67], 0, v[172:173]
	v_lshl_add_u64 v[172:173], v[192:193], 2, v[172:173]
	global_store_dwordx4 v[172:173], v[132:135], off
	global_store_dwordx4 v[172:173], v[128:131], off offset:16

; DI unsigned pk(float lo, float hi) { f32x2 v = {lo, hi}; bf2_t b = __builtin_convertvector(v, bf2_t); return __builtin_bit_cast(unsigned, b); }
; DI void gemm_epilogue(const GemmDesc& g, f32x4 (&acc)[2][2][4][2], int brow, int bcol, int wr, int wc, int fr, int fq) {
;     ...
;           const int row = rowb + ai * HALF + m * 16;
;           const float ru = gld<float>(g.rowscale + row);
;           f32x4 v0 = acc[ai][bj][m][0] * ru, v1 = acc[ai][bj][m][1] * ru;
;           if (bcol < 2048) {
;             if (bcol < 512) { v0 = v0 * 0.08838834764831845f; v1 = v1 * 0.08838834764831845f; }
;             bf16_t* base = (bcol < 1024) ? (g.o0 + (size_t)row * 1024 + col) : (g.o1 + (size_t)row * 1024 + (col - 1024));
;             u32x4 w; w.x = pk(v0[0], v0[1]); w.y = pk(v0[2], v0[3]); w.z = pk(v1[0], v1[1]); w.w = pk(v1[2], v1[3]);
;             gst<u32x4>(base, w);
;           } else if (col < 2080) {
;             gst<f32x4>(g.f0 + (size_t)row * 32 + (col - 2048), v0); gst<f32x4>(g.f0 + (size_t)row * 32 + (col - 2048) + 4, v1);
;           }
.LBB0_287:
	s_nop 1
	v_mov_b32_e32 v128, v239
	v_or_b32_e32 v172, 48, v166
	s_and_b64 vcc, exec, s[48:49]
	v_ashrrev_i32_e32 v173, 31, v172
	s_mov_b64 s[26:27], -1
	s_waitcnt vmcnt(0)
	v_pk_mul_f32 v[134:135], v[102:103], v[128:129] op_sel_hi:[1,0]
	v_pk_mul_f32 v[132:133], v[100:101], v[128:129] op_sel_hi:[1,0]
	v_pk_mul_f32 v[130:131], v[98:99], v[128:129] op_sel_hi:[1,0]
	v_pk_mul_f32 v[128:129], v[96:97], v[128:129] op_sel_hi:[1,0]
	s_cbranch_vccnz .LBB0_291
	s_and_saveexec_b64 s[26:27], s[50:51]
	s_cbranch_execz .LBB0_290
	v_lshlrev_b64 v[176:177], 7, v[172:173]
	v_lshl_add_u64 v[176:177], s[66:67], 0, v[176:177]
	v_lshl_add_u64 v[176:177], v[192:193], 2, v[176:177]
	global_store_dwordx4 v[176:177], v[132:135], off
	global_store_dwordx4 v[176:177], v[128:131], off offset:16

; DI unsigned pk(float lo, float hi) { f32x2 v = {lo, hi}; bf2_t b = __builtin_convertvector(v, bf2_t); return __builtin_bit_cast(unsigned, b); }
; DI void gemm_epilogue(const GemmDesc& g, f32x4 (&acc)[2][2][4][2], int brow, int bcol, int wr, int wc, int fr, int fq) {
;     ...
;           const int row = rowb + ai * HALF + m * 16;
;           const float ru = gld<float>(g.rowscale + row);
;           f32x4 v0 = acc[ai][bj][m][0] * ru, v1 = acc[ai][bj][m][1] * ru;
;           if (bcol < 2048) {
;             if (bcol < 512) { v0 = v0 * 0.08838834764831845f; v1 = v1 * 0.08838834764831845f; }
;             bf16_t* base = (bcol < 1024) ? (g.o0 + (size_t)row * 1024 + col) : (g.o1 + (size_t)row * 1024 + (col - 1024));
;             u32x4 w; w.x = pk(v0[0], v0[1]); w.y = pk(v0[2], v0[3]); w.z = pk(v1[0], v1[1]); w.w = pk(v1[2], v1[3]);
;             gst<u32x4>(base, w);
;           } else if (col < 2080) {
;             gst<f32x4>(g.f0 + (size_t)row * 32 + (col - 2048), v0); gst<f32x4>(g.f0 + (size_t)row * 32 + (col - 2048) + 4, v1);
;           }
.LBB0_297:
	s_nop 1
	v_mov_b32_e32 v128, v240
	v_add_u32_e32 v176, 0x80, v166
	s_and_b64 vcc, exec, s[48:49]
	v_ashrrev_i32_e32 v177, 31, v176
	s_mov_b64 s[26:27], -1
	s_waitcnt vmcnt(0)
	v_pk_mul_f32 v[134:135], v[94:95], v[128:129] op_sel_hi:[1,0]
	v_pk_mul_f32 v[132:133], v[92:93], v[128:129] op_sel_hi:[1,0]
	v_pk_mul_f32 v[130:131], v[90:91], v[128:129] op_sel_hi:[1,0]
	v_pk_mul_f32 v[128:129], v[88:89], v[128:129] op_sel_hi:[1,0]
	s_cbranch_vccnz .LBB0_301
	s_and_saveexec_b64 s[26:27], s[50:51]
	s_cbranch_execz .LBB0_300
	v_lshlrev_b64 v[180:181], 7, v[176:177]
	v_lshl_add_u64 v[180:181], s[66:67], 0, v[180:181]
	v_lshl_add_u64 v[180:181], v[192:193], 2, v[180:181]
	global_store_dwordx4 v[180:181], v[132:135], off
	global_store_dwordx4 v[180:181], v[128:131], off offset:16

; DI unsigned pk(float lo, float hi) { f32x2 v = {lo, hi}; bf2_t b = __builtin_convertvector(v, bf2_t); return __builtin_bit_cast(unsigned, b); }
; DI void gemm_epilogue(const GemmDesc& g, f32x4 (&acc)[2][2][4][2], int brow, int bcol, int wr, int wc, int fr, int fq) {
;     ...
;           const int row = rowb + ai * HALF + m * 16;
;           const float ru = gld<float>(g.rowscale + row);
;           f32x4 v0 = acc[ai][bj][m][0] * ru, v1 = acc[ai][bj][m][1] * ru;
;           if (bcol < 2048) {
;             if (bcol < 512) { v0 = v0 * 0.08838834764831845f; v1 = v1 * 0.08838834764831845f; }
;             bf16_t* base = (bcol < 1024) ? (g.o0 + (size_t)row * 1024 + col) : (g.o1 + (size_t)row * 1024 + (col - 1024));
;             u32x4 w; w.x = pk(v0[0], v0[1]); w.y = pk(v0[2], v0[3]); w.z = pk(v1[0], v1[1]); w.w = pk(v1[2], v1[3]);
;             gst<u32x4>(base, w);
;           } else if (col < 2080) {
;             gst<f32x4>(g.f0 + (size_t)row * 32 + (col - 2048), v0); gst<f32x4>(g.f0 + (size_t)row * 32 + (col - 2048) + 4, v1);
;           }
.LBB0_307:
	s_nop 1
	v_mov_b32_e32 v128, v241
	v_add_u32_e32 v180, 0x90, v166
	s_and_b64 vcc, exec, s[48:49]
	v_ashrrev_i32_e32 v181, 31, v180
	s_mov_b64 s[26:27], -1
	s_waitcnt vmcnt(0)
	v_pk_mul_f32 v[134:135], v[86:87], v[128:129] op_sel_hi:[1,0]
	v_pk_mul_f32 v[132:133], v[84:85], v[128:129] op_sel_hi:[1,0]
	v_pk_mul_f32 v[130:131], v[82:83], v[128:129] op_sel_hi:[1,0]
	v_pk_mul_f32 v[128:129], v[80:81], v[128:129] op_sel_hi:[1,0]
	s_cbranch_vccnz .LBB0_311
	s_and_saveexec_b64 s[26:27], s[50:51]
	s_cbranch_execz .LBB0_310
	v_lshlrev_b64 v[184:185], 7, v[180:181]
	v_lshl_add_u64 v[184:185], s[66:67], 0, v[184:185]
	v_lshl_add_u64 v[184:185], v[192:193], 2, v[184:185]
	global_store_dwordx4 v[184:185], v[132:135], off
	global_store_dwordx4 v[184:185], v[128:131], off offset:16

; DI unsigned pk(float lo, float hi) { f32x2 v = {lo, hi}; bf2_t b = __builtin_convertvector(v, bf2_t); return __builtin_bit_cast(unsigned, b); }
; DI void gemm_epilogue(const GemmDesc& g, f32x4 (&acc)[2][2][4][2], int brow, int bcol, int wr, int wc, int fr, int fq) {
;     ...
;           const int row = rowb + ai * HALF + m * 16;
;           const float ru = gld<float>(g.rowscale + row);
;           f32x4 v0 = acc[ai][bj][m][0] * ru, v1 = acc[ai][bj][m][1] * ru;
;           if (bcol < 2048) {
;             if (bcol < 512) { v0 = v0 * 0.08838834764831845f; v1 = v1 * 0.08838834764831845f; }
;             bf16_t* base = (bcol < 1024) ? (g.o0 + (size_t)row * 1024 + col) : (g.o1 + (size_t)row * 1024 + (col - 1024));
;             u32x4 w; w.x = pk(v0[0], v0[1]); w.y = pk(v0[2], v0[3]); w.z = pk(v1[0], v1[1]); w.w = pk(v1[2], v1[3]);
;             gst<u32x4>(base, w);
;           } else if (col < 2080) {
;             gst<f32x4>(g.f0 + (size_t)row * 32 + (col - 2048), v0); gst<f32x4>(g.f0 + (size_t)row * 32 + (col - 2048) + 4, v1);
;           }
.LBB0_317:
	s_nop 1
	v_mov_b32_e32 v128, v242
	v_add_u32_e32 v184, 0xa0, v166
	s_and_b64 vcc, exec, s[48:49]
	v_ashrrev_i32_e32 v185, 31, v184
	s_mov_b64 s[26:27], -1
	s_waitcnt vmcnt(0)
	v_pk_mul_f32 v[134:135], v[78:79], v[128:129] op_sel_hi:[1,0]
	v_pk_mul_f32 v[132:133], v[76:77], v[128:129] op_sel_hi:[1,0]
	v_pk_mul_f32 v[130:131], v[74:75], v[128:129] op_sel_hi:[1,0]
	v_pk_mul_f32 v[128:129], v[72:73], v[128:129] op_sel_hi:[1,0]
	s_cbranch_vccnz .LBB0_321
	s_and_saveexec_b64 s[26:27], s[50:51]
	s_cbranch_execz .LBB0_320
	v_lshlrev_b64 v[188:189], 7, v[184:185]
	v_lshl_add_u64 v[188:189], s[66:67], 0, v[188:189]
	v_lshl_add_u64 v[188:189], v[192:193], 2, v[188:189]
	global_store_dwordx4 v[188:189], v[132:135], off
	global_store_dwordx4 v[188:189], v[128:131], off offset:16

; DI unsigned pk(float lo, float hi) { f32x2 v = {lo, hi}; bf2_t b = __builtin_convertvector(v, bf2_t); return __builtin_bit_cast(unsigned, b); }
; DI void gemm_epilogue(const GemmDesc& g, f32x4 (&acc)[2][2][4][2], int brow, int bcol, int wr, int wc, int fr, int fq) {
;     ...
;           const int row = rowb + ai * HALF + m * 16;
;           const float ru = gld<float>(g.rowscale + row);
;           f32x4 v0 = acc[ai][bj][m][0] * ru, v1 = acc[ai][bj][m][1] * ru;
;           if (bcol < 2048) {
;             if (bcol < 512) { v0 = v0 * 0.08838834764831845f; v1 = v1 * 0.08838834764831845f; }
;             bf16_t* base = (bcol < 1024) ? (g.o0 + (size_t)row * 1024 + col) : (g.o1 + (size_t)row * 1024 + (col - 1024));
;             u32x4 w; w.x = pk(v0[0], v0[1]); w.y = pk(v0[2], v0[3]); w.z = pk(v1[0], v1[1]); w.w = pk(v1[2], v1[3]);
;             gst<u32x4>(base, w);
;           } else if (col < 2080) {
;             gst<f32x4>(g.f0 + (size_t)row * 32 + (col - 2048), v0); gst<f32x4>(g.f0 + (size_t)row * 32 + (col - 2048) + 4, v1);
;           }
.LBB0_327:
	s_nop 1
	v_mov_b32_e32 v128, v243
	v_add_u32_e32 v188, 0xb0, v166
	s_and_b64 vcc, exec, s[48:49]
	v_ashrrev_i32_e32 v189, 31, v188
	s_mov_b64 s[26:27], -1
	s_waitcnt vmcnt(0)
	v_pk_mul_f32 v[134:135], v[70:71], v[128:129] op_sel_hi:[1,0]
	v_pk_mul_f32 v[132:133], v[68:69], v[128:129] op_sel_hi:[1,0]
	v_pk_mul_f32 v[130:131], v[66:67], v[128:129] op_sel_hi:[1,0]
	v_pk_mul_f32 v[128:129], v[64:65], v[128:129] op_sel_hi:[1,0]
	s_cbranch_vccnz .LBB0_331
	s_and_saveexec_b64 s[26:27], s[50:51]
	s_cbranch_execz .LBB0_330
	v_lshlrev_b64 v[194:195], 7, v[188:189]
	v_lshl_add_u64 v[194:195], s[66:67], 0, v[194:195]
	v_lshl_add_u64 v[192:193], v[192:193], 2, v[194:195]
	global_store_dwordx4 v[192:193], v[132:135], off
	global_store_dwordx4 v[192:193], v[128:131], off offset:16

; DI unsigned pk(float lo, float hi) { f32x2 v = {lo, hi}; bf2_t b = __builtin_convertvector(v, bf2_t); return __builtin_bit_cast(unsigned, b); }
; DI void gemm_epilogue(const GemmDesc& g, f32x4 (&acc)[2][2][4][2], int brow, int bcol, int wr, int wc, int fr, int fq) {
;     ...
;           const int row = rowb + ai * HALF + m * 16;
;           const float ru = gld<float>(g.rowscale + row);
;           f32x4 v0 = acc[ai][bj][m][0] * ru, v1 = acc[ai][bj][m][1] * ru;
;           if (bcol < 2048) {
;             if (bcol < 512) { v0 = v0 * 0.08838834764831845f; v1 = v1 * 0.08838834764831845f; }
;             bf16_t* base = (bcol < 1024) ? (g.o0 + (size_t)row * 1024 + col) : (g.o1 + (size_t)row * 1024 + (col - 1024));
;             u32x4 w; w.x = pk(v0[0], v0[1]); w.y = pk(v0[2], v0[3]); w.z = pk(v1[0], v1[1]); w.w = pk(v1[2], v1[3]);
;             gst<u32x4>(base, w);
;           } else if (col < 2080) {
;             gst<f32x4>(g.f0 + (size_t)row * 32 + (col - 2048), v0); gst<f32x4>(g.f0 + (size_t)row * 32 + (col - 2048) + 4, v1);
;           }
.LBB0_337:
	s_nop 1
	v_mov_b32_e32 v128, v236
	s_movk_i32 s26, 0x7a0
	v_add_u32_e32 v194, 0xfffff880, v164
	v_cmp_gt_i32_e64 s[50:51], s26, v164
	s_and_b64 vcc, exec, s[48:49]
	v_ashrrev_i32_e32 v195, 31, v194
	s_mov_b64 s[26:27], -1
	s_waitcnt vmcnt(0)
	v_pk_mul_f32 v[134:135], v[62:63], v[128:129] op_sel_hi:[1,0]
	v_pk_mul_f32 v[132:133], v[60:61], v[128:129] op_sel_hi:[1,0]
	v_pk_mul_f32 v[130:131], v[58:59], v[128:129] op_sel_hi:[1,0]
	v_pk_mul_f32 v[128:129], v[56:57], v[128:129] op_sel_hi:[1,0]
	s_cbranch_vccnz .LBB0_341
	s_and_saveexec_b64 s[26:27], s[50:51]
	s_cbranch_execz .LBB0_340
	v_lshlrev_b64 v[196:197], 7, v[166:167]
	v_lshl_add_u64 v[196:197], s[66:67], 0, v[196:197]
	v_lshl_add_u64 v[196:197], v[194:195], 2, v[196:197]
	global_store_dwordx4 v[196:197], v[132:135], off
	global_store_dwordx4 v[196:197], v[128:131], off offset:16

; DI unsigned pk(float lo, float hi) { f32x2 v = {lo, hi}; bf2_t b = __builtin_convertvector(v, bf2_t); return __builtin_bit_cast(unsigned, b); }
; DI void gemm_epilogue(const GemmDesc& g, f32x4 (&acc)[2][2][4][2], int brow, int bcol, int wr, int wc, int fr, int fq) {
;     ...
;           const int row = rowb + ai * HALF + m * 16;
;           const float ru = gld<float>(g.rowscale + row);
;           f32x4 v0 = acc[ai][bj][m][0] * ru, v1 = acc[ai][bj][m][1] * ru;
;           if (bcol < 2048) {
;             if (bcol < 512) { v0 = v0 * 0.08838834764831845f; v1 = v1 * 0.08838834764831845f; }
;             bf16_t* base = (bcol < 1024) ? (g.o0 + (size_t)row * 1024 + col) : (g.o1 + (size_t)row * 1024 + (col - 1024));
;             u32x4 w; w.x = pk(v0[0], v0[1]); w.y = pk(v0[2], v0[3]); w.z = pk(v1[0], v1[1]); w.w = pk(v1[2], v1[3]);
;             gst<u32x4>(base, w);
;           } else if (col < 2080) {
;             gst<f32x4>(g.f0 + (size_t)row * 32 + (col - 2048), v0); gst<f32x4>(g.f0 + (size_t)row * 32 + (col - 2048) + 4, v1);
;           }
.LBB0_347:
	s_nop 1
	v_mov_b32_e32 v128, v237
	s_and_b64 vcc, exec, s[48:49]
	s_mov_b64 s[26:27], -1
	s_waitcnt vmcnt(0)
	v_pk_mul_f32 v[134:135], v[54:55], v[128:129] op_sel_hi:[1,0]
	v_pk_mul_f32 v[132:133], v[52:53], v[128:129] op_sel_hi:[1,0]
	v_pk_mul_f32 v[130:131], v[50:51], v[128:129] op_sel_hi:[1,0]
	v_pk_mul_f32 v[128:129], v[48:49], v[128:129] op_sel_hi:[1,0]
	s_cbranch_vccnz .LBB0_351
	s_and_saveexec_b64 s[26:27], s[50:51]
	s_cbranch_execz .LBB0_350
	v_lshlrev_b64 v[140:141], 7, v[140:141]
	v_lshl_add_u64 v[140:141], s[66:67], 0, v[140:141]
	v_lshl_add_u64 v[140:141], v[194:195], 2, v[140:141]
	global_store_dwordx4 v[140:141], v[132:135], off
	global_store_dwordx4 v[140:141], v[128:131], off offset:16

; DI unsigned pk(float lo, float hi) { f32x2 v = {lo, hi}; bf2_t b = __builtin_convertvector(v, bf2_t); return __builtin_bit_cast(unsigned, b); }
; DI void gemm_epilogue(const GemmDesc& g, f32x4 (&acc)[2][2][4][2], int brow, int bcol, int wr, int wc, int fr, int fq) {
;     ...
;           const int row = rowb + ai * HALF + m * 16;
;           const float ru = gld<float>(g.rowscale + row);
;           f32x4 v0 = acc[ai][bj][m][0] * ru, v1 = acc[ai][bj][m][1] * ru;
;           if (bcol < 2048) {
;             if (bcol < 512) { v0 = v0 * 0.08838834764831845f; v1 = v1 * 0.08838834764831845f; }
;             bf16_t* base = (bcol < 1024) ? (g.o0 + (size_t)row * 1024 + col) : (g.o1 + (size_t)row * 1024 + (col - 1024));
;             u32x4 w; w.x = pk(v0[0], v0[1]); w.y = pk(v0[2], v0[3]); w.z = pk(v1[0], v1[1]); w.w = pk(v1[2], v1[3]);
;             gst<u32x4>(base, w);
;           } else if (col < 2080) {
;             gst<f32x4>(g.f0 + (size_t)row * 32 + (col - 2048), v0); gst<f32x4>(g.f0 + (size_t)row * 32 + (col - 2048) + 4, v1);
;           }
.LBB0_357:
	s_nop 1
	v_mov_b32_e32 v128, v238
	s_and_b64 vcc, exec, s[48:49]
	s_mov_b64 s[26:27], -1
	s_waitcnt vmcnt(0)
	v_pk_mul_f32 v[134:135], v[46:47], v[128:129] op_sel_hi:[1,0]
	v_pk_mul_f32 v[132:133], v[44:45], v[128:129] op_sel_hi:[1,0]
	v_pk_mul_f32 v[130:131], v[42:43], v[128:129] op_sel_hi:[1,0]
	v_pk_mul_f32 v[128:129], v[40:41], v[128:129] op_sel_hi:[1,0]
	s_cbranch_vccnz .LBB0_361
	s_and_saveexec_b64 s[26:27], s[50:51]
	s_cbranch_execz .LBB0_360
	v_lshlrev_b64 v[140:141], 7, v[168:169]
	v_lshl_add_u64 v[140:141], s[66:67], 0, v[140:141]
	v_lshl_add_u64 v[140:141], v[194:195], 2, v[140:141]
	global_store_dwordx4 v[140:141], v[132:135], off
	global_store_dwordx4 v[140:141], v[128:131], off offset:16

; DI unsigned pk(float lo, float hi) { f32x2 v = {lo, hi}; bf2_t b = __builtin_convertvector(v, bf2_t); return __builtin_bit_cast(unsigned, b); }
; DI void gemm_epilogue(const GemmDesc& g, f32x4 (&acc)[2][2][4][2], int brow, int bcol, int wr, int wc, int fr, int fq) {
;     ...
;           const int row = rowb + ai * HALF + m * 16;
;           const float ru = gld<float>(g.rowscale + row);
;           f32x4 v0 = acc[ai][bj][m][0] * ru, v1 = acc[ai][bj][m][1] * ru;
;           if (bcol < 2048) {
;             if (bcol < 512) { v0 = v0 * 0.08838834764831845f; v1 = v1 * 0.08838834764831845f; }
;             bf16_t* base = (bcol < 1024) ? (g.o0 + (size_t)row * 1024 + col) : (g.o1 + (size_t)row * 1024 + (col - 1024));
;             u32x4 w; w.x = pk(v0[0], v0[1]); w.y = pk(v0[2], v0[3]); w.z = pk(v1[0], v1[1]); w.w = pk(v1[2], v1[3]);
;             gst<u32x4>(base, w);
;           } else if (col < 2080) {
;             gst<f32x4>(g.f0 + (size_t)row * 32 + (col - 2048), v0); gst<f32x4>(g.f0 + (size_t)row * 32 + (col - 2048) + 4, v1);
;           }
.LBB0_367:
	s_nop 1
	v_mov_b32_e32 v128, v239
	s_and_b64 vcc, exec, s[48:49]
	s_mov_b64 s[26:27], -1
	s_waitcnt vmcnt(0)
	v_pk_mul_f32 v[134:135], v[38:39], v[128:129] op_sel_hi:[1,0]
	v_pk_mul_f32 v[132:133], v[36:37], v[128:129] op_sel_hi:[1,0]
	v_pk_mul_f32 v[130:131], v[34:35], v[128:129] op_sel_hi:[1,0]
	v_pk_mul_f32 v[128:129], v[32:33], v[128:129] op_sel_hi:[1,0]
	s_cbranch_vccnz .LBB0_371
	s_and_saveexec_b64 s[26:27], s[50:51]
	s_cbranch_execz .LBB0_370
	v_lshlrev_b64 v[140:141], 7, v[172:173]
	v_lshl_add_u64 v[140:141], s[66:67], 0, v[140:141]
	v_lshl_add_u64 v[140:141], v[194:195], 2, v[140:141]
	global_store_dwordx4 v[140:141], v[132:135], off
	global_store_dwordx4 v[140:141], v[128:131], off offset:16

; DI unsigned pk(float lo, float hi) { f32x2 v = {lo, hi}; bf2_t b = __builtin_convertvector(v, bf2_t); return __builtin_bit_cast(unsigned, b); }
; DI void gemm_epilogue(const GemmDesc& g, f32x4 (&acc)[2][2][4][2], int brow, int bcol, int wr, int wc, int fr, int fq) {
;     ...
;           const int row = rowb + ai * HALF + m * 16;
;           const float ru = gld<float>(g.rowscale + row);
;           f32x4 v0 = acc[ai][bj][m][0] * ru, v1 = acc[ai][bj][m][1] * ru;
;           if (bcol < 2048) {
;             if (bcol < 512) { v0 = v0 * 0.08838834764831845f; v1 = v1 * 0.08838834764831845f; }
;             bf16_t* base = (bcol < 1024) ? (g.o0 + (size_t)row * 1024 + col) : (g.o1 + (size_t)row * 1024 + (col - 1024));
;             u32x4 w; w.x = pk(v0[0], v0[1]); w.y = pk(v0[2], v0[3]); w.z = pk(v1[0], v1[1]); w.w = pk(v1[2], v1[3]);
;             gst<u32x4>(base, w);
;           } else if (col < 2080) {
;             gst<f32x4>(g.f0 + (size_t)row * 32 + (col - 2048), v0); gst<f32x4>(g.f0 + (size_t)row * 32 + (col - 2048) + 4, v1);
;           }
.LBB0_377:
	s_nop 1
	v_mov_b32_e32 v128, v240
	s_and_b64 vcc, exec, s[48:49]
	s_mov_b64 s[26:27], -1
	s_waitcnt vmcnt(0)
	v_pk_mul_f32 v[134:135], v[30:31], v[128:129] op_sel_hi:[1,0]
	v_pk_mul_f32 v[132:133], v[28:29], v[128:129] op_sel_hi:[1,0]
	v_pk_mul_f32 v[130:131], v[26:27], v[128:129] op_sel_hi:[1,0]
	v_pk_mul_f32 v[128:129], v[24:25], v[128:129] op_sel_hi:[1,0]
	s_cbranch_vccnz .LBB0_381
	s_and_saveexec_b64 s[26:27], s[50:51]
	s_cbranch_execz .LBB0_380
	v_lshlrev_b64 v[140:141], 7, v[176:177]
	v_lshl_add_u64 v[140:141], s[66:67], 0, v[140:141]
	v_lshl_add_u64 v[140:141], v[194:195], 2, v[140:141]
	global_store_dwordx4 v[140:141], v[132:135], off
	global_store_dwordx4 v[140:141], v[128:131], off offset:16

; DI unsigned pk(float lo, float hi) { f32x2 v = {lo, hi}; bf2_t b = __builtin_convertvector(v, bf2_t); return __builtin_bit_cast(unsigned, b); }
; DI void gemm_epilogue(const GemmDesc& g, f32x4 (&acc)[2][2][4][2], int brow, int bcol, int wr, int wc, int fr, int fq) {
;     ...
;           const int row = rowb + ai * HALF + m * 16;
;           const float ru = gld<float>(g.rowscale + row);
;           f32x4 v0 = acc[ai][bj][m][0] * ru, v1 = acc[ai][bj][m][1] * ru;
;           if (bcol < 2048) {
;             if (bcol < 512) { v0 = v0 * 0.08838834764831845f; v1 = v1 * 0.08838834764831845f; }
;             bf16_t* base = (bcol < 1024) ? (g.o0 + (size_t)row * 1024 + col) : (g.o1 + (size_t)row * 1024 + (col - 1024));
;             u32x4 w; w.x = pk(v0[0], v0[1]); w.y = pk(v0[2], v0[3]); w.z = pk(v1[0], v1[1]); w.w = pk(v1[2], v1[3]);
;             gst<u32x4>(base, w);
;           } else if (col < 2080) {
;             gst<f32x4>(g.f0 + (size_t)row * 32 + (col - 2048), v0); gst<f32x4>(g.f0 + (size_t)row * 32 + (col - 2048) + 4, v1);
;           }
.LBB0_387:
	s_nop 1
	v_mov_b32_e32 v128, v241
	s_and_b64 vcc, exec, s[48:49]
	s_mov_b64 s[26:27], -1
	s_waitcnt vmcnt(0)
	v_pk_mul_f32 v[134:135], v[22:23], v[128:129] op_sel_hi:[1,0]
	v_pk_mul_f32 v[132:133], v[20:21], v[128:129] op_sel_hi:[1,0]
	v_pk_mul_f32 v[130:131], v[18:19], v[128:129] op_sel_hi:[1,0]
	v_pk_mul_f32 v[128:129], v[16:17], v[128:129] op_sel_hi:[1,0]
	s_cbranch_vccnz .LBB0_391
	s_and_saveexec_b64 s[26:27], s[50:51]
	s_cbranch_execz .LBB0_390
	v_lshlrev_b64 v[140:141], 7, v[180:181]
	v_lshl_add_u64 v[140:141], s[66:67], 0, v[140:141]
	v_lshl_add_u64 v[140:141], v[194:195], 2, v[140:141]
	global_store_dwordx4 v[140:141], v[132:135], off
	global_store_dwordx4 v[140:141], v[128:131], off offset:16

; DI unsigned pk(float lo, float hi) { f32x2 v = {lo, hi}; bf2_t b = __builtin_convertvector(v, bf2_t); return __builtin_bit_cast(unsigned, b); }
; DI void gemm_epilogue(const GemmDesc& g, f32x4 (&acc)[2][2][4][2], int brow, int bcol, int wr, int wc, int fr, int fq) {
;     ...
;           const int row = rowb + ai * HALF + m * 16;
;           const float ru = gld<float>(g.rowscale + row);
;           f32x4 v0 = acc[ai][bj][m][0] * ru, v1 = acc[ai][bj][m][1] * ru;
;           if (bcol < 2048) {
;             if (bcol < 512) { v0 = v0 * 0.08838834764831845f; v1 = v1 * 0.08838834764831845f; }
;             bf16_t* base = (bcol < 1024) ? (g.o0 + (size_t)row * 1024 + col) : (g.o1 + (size_t)row * 1024 + (col - 1024));
;             u32x4 w; w.x = pk(v0[0], v0[1]); w.y = pk(v0[2], v0[3]); w.z = pk(v1[0], v1[1]); w.w = pk(v1[2], v1[3]);
;             gst<u32x4>(base, w);
;           } else if (col < 2080) {
;             gst<f32x4>(g.f0 + (size_t)row * 32 + (col - 2048), v0); gst<f32x4>(g.f0 + (size_t)row * 32 + (col - 2048) + 4, v1);
;           }
.LBB0_397:
	s_nop 1
	v_mov_b32_e32 v128, v242
	s_and_b64 vcc, exec, s[48:49]
	s_mov_b64 s[26:27], -1
	s_waitcnt vmcnt(0)
	v_pk_mul_f32 v[134:135], v[14:15], v[128:129] op_sel_hi:[1,0]
	v_pk_mul_f32 v[132:133], v[12:13], v[128:129] op_sel_hi:[1,0]
	v_pk_mul_f32 v[130:131], v[10:11], v[128:129] op_sel_hi:[1,0]
	v_pk_mul_f32 v[128:129], v[8:9], v[128:129] op_sel_hi:[1,0]
	s_cbranch_vccnz .LBB0_401
	s_and_saveexec_b64 s[26:27], s[50:51]
	s_cbranch_execz .LBB0_400
	v_lshlrev_b64 v[140:141], 7, v[184:185]
	v_lshl_add_u64 v[140:141], s[66:67], 0, v[140:141]
	v_lshl_add_u64 v[140:141], v[194:195], 2, v[140:141]
	global_store_dwordx4 v[140:141], v[132:135], off
	global_store_dwordx4 v[140:141], v[128:131], off offset:16

; DI unsigned pk(float lo, float hi) { f32x2 v = {lo, hi}; bf2_t b = __builtin_convertvector(v, bf2_t); return __builtin_bit_cast(unsigned, b); }
; DI void gemm_epilogue(const GemmDesc& g, f32x4 (&acc)[2][2][4][2], int brow, int bcol, int wr, int wc, int fr, int fq) {
;     ...
;           const int row = rowb + ai * HALF + m * 16;
;           const float ru = gld<float>(g.rowscale + row);
;           f32x4 v0 = acc[ai][bj][m][0] * ru, v1 = acc[ai][bj][m][1] * ru;
;           if (bcol < 2048) {
;             if (bcol < 512) { v0 = v0 * 0.08838834764831845f; v1 = v1 * 0.08838834764831845f; }
;             bf16_t* base = (bcol < 1024) ? (g.o0 + (size_t)row * 1024 + col) : (g.o1 + (size_t)row * 1024 + (col - 1024));
;             u32x4 w; w.x = pk(v0[0], v0[1]); w.y = pk(v0[2], v0[3]); w.z = pk(v1[0], v1[1]); w.w = pk(v1[2], v1[3]);
;             gst<u32x4>(base, w);
;           } else if (col < 2080) {
;             gst<f32x4>(g.f0 + (size_t)row * 32 + (col - 2048), v0); gst<f32x4>(g.f0 + (size_t)row * 32 + (col - 2048) + 4, v1);
;           }
.LBB0_407:
	s_nop 1
	v_mov_b32_e32 v128, v243
	s_and_b64 vcc, exec, s[48:49]
	s_mov_b64 s[26:27], -1
	s_waitcnt vmcnt(0)
	v_pk_mul_f32 v[134:135], v[6:7], v[128:129] op_sel_hi:[1,0]
	v_pk_mul_f32 v[132:133], v[4:5], v[128:129] op_sel_hi:[1,0]
	v_pk_mul_f32 v[130:131], v[2:3], v[128:129] op_sel_hi:[1,0]
	v_pk_mul_f32 v[128:129], v[0:1], v[128:129] op_sel_hi:[1,0]
	s_cbranch_vccnz .LBB0_411
	s_and_saveexec_b64 s[26:27], s[50:51]
	s_cbranch_execz .LBB0_410
	v_lshlrev_b64 v[138:139], 7, v[188:189]
	v_lshl_add_u64 v[138:139], s[66:67], 0, v[138:139]
	v_lshl_add_u64 v[138:139], v[194:195], 2, v[138:139]
	global_store_dwordx4 v[138:139], v[132:135], off
	global_store_dwordx4 v[138:139], v[128:131], off offset:16

; DI unsigned pk(float lo, float hi) { f32x2 v = {lo, hi}; bf2_t b = __builtin_convertvector(v, bf2_t); return __builtin_bit_cast(unsigned, b); }
; DI void gemm_epilogue(const GemmDesc& g, f32x4 (&acc)[2][2][4][2], int brow, int bcol, int wr, int wc, int fr, int fq) {
;     ...
;         const int col = colb - 2048 + bj * HALF;
; #pragma unroll
;         for (int ai = 0; ai < 2; ++ai)
; #pragma unroll
;           for (int m = 0; m < 4; ++m) {
;             const int row = rowb + ai * HALF + m * 16;
;             const float ru = gld<float>(g.rowscale + row);
;             const f32x4 v0 = acc[ai][bj][m][0] * ru, v1 = acc[ai][bj][m][1] * ru;
;             u32x4 w; w.x = pk(v0[0], v0[1]); w.y = pk(v0[2], v0[3]); w.z = pk(v1[0], v1[1]); w.w = pk(v1[2], v1[3]);
;             gst<u32x4>(g.o1 + (size_t)row * 2048 + col, w);
;           }
.LBB0_418:
	s_cmp_lt_i32 s5, 8
	s_mov_b64 s[26:27], -1
	s_cbranch_scc1 .LBB0_420
	v_ashrrev_i32_e32 v167, 31, v166
	v_lshl_add_u64 v[128:129], v[166:167], 2, s[22:23]
	global_load_dword v236, v[128:129], off
	global_load_dword v237, v[128:129], off offset:64
	global_load_dword v238, v[128:129], off offset:128
	global_load_dword v239, v[128:129], off offset:192
	global_load_dword v240, v[128:129], off offset:512
	global_load_dword v241, v[128:129], off offset:576
	global_load_dword v242, v[128:129], off offset:640
	global_load_dword v243, v[128:129], off offset:704
	global_load_dword v132, v[128:129], off
	v_ashrrev_i32_e32 v165, 31, v164
	s_movk_i32 s26, 0xf000
	v_lshlrev_b64 v[130:131], 1, v[164:165]
	s_mov_b32 s27, -1
	v_lshl_add_u64 v[134:135], v[130:131], 0, s[26:27]
	s_mov_b64 s[26:27], 0x80000
	s_waitcnt vmcnt(0)
	v_pk_mul_f32 v[138:139], v[126:127], v[132:133] op_sel_hi:[1,0]
	v_pk_mul_f32 v[136:137], v[124:125], v[132:133] op_sel_hi:[1,0]
	v_pk_mul_f32 v[140:141], v[122:123], v[132:133] op_sel_hi:[1,0]
	v_pk_mul_f32 v[132:133], v[120:121], v[132:133] op_sel_hi:[1,0]
	v_cvt_pk_bf16_f32 v136, v136, v137
	v_cvt_pk_bf16_f32 v137, v138, v139
	v_cvt_pk_bf16_f32 v138, v132, v133
	v_lshlrev_b64 v[132:133], 12, v[166:167]
	v_lshl_add_u64 v[132:133], s[52:53], 0, v[132:133]
	v_cvt_pk_bf16_f32 v139, v140, v141
	v_lshl_add_u64 v[140:141], v[132:133], 0, v[134:135]
	global_store_dwordx4 v[140:141], v[136:139], off
	s_nop 1
	v_mov_b32_e32 v138, v237
	s_waitcnt vmcnt(0)
	v_pk_mul_f32 v[140:141], v[118:119], v[138:139] op_sel_hi:[1,0]
	v_or_b32_e32 v136, 16, v166
	v_ashrrev_i32_e32 v137, 31, v136
	v_lshlrev_b64 v[136:137], 12, v[136:137]
	v_pk_mul_f32 v[142:143], v[116:117], v[138:139] op_sel_hi:[1,0]
	v_pk_mul_f32 v[168:169], v[114:115], v[138:139] op_sel_hi:[1,0]
	v_pk_mul_f32 v[170:171], v[112:113], v[138:139] op_sel_hi:[1,0]
	v_lshl_add_u64 v[136:137], s[52:53], 0, v[136:137]
	v_cvt_pk_bf16_f32 v138, v142, v143
	v_cvt_pk_bf16_f32 v139, v140, v141
	v_cvt_pk_bf16_f32 v140, v170, v171
	v_cvt_pk_bf16_f32 v141, v168, v169
	v_lshl_add_u64 v[142:143], v[136:137], 0, v[134:135]
	global_store_dwordx4 v[142:143], v[138:141], off
	s_nop 1
	v_mov_b32_e32 v140, v238
	s_waitcnt vmcnt(0)
	v_pk_mul_f32 v[142:143], v[110:111], v[140:141] op_sel_hi:[1,0]
	v_or_b32_e32 v138, 32, v166
	v_ashrrev_i32_e32 v139, 31, v138
	v_lshlrev_b64 v[138:139], 12, v[138:139]
	v_pk_mul_f32 v[168:169], v[108:109], v[140:141] op_sel_hi:[1,0]
	v_pk_mul_f32 v[170:171], v[106:107], v[140:141] op_sel_hi:[1,0]
	v_pk_mul_f32 v[172:173], v[104:105], v[140:141] op_sel_hi:[1,0]
	v_lshl_add_u64 v[138:139], s[52:53], 0, v[138:139]
	v_cvt_pk_bf16_f32 v140, v168, v169
	v_cvt_pk_bf16_f32 v141, v142, v143
	v_cvt_pk_bf16_f32 v142, v172, v173
	v_cvt_pk_bf16_f32 v143, v170, v171
	v_lshl_add_u64 v[168:169], v[138:139], 0, v[134:135]
	global_store_dwordx4 v[168:169], v[140:143], off
	s_nop 1
	v_mov_b32_e32 v142, v239
	s_waitcnt vmcnt(0)
	v_pk_mul_f32 v[170:171], v[102:103], v[142:143] op_sel_hi:[1,0]
	v_or_b32_e32 v140, 48, v166
	v_ashrrev_i32_e32 v141, 31, v140
	v_lshlrev_b64 v[140:141], 12, v[140:141]
	v_pk_mul_f32 v[168:169], v[100:101], v[142:143] op_sel_hi:[1,0]
	v_pk_mul_f32 v[172:173], v[98:99], v[142:143] op_sel_hi:[1,0]
	v_pk_mul_f32 v[142:143], v[96:97], v[142:143] op_sel_hi:[1,0]
	v_lshl_add_u64 v[140:141], s[52:53], 0, v[140:141]
	v_cvt_pk_bf16_f32 v168, v168, v169
	v_cvt_pk_bf16_f32 v169, v170, v171
	v_cvt_pk_bf16_f32 v170, v142, v143
	v_cvt_pk_bf16_f32 v171, v172, v173
	v_lshl_add_u64 v[142:143], v[140:141], 0, v[134:135]
	global_store_dwordx4 v[142:143], v[168:171], off
	s_nop 1
	v_mov_b32_e32 v142, v240
	s_waitcnt vmcnt(0)
	v_pk_mul_f32 v[172:173], v[90:91], v[142:143] op_sel_hi:[1,0]
	v_pk_mul_f32 v[170:171], v[94:95], v[142:143] op_sel_hi:[1,0]
	v_pk_mul_f32 v[168:169], v[92:93], v[142:143] op_sel_hi:[1,0]
	v_pk_mul_f32 v[142:143], v[88:89], v[142:143] op_sel_hi:[1,0]
	v_cvt_pk_bf16_f32 v168, v168, v169
	v_cvt_pk_bf16_f32 v169, v170, v171
	v_cvt_pk_bf16_f32 v170, v142, v143
	v_lshl_add_u64 v[142:143], v[132:133], 0, s[26:27]
	v_cvt_pk_bf16_f32 v171, v172, v173
	v_lshl_add_u64 v[172:173], v[142:143], 0, v[134:135]
	global_store_dwordx4 v[172:173], v[168:171], off
	s_nop 1
	v_mov_b32_e32 v148, v241
	s_mov_b64 s[26:27], 0x90000
	s_waitcnt vmcnt(0)
	v_pk_mul_f32 v[168:169], v[86:87], v[148:149] op_sel_hi:[1,0]
	v_pk_mul_f32 v[170:171], v[84:85], v[148:149] op_sel_hi:[1,0]
	v_pk_mul_f32 v[174:175], v[82:83], v[148:149] op_sel_hi:[1,0]
	v_pk_mul_f32 v[172:173], v[80:81], v[148:149] op_sel_hi:[1,0]
	v_cvt_pk_bf16_f32 v170, v170, v171
	v_cvt_pk_bf16_f32 v171, v168, v169
	v_lshl_add_u64 v[168:169], v[132:133], 0, s[26:27]
	v_cvt_pk_bf16_f32 v172, v172, v173
	v_cvt_pk_bf16_f32 v173, v174, v175
	v_lshl_add_u64 v[174:175], v[168:169], 0, v[134:135]
	global_store_dwordx4 v[174:175], v[170:173], off
	s_nop 1
	v_mov_b32_e32 v148, v242
	s_mov_b64 s[26:27], 0xa0000
	s_waitcnt vmcnt(0)
	v_pk_mul_f32 v[170:171], v[78:79], v[148:149] op_sel_hi:[1,0]
	v_pk_mul_f32 v[172:173], v[76:77], v[148:149] op_sel_hi:[1,0]
	v_pk_mul_f32 v[176:177], v[74:75], v[148:149] op_sel_hi:[1,0]
	v_pk_mul_f32 v[174:175], v[72:73], v[148:149] op_sel_hi:[1,0]
	v_cvt_pk_bf16_f32 v172, v172, v173
	v_cvt_pk_bf16_f32 v173, v170, v171
	v_lshl_add_u64 v[170:171], v[132:133], 0, s[26:27]
	v_cvt_pk_bf16_f32 v174, v174, v175
	v_cvt_pk_bf16_f32 v175, v176, v177
	v_lshl_add_u64 v[176:177], v[170:171], 0, v[134:135]
	global_store_dwordx4 v[176:177], v[172:175], off
	s_nop 1
	v_mov_b32_e32 v148, v243
	s_mov_b64 s[26:27], 0xb0000
	s_waitcnt vmcnt(0)
; DI unsigned pk(float lo, float hi) { f32x2 v = {lo, hi}; bf2_t b = __builtin_convertvector(v, bf2_t); return __builtin_bit_cast(unsigned, b); }
; DI void gemm_epilogue(const GemmDesc& g, f32x4 (&acc)[2][2][4][2], int brow, int bcol, int wr, int wc, int fr, int fq) {
;     ...
;         const int col = colb - 2048 + bj * HALF;
; #pragma unroll
;         for (int ai = 0; ai < 2; ++ai)
; #pragma unroll
;           for (int m = 0; m < 4; ++m) {
;             const int row = rowb + ai * HALF + m * 16;
;             const float ru = gld<float>(g.rowscale + row);
;             const f32x4 v0 = acc[ai][bj][m][0] * ru, v1 = acc[ai][bj][m][1] * ru;
;             u32x4 w; w.x = pk(v0[0], v0[1]); w.y = pk(v0[2], v0[3]); w.z = pk(v1[0], v1[1]); w.w = pk(v1[2], v1[3]);
;             gst<u32x4>(g.o1 + (size_t)row * 2048 + col, w);
;           }
	v_pk_mul_f32 v[172:173], v[70:71], v[148:149] op_sel_hi:[1,0]
	v_pk_mul_f32 v[174:175], v[68:69], v[148:149] op_sel_hi:[1,0]
	v_pk_mul_f32 v[178:179], v[66:67], v[148:149] op_sel_hi:[1,0]
	v_pk_mul_f32 v[176:177], v[64:65], v[148:149] op_sel_hi:[1,0]
	v_cvt_pk_bf16_f32 v174, v174, v175
	v_cvt_pk_bf16_f32 v175, v172, v173
	v_lshl_add_u64 v[172:173], v[132:133], 0, s[26:27]
	v_cvt_pk_bf16_f32 v176, v176, v177
	v_cvt_pk_bf16_f32 v177, v178, v179
	v_lshl_add_u64 v[134:135], v[172:173], 0, v[134:135]
	global_store_dwordx4 v[134:135], v[174:177], off
	s_nop 1
	v_mov_b32_e32 v134, v236
	s_movk_i32 s26, 0xf100
	s_mov_b32 s27, -1
	v_lshl_add_u64 v[130:131], v[130:131], 0, s[26:27]
	v_lshl_add_u64 v[132:133], v[132:133], 0, v[130:131]
	v_lshl_add_u64 v[136:137], v[136:137], 0, v[130:131]
	s_mov_b64 s[26:27], 0
	s_waitcnt vmcnt(0)
	v_pk_mul_f32 v[176:177], v[62:63], v[134:135] op_sel_hi:[1,0]
	v_pk_mul_f32 v[174:175], v[60:61], v[134:135] op_sel_hi:[1,0]
	v_pk_mul_f32 v[178:179], v[58:59], v[134:135] op_sel_hi:[1,0]
	v_pk_mul_f32 v[134:135], v[56:57], v[134:135] op_sel_hi:[1,0]
	v_cvt_pk_bf16_f32 v174, v174, v175
	v_cvt_pk_bf16_f32 v175, v176, v177
	v_cvt_pk_bf16_f32 v176, v134, v135
	v_cvt_pk_bf16_f32 v177, v178, v179
	global_store_dwordx4 v[132:133], v[174:177], off
	s_nop 1
	v_mov_b32_e32 v132, v237
	s_waitcnt vmcnt(0)
	v_pk_mul_f32 v[134:135], v[54:55], v[132:133] op_sel_hi:[1,0]
	v_pk_mul_f32 v[174:175], v[52:53], v[132:133] op_sel_hi:[1,0]
	v_pk_mul_f32 v[176:177], v[50:51], v[132:133] op_sel_hi:[1,0]
	v_pk_mul_f32 v[178:179], v[48:49], v[132:133] op_sel_hi:[1,0]
	v_cvt_pk_bf16_f32 v132, v174, v175
	v_cvt_pk_bf16_f32 v133, v134, v135
	v_cvt_pk_bf16_f32 v134, v178, v179
	v_cvt_pk_bf16_f32 v135, v176, v177
	global_store_dwordx4 v[136:137], v[132:135], off
	s_nop 1
	v_mov_b32_e32 v132, v238
	s_waitcnt vmcnt(0)
	v_pk_mul_f32 v[136:137], v[44:45], v[132:133] op_sel_hi:[1,0]
	v_pk_mul_f32 v[134:135], v[46:47], v[132:133] op_sel_hi:[1,0]
	v_pk_mul_f32 v[174:175], v[42:43], v[132:133] op_sel_hi:[1,0]
	v_pk_mul_f32 v[176:177], v[40:41], v[132:133] op_sel_hi:[1,0]
	v_cvt_pk_bf16_f32 v132, v136, v137
	v_cvt_pk_bf16_f32 v133, v134, v135
	v_cvt_pk_bf16_f32 v134, v176, v177
	v_cvt_pk_bf16_f32 v135, v174, v175
	v_lshl_add_u64 v[136:137], v[138:139], 0, v[130:131]
	global_store_dwordx4 v[136:137], v[132:135], off
	s_nop 1
	v_mov_b32_e32 v132, v239
	s_waitcnt vmcnt(0)
	v_pk_mul_f32 v[136:137], v[36:37], v[132:133] op_sel_hi:[1,0]
	v_pk_mul_f32 v[134:135], v[38:39], v[132:133] op_sel_hi:[1,0]
	v_pk_mul_f32 v[138:139], v[34:35], v[132:133] op_sel_hi:[1,0]
	v_pk_mul_f32 v[174:175], v[32:33], v[132:133] op_sel_hi:[1,0]
	v_cvt_pk_bf16_f32 v132, v136, v137
	v_cvt_pk_bf16_f32 v133, v134, v135
	v_cvt_pk_bf16_f32 v134, v174, v175
	v_cvt_pk_bf16_f32 v135, v138, v139
	v_lshl_add_u64 v[136:137], v[140:141], 0, v[130:131]
	global_store_dwordx4 v[136:137], v[132:135], off
	s_nop 1
	v_mov_b32_e32 v132, v240
	s_waitcnt vmcnt(0)
	v_pk_mul_f32 v[136:137], v[28:29], v[132:133] op_sel_hi:[1,0]
	v_pk_mul_f32 v[134:135], v[30:31], v[132:133] op_sel_hi:[1,0]
	v_pk_mul_f32 v[138:139], v[26:27], v[132:133] op_sel_hi:[1,0]
	v_pk_mul_f32 v[140:141], v[24:25], v[132:133] op_sel_hi:[1,0]
	v_cvt_pk_bf16_f32 v132, v136, v137
	v_cvt_pk_bf16_f32 v133, v134, v135
	v_cvt_pk_bf16_f32 v134, v140, v141
	v_cvt_pk_bf16_f32 v135, v138, v139
	v_lshl_add_u64 v[136:137], v[142:143], 0, v[130:131]
	global_store_dwordx4 v[136:137], v[132:135], off
	s_nop 1
	v_mov_b32_e32 v132, v241
	s_waitcnt vmcnt(0)
	v_pk_mul_f32 v[136:137], v[20:21], v[132:133] op_sel_hi:[1,0]
	v_pk_mul_f32 v[134:135], v[22:23], v[132:133] op_sel_hi:[1,0]
	v_pk_mul_f32 v[138:139], v[18:19], v[132:133] op_sel_hi:[1,0]
	v_pk_mul_f32 v[140:141], v[16:17], v[132:133] op_sel_hi:[1,0]
	v_cvt_pk_bf16_f32 v132, v136, v137
	v_cvt_pk_bf16_f32 v133, v134, v135
	v_cvt_pk_bf16_f32 v134, v140, v141
	v_cvt_pk_bf16_f32 v135, v138, v139
	v_lshl_add_u64 v[136:137], v[168:169], 0, v[130:131]
	global_store_dwordx4 v[136:137], v[132:135], off
	s_nop 1
	v_mov_b32_e32 v132, v242
	s_waitcnt vmcnt(0)
	v_pk_mul_f32 v[136:137], v[12:13], v[132:133] op_sel_hi:[1,0]
	v_pk_mul_f32 v[134:135], v[14:15], v[132:133] op_sel_hi:[1,0]
	v_pk_mul_f32 v[138:139], v[10:11], v[132:133] op_sel_hi:[1,0]
	v_pk_mul_f32 v[140:141], v[8:9], v[132:133] op_sel_hi:[1,0]
	v_cvt_pk_bf16_f32 v132, v136, v137
	v_cvt_pk_bf16_f32 v133, v134, v135
	v_cvt_pk_bf16_f32 v134, v140, v141
	v_cvt_pk_bf16_f32 v135, v138, v139
	v_lshl_add_u64 v[136:137], v[170:171], 0, v[130:131]
	global_store_dwordx4 v[136:137], v[132:135], off
	s_nop 1
	v_mov_b32_e32 v128, v243
	s_waitcnt vmcnt(0)
	v_pk_mul_f32 v[136:137], v[2:3], v[128:129] op_sel_hi:[1,0]
	v_pk_mul_f32 v[134:135], v[6:7], v[128:129] op_sel_hi:[1,0]
	v_pk_mul_f32 v[132:133], v[4:5], v[128:129] op_sel_hi:[1,0]
	v_pk_mul_f32 v[128:129], v[0:1], v[128:129] op_sel_hi:[1,0]
	v_cvt_pk_bf16_f32 v132, v132, v133
	v_cvt_pk_bf16_f32 v133, v134, v135
	v_cvt_pk_bf16_f32 v134, v128, v129
	v_cvt_pk_bf16_f32 v135, v136, v137
	v_lshl_add_u64 v[128:129], v[172:173], 0, v[130:131]
	global_store_dwordx4 v[128:129], v[132:135], off
; DI unsigned pk(float lo, float hi) { f32x2 v = {lo, hi}; bf2_t b = __builtin_convertvector(v, bf2_t); return __builtin_bit_cast(unsigned, b); }
; DI void gemm_epilogue(const GemmDesc& g, f32x4 (&acc)[2][2][4][2], int brow, int bcol, int wr, int wc, int fr, int fq) {
;     ...
;     if (bcol < 2048) {
;       const float sc = (bcol < 1024) ? 0.0625f : 1.0f;
;       const int d0 = wc * 32 + 8 * fq;
;       float fr_[8];
; #pragma unroll
;       for (int j = 0; j < 8; ++j) fr_[j] = exp2f(-(float)(d0 + j) * (13.287712379549449f / 128.0f)) * 0.15915494309189535f;
; #pragma unroll
;       for (int ai = 0; ai < 2; ++ai)
; #pragma unroll
;         for (int m = 0; m < 4; ++m) {
;           const int row = rowb + ai * HALF + m * 16;
;           const float pf = (float)gld<int>(g.pos + row);
;           const float scr = sc * gld<float>(g.rowscale + row);
;           float y1[8], y2[8];
; #pragma unroll
;           for (int n = 0; n < 2; ++n) {
;             const f32x4 x1 = acc[ai][0][m][n], x2 = acc[ai][1][m][n];
; #pragma unroll
;             for (int j = 0; j < 4; ++j) {
;               float rev = pf * fr_[4 * n + j]; rev = rev - rintf(rev);
;               const float sn = __builtin_amdgcn_sinf(rev), cs = __builtin_amdgcn_cosf(rev);
;               y1[4 * n + j] = (x1[j] * cs - x2[j] * sn) * scr; y2[4 * n + j] = (x2[j] * cs + x1[j] * sn) * scr;
;             }
;           }
;           u32x4 w1, w2;
;           w1.x = pk(y1[0], y1[1]); w1.y = pk(y1[2], y1[3]); w1.z = pk(y1[4], y1[5]); w1.w = pk(y1[6], y1[7]);
;           w2.x = pk(y2[0], y2[1]); w2.y = pk(y2[2], y2[3]); w2.z = pk(y2[4], y2[5]); w2.w = pk(y2[6], y2[7]);
;           bf16_t* op = g.o0 + (size_t)row * 2048 + bcol + d0;
;           gst<u32x4>(op, w1); gst<u32x4>(op + 128, w2);
.LBB0_420:
	s_andn2_b64 vcc, exec, s[26:27]
	s_cbranch_vccnz .LBB0_422
	s_cmp_lt_i32 s5, 4
	s_cselect_b64 vcc, -1, 0
	v_mov_b32_e32 v128, 0x3d800000
	v_ashrrev_i32_e32 v167, 31, v166
	v_readlane_b32 s26, v255, 31
	v_cndmask_b32_e32 v165, 1.0, v128, vcc
	v_lshlrev_b64 v[128:129], 2, v[166:167]
	v_readlane_b32 s27, v255, 32
	v_lshl_add_u64 v[138:139], s[22:23], 0, v[128:129]
	s_ashr_i32 s87, s86, 31
	v_lshl_add_u64 v[136:137], s[26:27], 0, v[128:129]
	global_load_dword v236, v[136:137], off
	global_load_dword v237, v[136:137], off offset:64
	global_load_dword v238, v[136:137], off offset:128
	global_load_dword v239, v[136:137], off offset:192
	global_load_dword v240, v[136:137], off offset:512
	global_load_dword v241, v[136:137], off offset:576
	global_load_dword v242, v[136:137], off offset:640
	global_load_dword v243, v[136:137], off offset:704
	global_load_dword v130, v[136:137], off
	global_load_dword v244, v[138:139], off
	global_load_dword v245, v[138:139], off offset:64
	global_load_dword v246, v[138:139], off offset:128
	global_load_dword v247, v[138:139], off offset:192
	global_load_dword v248, v[138:139], off offset:512
	global_load_dword v249, v[138:139], off offset:576
	global_load_dword v251, v[138:139], off offset:640
	global_load_dword v252, v[138:139], off offset:704
	global_load_dword v128, v[138:139], off
	s_lshl_b64 s[26:27], s[86:87], 1
	s_mov_b32 s5, 0x80000
	s_waitcnt vmcnt(0)
	v_cvt_f32_i32_e32 v148, v130
	v_mul_f32_e32 v128, v165, v128
	v_mul_f32_e32 v129, v220, v148
	v_rndne_f32_e32 v129, v129
	v_fma_f32 v129, v220, v148, -v129
	v_sin_f32_e32 v130, v129
	v_cos_f32_e32 v132, v129
	v_mul_f32_e32 v129, v221, v148
	v_rndne_f32_e32 v129, v129
	v_fma_f32 v129, v221, v148, -v129
	v_sin_f32_e32 v131, v129
	v_cos_f32_e32 v133, v129
	v_pk_mul_f32 v[134:135], v[60:61], v[130:131]
	v_pk_mul_f32 v[130:131], v[124:125], v[130:131]
	v_pk_fma_f32 v[134:135], v[124:125], v[132:133], v[134:135] neg_lo:[0,0,1] neg_hi:[0,0,1]
	v_pk_fma_f32 v[130:131], v[60:61], v[132:133], v[130:131]
	v_pk_mul_f32 v[134:135], v[128:129], v[134:135] op_sel_hi:[0,1]
	v_pk_mul_f32 v[132:133], v[128:129], v[130:131] op_sel_hi:[0,1]
	v_mul_f32_e32 v129, v222, v148
	v_rndne_f32_e32 v129, v129
	v_fma_f32 v129, v222, v148, -v129
	v_sin_f32_e32 v130, v129
	v_cos_f32_e32 v140, v129
	v_mul_f32_e32 v129, v223, v148
	v_rndne_f32_e32 v129, v129
	v_fma_f32 v129, v223, v148, -v129
	v_sin_f32_e32 v131, v129
	v_cos_f32_e32 v141, v129
	v_cvt_pk_bf16_f32 v132, v132, v133
	v_pk_mul_f32 v[142:143], v[62:63], v[130:131]
	v_pk_mul_f32 v[130:131], v[126:127], v[130:131]
	v_pk_fma_f32 v[142:143], v[126:127], v[140:141], v[142:143] neg_lo:[0,0,1] neg_hi:[0,0,1]
	v_pk_fma_f32 v[130:131], v[62:63], v[140:141], v[130:131]
	v_pk_mul_f32 v[142:143], v[128:129], v[142:143] op_sel_hi:[0,1]
	v_pk_mul_f32 v[140:141], v[128:129], v[130:131] op_sel_hi:[0,1]
	v_mul_f32_e32 v129, v224, v148
	v_rndne_f32_e32 v129, v129
	v_fma_f32 v129, v224, v148, -v129
	v_sin_f32_e32 v130, v129
	v_cos_f32_e32 v168, v129
	v_mul_f32_e32 v129, v225, v148
	v_rndne_f32_e32 v129, v129
	v_fma_f32 v129, v225, v148, -v129
	v_sin_f32_e32 v131, v129
	v_cos_f32_e32 v169, v129
	v_cvt_pk_bf16_f32 v133, v140, v141
	v_lshlrev_b64 v[140:141], 12, v[166:167]
	v_pk_mul_f32 v[170:171], v[56:57], v[130:131]
	v_lshl_add_u64 v[140:141], s[64:65], 0, v[140:141]
	v_pk_fma_f32 v[170:171], v[120:121], v[168:169], v[170:171] neg_lo:[0,0,1] neg_hi:[0,0,1]
	v_pk_mul_f32 v[168:169], v[56:57], v[168:169]
	v_pk_mul_f32 v[170:171], v[128:129], v[170:171] op_sel_hi:[0,1]
	v_pk_fma_f32 v[130:131], v[120:121], v[130:131], v[168:169]
	v_lshl_add_u64 v[140:141], v[140:141], 0, s[26:27]
	v_pk_mul_f32 v[168:169], v[128:129], v[130:131] op_sel_hi:[0,1]
	v_mul_f32_e32 v129, v226, v148
	v_rndne_f32_e32 v129, v129
	v_fma_f32 v129, v226, v148, -v129
	v_sin_f32_e32 v130, v129
	v_cos_f32_e32 v172, v129
	v_mul_f32_e32 v129, v227, v148
	v_rndne_f32_e32 v129, v129
	v_fma_f32 v129, v227, v148, -v129
	v_sin_f32_e32 v131, v129
	v_cos_f32_e32 v173, v129
	v_lshlrev_b32_e32 v148, 1, v158
	v_lshl_add_u64 v[140:141], v[140:141], 0, v[148:149]
	v_pk_mul_f32 v[174:175], v[58:59], v[130:131]
	s_nop 0
	v_pk_fma_f32 v[174:175], v[122:123], v[172:173], v[174:175] neg_lo:[0,0,1] neg_hi:[0,0,1]
	v_pk_mul_f32 v[172:173], v[58:59], v[172:173]
	v_pk_mul_f32 v[174:175], v[128:129], v[174:175] op_sel_hi:[0,1]
	v_pk_fma_f32 v[130:131], v[122:123], v[130:131], v[172:173]
	s_nop 0
	v_pk_mul_f32 v[172:173], v[128:129], v[130:131] op_sel_hi:[0,1]
	v_cvt_pk_bf16_f32 v128, v134, v135
	v_cvt_pk_bf16_f32 v129, v142, v143
	v_cvt_pk_bf16_f32 v130, v170, v171
	v_cvt_pk_bf16_f32 v131, v174, v175
	v_cvt_pk_bf16_f32 v134, v168, v169
	v_cvt_pk_bf16_f32 v135, v172, v173
	global_store_dwordx4 v[140:141], v[128:131], off
	global_store_dwordx4 v[140:141], v[132:135], off offset:256
	s_nop 1
	v_mov_b32_e32 v128, v237
	v_or_b32_e32 v142, 16, v166
	v_ashrrev_i32_e32 v143, 31, v142
	v_lshlrev_b64 v[142:143], 12, v[142:143]
	v_lshl_add_u64 v[142:143], s[64:65], 0, v[142:143]
	v_lshl_add_u64 v[142:143], v[142:143], 0, s[26:27]
	v_lshl_add_u64 v[142:143], v[142:143], 0, v[148:149]
	s_waitcnt vmcnt(0)
	v_cvt_f32_i32_e32 v129, v128
	s_nop 1
	v_mov_b32_e32 v128, v245
	v_mul_f32_e32 v130, v220, v129
	v_rndne_f32_e32 v130, v130
	v_fma_f32 v131, v220, v129, -v130
	v_sin_f32_e32 v130, v131
	v_cos_f32_e32 v132, v131
	v_mul_f32_e32 v131, v221, v129
	v_rndne_f32_e32 v131, v131
	v_fma_f32 v133, v221, v129, -v131
	v_sin_f32_e32 v131, v133
	v_cos_f32_e32 v133, v133
	v_pk_mul_f32 v[134:135], v[52:53], v[130:131]
	v_pk_mul_f32 v[130:131], v[116:117], v[130:131]
	v_pk_fma_f32 v[134:135], v[116:117], v[132:133], v[134:135] neg_lo:[0,0,1] neg_hi:[0,0,1]
	v_pk_fma_f32 v[130:131], v[52:53], v[132:133], v[130:131]
	s_waitcnt vmcnt(0)
; DI unsigned pk(float lo, float hi) { f32x2 v = {lo, hi}; bf2_t b = __builtin_convertvector(v, bf2_t); return __builtin_bit_cast(unsigned, b); }
; DI void gemm_epilogue(const GemmDesc& g, f32x4 (&acc)[2][2][4][2], int brow, int bcol, int wr, int wc, int fr, int fq) {
;     ...
;           const int row = rowb + ai * HALF + m * 16;
;           const float pf = (float)gld<int>(g.pos + row);
;           const float scr = sc * gld<float>(g.rowscale + row);
;           float y1[8], y2[8];
; #pragma unroll
;           for (int n = 0; n < 2; ++n) {
;             const f32x4 x1 = acc[ai][0][m][n], x2 = acc[ai][1][m][n];
; #pragma unroll
;             for (int j = 0; j < 4; ++j) {
;               float rev = pf * fr_[4 * n + j]; rev = rev - rintf(rev);
;               const float sn = __builtin_amdgcn_sinf(rev), cs = __builtin_amdgcn_cosf(rev);
;               y1[4 * n + j] = (x1[j] * cs - x2[j] * sn) * scr; y2[4 * n + j] = (x2[j] * cs + x1[j] * sn) * scr;
;             }
;           }
;           u32x4 w1, w2;
;           w1.x = pk(y1[0], y1[1]); w1.y = pk(y1[2], y1[3]); w1.z = pk(y1[4], y1[5]); w1.w = pk(y1[6], y1[7]);
;           w2.x = pk(y2[0], y2[1]); w2.y = pk(y2[2], y2[3]); w2.z = pk(y2[4], y2[5]); w2.w = pk(y2[6], y2[7]);
;           bf16_t* op = g.o0 + (size_t)row * 2048 + bcol + d0;
;           gst<u32x4>(op, w1); gst<u32x4>(op + 128, w2);
	v_mul_f32_e32 v128, v165, v128
	v_pk_mul_f32 v[132:133], v[128:129], v[130:131] op_sel_hi:[0,1]
	v_mul_f32_e32 v130, v222, v129
	v_rndne_f32_e32 v130, v130
	v_fma_f32 v131, v222, v129, -v130
	v_sin_f32_e32 v130, v131
	v_cos_f32_e32 v168, v131
	v_mul_f32_e32 v131, v223, v129
	v_rndne_f32_e32 v131, v131
	v_fma_f32 v167, v223, v129, -v131
	v_sin_f32_e32 v131, v167
	v_cos_f32_e32 v169, v167
	v_pk_mul_f32 v[134:135], v[128:129], v[134:135] op_sel_hi:[0,1]
	v_cvt_pk_bf16_f32 v132, v132, v133
	v_pk_mul_f32 v[170:171], v[54:55], v[130:131]
	v_pk_mul_f32 v[130:131], v[118:119], v[130:131]
	v_pk_fma_f32 v[170:171], v[118:119], v[168:169], v[170:171] neg_lo:[0,0,1] neg_hi:[0,0,1]
	v_pk_fma_f32 v[130:131], v[54:55], v[168:169], v[130:131]
	v_pk_mul_f32 v[170:171], v[128:129], v[170:171] op_sel_hi:[0,1]
	v_pk_mul_f32 v[168:169], v[128:129], v[130:131] op_sel_hi:[0,1]
	v_mul_f32_e32 v130, v224, v129
	v_rndne_f32_e32 v130, v130
	v_fma_f32 v131, v224, v129, -v130
	v_sin_f32_e32 v130, v131
	v_cos_f32_e32 v172, v131
	v_mul_f32_e32 v131, v225, v129
	v_rndne_f32_e32 v131, v131
	v_fma_f32 v167, v225, v129, -v131
	v_sin_f32_e32 v131, v167
	v_cos_f32_e32 v173, v167
	v_cvt_pk_bf16_f32 v133, v168, v169
	v_pk_mul_f32 v[174:175], v[48:49], v[130:131]
	s_nop 0
	v_pk_fma_f32 v[174:175], v[112:113], v[172:173], v[174:175] neg_lo:[0,0,1] neg_hi:[0,0,1]
	v_pk_mul_f32 v[172:173], v[48:49], v[172:173]
	v_pk_mul_f32 v[174:175], v[128:129], v[174:175] op_sel_hi:[0,1]
	v_pk_fma_f32 v[130:131], v[112:113], v[130:131], v[172:173]
	s_nop 0
	v_pk_mul_f32 v[172:173], v[128:129], v[130:131] op_sel_hi:[0,1]
	v_mul_f32_e32 v130, v226, v129
	v_rndne_f32_e32 v130, v130
	v_fma_f32 v131, v226, v129, -v130
	v_sin_f32_e32 v130, v131
	v_cos_f32_e32 v176, v131
	v_mul_f32_e32 v131, v227, v129
	v_rndne_f32_e32 v131, v131
	v_fma_f32 v129, v227, v129, -v131
	v_sin_f32_e32 v131, v129
	v_cos_f32_e32 v177, v129
	v_pk_mul_f32 v[178:179], v[50:51], v[130:131]
	s_nop 0
	v_pk_fma_f32 v[178:179], v[114:115], v[176:177], v[178:179] neg_lo:[0,0,1] neg_hi:[0,0,1]
	v_pk_mul_f32 v[176:177], v[50:51], v[176:177]
	v_pk_mul_f32 v[178:179], v[128:129], v[178:179] op_sel_hi:[0,1]
	v_pk_fma_f32 v[130:131], v[114:115], v[130:131], v[176:177]
	s_nop 0
	v_pk_mul_f32 v[176:177], v[128:129], v[130:131] op_sel_hi:[0,1]
	v_cvt_pk_bf16_f32 v128, v134, v135
	v_cvt_pk_bf16_f32 v129, v170, v171
	v_cvt_pk_bf16_f32 v130, v174, v175
	v_cvt_pk_bf16_f32 v131, v178, v179
	v_cvt_pk_bf16_f32 v134, v172, v173
	v_cvt_pk_bf16_f32 v135, v176, v177
	global_store_dwordx4 v[142:143], v[128:131], off
	global_store_dwordx4 v[142:143], v[132:135], off offset:256
	s_nop 1
	v_mov_b32_e32 v128, v238
	v_or_b32_e32 v142, 32, v166
	v_ashrrev_i32_e32 v143, 31, v142
	v_lshlrev_b64 v[142:143], 12, v[142:143]
	v_lshl_add_u64 v[142:143], s[64:65], 0, v[142:143]
	v_lshl_add_u64 v[142:143], v[142:143], 0, s[26:27]
	v_lshl_add_u64 v[142:143], v[142:143], 0, v[148:149]
	s_waitcnt vmcnt(0)
	v_cvt_f32_i32_e32 v129, v128
	s_nop 1
	v_mov_b32_e32 v128, v246
	v_mul_f32_e32 v130, v220, v129
	v_rndne_f32_e32 v130, v130
	v_fma_f32 v131, v220, v129, -v130
	v_sin_f32_e32 v130, v131
	v_cos_f32_e32 v132, v131
	v_mul_f32_e32 v131, v221, v129
	v_rndne_f32_e32 v131, v131
	v_fma_f32 v133, v221, v129, -v131
	v_sin_f32_e32 v131, v133
	v_cos_f32_e32 v133, v133
	v_pk_mul_f32 v[134:135], v[44:45], v[130:131]
	v_pk_mul_f32 v[130:131], v[108:109], v[130:131]
	v_pk_fma_f32 v[134:135], v[108:109], v[132:133], v[134:135] neg_lo:[0,0,1] neg_hi:[0,0,1]
	v_pk_fma_f32 v[130:131], v[44:45], v[132:133], v[130:131]
	s_waitcnt vmcnt(0)
	v_mul_f32_e32 v128, v165, v128
	v_pk_mul_f32 v[132:133], v[128:129], v[130:131] op_sel_hi:[0,1]
	v_mul_f32_e32 v130, v222, v129
	v_rndne_f32_e32 v130, v130
	v_fma_f32 v131, v222, v129, -v130
	v_sin_f32_e32 v130, v131
	v_cos_f32_e32 v168, v131
	v_mul_f32_e32 v131, v223, v129
	v_rndne_f32_e32 v131, v131
	v_fma_f32 v167, v223, v129, -v131
	v_sin_f32_e32 v131, v167
	v_cos_f32_e32 v169, v167
	v_pk_mul_f32 v[134:135], v[128:129], v[134:135] op_sel_hi:[0,1]
	v_cvt_pk_bf16_f32 v132, v132, v133
	v_pk_mul_f32 v[170:171], v[46:47], v[130:131]
	v_pk_mul_f32 v[130:131], v[110:111], v[130:131]
	v_pk_fma_f32 v[170:171], v[110:111], v[168:169], v[170:171] neg_lo:[0,0,1] neg_hi:[0,0,1]
	v_pk_fma_f32 v[130:131], v[46:47], v[168:169], v[130:131]
	v_pk_mul_f32 v[170:171], v[128:129], v[170:171] op_sel_hi:[0,1]
	v_pk_mul_f32 v[168:169], v[128:129], v[130:131] op_sel_hi:[0,1]
	v_mul_f32_e32 v130, v224, v129
	v_rndne_f32_e32 v130, v130
	v_fma_f32 v131, v224, v129, -v130
	v_sin_f32_e32 v130, v131
	v_cos_f32_e32 v172, v131
	v_mul_f32_e32 v131, v225, v129
	v_rndne_f32_e32 v131, v131
	v_fma_f32 v167, v225, v129, -v131
	v_sin_f32_e32 v131, v167
	v_cos_f32_e32 v173, v167
	v_cvt_pk_bf16_f32 v133, v168, v169
	v_pk_mul_f32 v[174:175], v[40:41], v[130:131]
	s_nop 0
	v_pk_fma_f32 v[174:175], v[104:105], v[172:173], v[174:175] neg_lo:[0,0,1] neg_hi:[0,0,1]
	v_pk_mul_f32 v[172:173], v[40:41], v[172:173]
	v_pk_mul_f32 v[174:175], v[128:129], v[174:175] op_sel_hi:[0,1]
	v_pk_fma_f32 v[130:131], v[104:105], v[130:131], v[172:173]
	s_nop 0
	v_pk_mul_f32 v[172:173], v[128:129], v[130:131] op_sel_hi:[0,1]
	v_mul_f32_e32 v130, v226, v129
	v_rndne_f32_e32 v130, v130
	v_fma_f32 v131, v226, v129, -v130
	v_sin_f32_e32 v130, v131
	v_cos_f32_e32 v176, v131
	v_mul_f32_e32 v131, v227, v129
	v_rndne_f32_e32 v131, v131
	v_fma_f32 v129, v227, v129, -v131
	v_sin_f32_e32 v131, v129
	v_cos_f32_e32 v177, v129
	v_pk_mul_f32 v[178:179], v[42:43], v[130:131]
	s_nop 0
	v_pk_fma_f32 v[178:179], v[106:107], v[176:177], v[178:179] neg_lo:[0,0,1] neg_hi:[0,0,1]
	v_pk_mul_f32 v[176:177], v[42:43], v[176:177]
	v_pk_mul_f32 v[178:179], v[128:129], v[178:179] op_sel_hi:[0,1]
	v_pk_fma_f32 v[130:131], v[106:107], v[130:131], v[176:177]
	s_nop 0
	v_pk_mul_f32 v[176:177], v[128:129], v[130:131] op_sel_hi:[0,1]
	v_cvt_pk_bf16_f32 v128, v134, v135
	v_cvt_pk_bf16_f32 v129, v170, v171
	v_cvt_pk_bf16_f32 v130, v174, v175
	v_cvt_pk_bf16_f32 v131, v178, v179
	v_cvt_pk_bf16_f32 v134, v172, v173
	v_cvt_pk_bf16_f32 v135, v176, v177
	global_store_dwordx4 v[142:143], v[128:131], off
	global_store_dwordx4 v[142:143], v[132:135], off offset:256
	s_nop 1
	v_mov_b32_e32 v128, v239
	v_or_b32_e32 v142, 48, v166
	v_ashrrev_i32_e32 v143, 31, v142
	v_lshlrev_b64 v[142:143], 12, v[142:143]
	v_lshl_add_u64 v[142:143], s[64:65], 0, v[142:143]
	v_lshl_add_u64 v[142:143], v[142:143], 0, s[26:27]
	v_lshl_add_u64 v[142:143], v[142:143], 0, v[148:149]
	s_mov_b64 s[26:27], 0x80000
	s_waitcnt vmcnt(0)
; DI unsigned pk(float lo, float hi) { f32x2 v = {lo, hi}; bf2_t b = __builtin_convertvector(v, bf2_t); return __builtin_bit_cast(unsigned, b); }
; DI void gemm_epilogue(const GemmDesc& g, f32x4 (&acc)[2][2][4][2], int brow, int bcol, int wr, int wc, int fr, int fq) {
;     ...
;           const int row = rowb + ai * HALF + m * 16;
;           const float pf = (float)gld<int>(g.pos + row);
;           const float scr = sc * gld<float>(g.rowscale + row);
;           float y1[8], y2[8];
; #pragma unroll
;           for (int n = 0; n < 2; ++n) {
;             const f32x4 x1 = acc[ai][0][m][n], x2 = acc[ai][1][m][n];
; #pragma unroll
;             for (int j = 0; j < 4; ++j) {
;               float rev = pf * fr_[4 * n + j]; rev = rev - rintf(rev);
;               const float sn = __builtin_amdgcn_sinf(rev), cs = __builtin_amdgcn_cosf(rev);
;               y1[4 * n + j] = (x1[j] * cs - x2[j] * sn) * scr; y2[4 * n + j] = (x2[j] * cs + x1[j] * sn) * scr;
;             }
;           }
;           u32x4 w1, w2;
;           w1.x = pk(y1[0], y1[1]); w1.y = pk(y1[2], y1[3]); w1.z = pk(y1[4], y1[5]); w1.w = pk(y1[6], y1[7]);
;           w2.x = pk(y2[0], y2[1]); w2.y = pk(y2[2], y2[3]); w2.z = pk(y2[4], y2[5]); w2.w = pk(y2[6], y2[7]);
;           bf16_t* op = g.o0 + (size_t)row * 2048 + bcol + d0;
;           gst<u32x4>(op, w1); gst<u32x4>(op + 128, w2);
	v_cvt_f32_i32_e32 v129, v128
	s_nop 1
	v_mov_b32_e32 v128, v247
	v_mul_f32_e32 v130, v220, v129
	v_rndne_f32_e32 v130, v130
	v_fma_f32 v131, v220, v129, -v130
	v_sin_f32_e32 v130, v131
	v_cos_f32_e32 v132, v131
	v_mul_f32_e32 v131, v221, v129
	v_rndne_f32_e32 v131, v131
	v_fma_f32 v133, v221, v129, -v131
	v_sin_f32_e32 v131, v133
	v_cos_f32_e32 v133, v133
	v_pk_mul_f32 v[134:135], v[36:37], v[130:131]
	v_pk_mul_f32 v[130:131], v[100:101], v[130:131]
	v_pk_fma_f32 v[134:135], v[100:101], v[132:133], v[134:135] neg_lo:[0,0,1] neg_hi:[0,0,1]
	v_pk_fma_f32 v[130:131], v[36:37], v[132:133], v[130:131]
	s_waitcnt vmcnt(0)
	v_mul_f32_e32 v128, v165, v128
	v_pk_mul_f32 v[132:133], v[128:129], v[130:131] op_sel_hi:[0,1]
	v_mul_f32_e32 v130, v222, v129
	v_rndne_f32_e32 v130, v130
	v_fma_f32 v131, v222, v129, -v130
	v_sin_f32_e32 v130, v131
	v_cos_f32_e32 v168, v131
	v_mul_f32_e32 v131, v223, v129
	v_rndne_f32_e32 v131, v131
	v_fma_f32 v167, v223, v129, -v131
	v_sin_f32_e32 v131, v167
	v_cos_f32_e32 v169, v167
	v_pk_mul_f32 v[134:135], v[128:129], v[134:135] op_sel_hi:[0,1]
	v_cvt_pk_bf16_f32 v132, v132, v133
	v_pk_mul_f32 v[170:171], v[38:39], v[130:131]
	v_pk_mul_f32 v[130:131], v[102:103], v[130:131]
	v_pk_fma_f32 v[170:171], v[102:103], v[168:169], v[170:171] neg_lo:[0,0,1] neg_hi:[0,0,1]
	v_pk_fma_f32 v[130:131], v[38:39], v[168:169], v[130:131]
	v_pk_mul_f32 v[170:171], v[128:129], v[170:171] op_sel_hi:[0,1]
	v_pk_mul_f32 v[168:169], v[128:129], v[130:131] op_sel_hi:[0,1]
	v_mul_f32_e32 v130, v224, v129
	v_rndne_f32_e32 v130, v130
	v_fma_f32 v131, v224, v129, -v130
	v_sin_f32_e32 v130, v131
	v_cos_f32_e32 v172, v131
	v_mul_f32_e32 v131, v225, v129
	v_rndne_f32_e32 v131, v131
	v_fma_f32 v167, v225, v129, -v131
	v_sin_f32_e32 v131, v167
	v_cos_f32_e32 v173, v167
	v_cvt_pk_bf16_f32 v133, v168, v169
	v_pk_mul_f32 v[174:175], v[32:33], v[130:131]
	s_nop 0
	v_pk_fma_f32 v[174:175], v[96:97], v[172:173], v[174:175] neg_lo:[0,0,1] neg_hi:[0,0,1]
	v_pk_mul_f32 v[172:173], v[32:33], v[172:173]
	v_pk_mul_f32 v[174:175], v[128:129], v[174:175] op_sel_hi:[0,1]
	v_pk_fma_f32 v[130:131], v[96:97], v[130:131], v[172:173]
	s_nop 0
	v_pk_mul_f32 v[172:173], v[128:129], v[130:131] op_sel_hi:[0,1]
	v_mul_f32_e32 v130, v226, v129
	v_rndne_f32_e32 v130, v130
	v_fma_f32 v131, v226, v129, -v130
	v_sin_f32_e32 v130, v131
	v_cos_f32_e32 v176, v131
	v_mul_f32_e32 v131, v227, v129
	v_rndne_f32_e32 v131, v131
	v_fma_f32 v129, v227, v129, -v131
	v_sin_f32_e32 v131, v129
	v_cos_f32_e32 v177, v129
	v_pk_mul_f32 v[178:179], v[34:35], v[130:131]
	s_nop 0
	v_pk_fma_f32 v[178:179], v[98:99], v[176:177], v[178:179] neg_lo:[0,0,1] neg_hi:[0,0,1]
	v_pk_mul_f32 v[176:177], v[34:35], v[176:177]
	v_pk_mul_f32 v[178:179], v[128:129], v[178:179] op_sel_hi:[0,1]
	v_pk_fma_f32 v[130:131], v[98:99], v[130:131], v[176:177]
	s_nop 0
	v_pk_mul_f32 v[176:177], v[128:129], v[130:131] op_sel_hi:[0,1]
	v_cvt_pk_bf16_f32 v128, v134, v135
	v_cvt_pk_bf16_f32 v129, v170, v171
	v_cvt_pk_bf16_f32 v130, v174, v175
	v_cvt_pk_bf16_f32 v131, v178, v179
	v_cvt_pk_bf16_f32 v134, v172, v173
	v_cvt_pk_bf16_f32 v135, v176, v177
	global_store_dwordx4 v[142:143], v[128:131], off
	global_store_dwordx4 v[142:143], v[132:135], off offset:256
	s_nop 1
	v_mov_b32_e32 v128, v240
	s_waitcnt vmcnt(0)
	v_cvt_f32_i32_e32 v129, v128
	s_nop 1
	v_mov_b32_e32 v128, v248
	v_mul_f32_e32 v130, v220, v129
	v_rndne_f32_e32 v130, v130
	v_fma_f32 v131, v220, v129, -v130
	v_sin_f32_e32 v130, v131
	v_cos_f32_e32 v132, v131
	v_mul_f32_e32 v131, v221, v129
	v_rndne_f32_e32 v131, v131
	v_fma_f32 v133, v221, v129, -v131
	v_sin_f32_e32 v131, v133
	v_cos_f32_e32 v133, v133
	v_pk_mul_f32 v[134:135], v[28:29], v[130:131]
	v_pk_mul_f32 v[130:131], v[92:93], v[130:131]
	v_pk_fma_f32 v[134:135], v[92:93], v[132:133], v[134:135] neg_lo:[0,0,1] neg_hi:[0,0,1]
	v_pk_fma_f32 v[130:131], v[28:29], v[132:133], v[130:131]
	s_waitcnt vmcnt(0)
	v_mul_f32_e32 v128, v165, v128
	v_pk_mul_f32 v[132:133], v[128:129], v[130:131] op_sel_hi:[0,1]
	v_mul_f32_e32 v130, v222, v129
	v_rndne_f32_e32 v130, v130
	v_fma_f32 v131, v222, v129, -v130
	v_sin_f32_e32 v130, v131
	v_cos_f32_e32 v142, v131
	v_mul_f32_e32 v131, v223, v129
	v_rndne_f32_e32 v131, v131
	v_fma_f32 v143, v223, v129, -v131
	v_sin_f32_e32 v131, v143
	v_cos_f32_e32 v143, v143
	v_pk_mul_f32 v[134:135], v[128:129], v[134:135] op_sel_hi:[0,1]
	v_cvt_pk_bf16_f32 v132, v132, v133
	v_pk_mul_f32 v[168:169], v[30:31], v[130:131]
	v_pk_mul_f32 v[130:131], v[94:95], v[130:131]
	v_pk_fma_f32 v[168:169], v[94:95], v[142:143], v[168:169] neg_lo:[0,0,1] neg_hi:[0,0,1]
	v_pk_fma_f32 v[130:131], v[30:31], v[142:143], v[130:131]
	v_pk_mul_f32 v[168:169], v[128:129], v[168:169] op_sel_hi:[0,1]
	v_pk_mul_f32 v[142:143], v[128:129], v[130:131] op_sel_hi:[0,1]
	v_mul_f32_e32 v130, v224, v129
	v_rndne_f32_e32 v130, v130
	v_fma_f32 v131, v224, v129, -v130
	v_sin_f32_e32 v130, v131
	v_cos_f32_e32 v170, v131
	v_mul_f32_e32 v131, v225, v129
	v_rndne_f32_e32 v131, v131
	v_fma_f32 v148, v225, v129, -v131
	v_sin_f32_e32 v131, v148
	v_cos_f32_e32 v171, v148
	v_cvt_pk_bf16_f32 v133, v142, v143
	v_lshl_add_u64 v[142:143], v[140:141], 0, s[26:27]
	v_pk_mul_f32 v[172:173], v[24:25], v[130:131]
	s_mov_b64 s[26:27], 0x90000
	v_pk_fma_f32 v[172:173], v[88:89], v[170:171], v[172:173] neg_lo:[0,0,1] neg_hi:[0,0,1]
	v_pk_mul_f32 v[170:171], v[24:25], v[170:171]
	v_pk_mul_f32 v[172:173], v[128:129], v[172:173] op_sel_hi:[0,1]
	v_pk_fma_f32 v[130:131], v[88:89], v[130:131], v[170:171]
	s_nop 0
	v_pk_mul_f32 v[170:171], v[128:129], v[130:131] op_sel_hi:[0,1]
	v_mul_f32_e32 v130, v226, v129
	v_rndne_f32_e32 v130, v130
	v_fma_f32 v131, v226, v129, -v130
	v_sin_f32_e32 v130, v131
	v_cos_f32_e32 v174, v131
	v_mul_f32_e32 v131, v227, v129
	v_rndne_f32_e32 v131, v131
	v_fma_f32 v129, v227, v129, -v131
	v_sin_f32_e32 v131, v129
	v_cos_f32_e32 v175, v129
	v_pk_mul_f32 v[176:177], v[26:27], v[130:131]
	s_nop 0
	v_pk_fma_f32 v[176:177], v[90:91], v[174:175], v[176:177] neg_lo:[0,0,1] neg_hi:[0,0,1]
	v_pk_mul_f32 v[174:175], v[26:27], v[174:175]
	v_pk_mul_f32 v[176:177], v[128:129], v[176:177] op_sel_hi:[0,1]
	v_pk_fma_f32 v[130:131], v[90:91], v[130:131], v[174:175]
	s_nop 0
	v_pk_mul_f32 v[174:175], v[128:129], v[130:131] op_sel_hi:[0,1]
	v_cvt_pk_bf16_f32 v129, v168, v169
	v_add_co_u32_e32 v168, vcc, s5, v140
	v_cvt_pk_bf16_f32 v128, v134, v135
	v_cvt_pk_bf16_f32 v130, v172, v173
	v_cvt_pk_bf16_f32 v131, v176, v177
	v_addc_co_u32_e32 v169, vcc, 0, v141, vcc
	v_cvt_pk_bf16_f32 v134, v170, v171
	v_cvt_pk_bf16_f32 v135, v174, v175
	global_store_dwordx4 v[168:169], v[128:131], off
	global_store_dwordx4 v[142:143], v[132:135], off offset:256
	s_nop 1
	v_mov_b32_e32 v128, v241
	s_mov_b32 s5, 0x90000
	s_waitcnt vmcnt(0)
; DI unsigned pk(float lo, float hi) { f32x2 v = {lo, hi}; bf2_t b = __builtin_convertvector(v, bf2_t); return __builtin_bit_cast(unsigned, b); }
; DI void gemm_epilogue(const GemmDesc& g, f32x4 (&acc)[2][2][4][2], int brow, int bcol, int wr, int wc, int fr, int fq) {
;     ...
;           const int row = rowb + ai * HALF + m * 16;
;           const float pf = (float)gld<int>(g.pos + row);
;           const float scr = sc * gld<float>(g.rowscale + row);
;           float y1[8], y2[8];
; #pragma unroll
;           for (int n = 0; n < 2; ++n) {
;             const f32x4 x1 = acc[ai][0][m][n], x2 = acc[ai][1][m][n];
; #pragma unroll
;             for (int j = 0; j < 4; ++j) {
;               float rev = pf * fr_[4 * n + j]; rev = rev - rintf(rev);
;               const float sn = __builtin_amdgcn_sinf(rev), cs = __builtin_amdgcn_cosf(rev);
;               y1[4 * n + j] = (x1[j] * cs - x2[j] * sn) * scr; y2[4 * n + j] = (x2[j] * cs + x1[j] * sn) * scr;
;             }
;           }
;           u32x4 w1, w2;
;           w1.x = pk(y1[0], y1[1]); w1.y = pk(y1[2], y1[3]); w1.z = pk(y1[4], y1[5]); w1.w = pk(y1[6], y1[7]);
;           w2.x = pk(y2[0], y2[1]); w2.y = pk(y2[2], y2[3]); w2.z = pk(y2[4], y2[5]); w2.w = pk(y2[6], y2[7]);
;           bf16_t* op = g.o0 + (size_t)row * 2048 + bcol + d0;
;           gst<u32x4>(op, w1); gst<u32x4>(op + 128, w2);
	v_cvt_f32_i32_e32 v129, v128
	s_nop 1
	v_mov_b32_e32 v128, v249
	v_mul_f32_e32 v130, v220, v129
	v_rndne_f32_e32 v130, v130
	v_fma_f32 v131, v220, v129, -v130
	v_sin_f32_e32 v130, v131
	v_cos_f32_e32 v132, v131
	v_mul_f32_e32 v131, v221, v129
	v_rndne_f32_e32 v131, v131
	v_fma_f32 v133, v221, v129, -v131
	v_sin_f32_e32 v131, v133
	v_cos_f32_e32 v133, v133
	v_pk_mul_f32 v[134:135], v[20:21], v[130:131]
	v_pk_mul_f32 v[130:131], v[84:85], v[130:131]
	v_pk_fma_f32 v[134:135], v[84:85], v[132:133], v[134:135] neg_lo:[0,0,1] neg_hi:[0,0,1]
	v_pk_fma_f32 v[130:131], v[20:21], v[132:133], v[130:131]
	s_waitcnt vmcnt(0)
	v_mul_f32_e32 v128, v165, v128
	v_pk_mul_f32 v[132:133], v[128:129], v[130:131] op_sel_hi:[0,1]
	v_mul_f32_e32 v130, v222, v129
	v_rndne_f32_e32 v130, v130
	v_fma_f32 v131, v222, v129, -v130
	v_sin_f32_e32 v130, v131
	v_cos_f32_e32 v142, v131
	v_mul_f32_e32 v131, v223, v129
	v_rndne_f32_e32 v131, v131
	v_fma_f32 v143, v223, v129, -v131
	v_sin_f32_e32 v131, v143
	v_cos_f32_e32 v143, v143
	v_pk_mul_f32 v[134:135], v[128:129], v[134:135] op_sel_hi:[0,1]
	v_cvt_pk_bf16_f32 v132, v132, v133
	v_pk_mul_f32 v[168:169], v[22:23], v[130:131]
	v_pk_mul_f32 v[130:131], v[86:87], v[130:131]
	v_pk_fma_f32 v[168:169], v[86:87], v[142:143], v[168:169] neg_lo:[0,0,1] neg_hi:[0,0,1]
	v_pk_fma_f32 v[130:131], v[22:23], v[142:143], v[130:131]
	v_pk_mul_f32 v[168:169], v[128:129], v[168:169] op_sel_hi:[0,1]
	v_pk_mul_f32 v[142:143], v[128:129], v[130:131] op_sel_hi:[0,1]
	v_mul_f32_e32 v130, v224, v129
	v_rndne_f32_e32 v130, v130
	v_fma_f32 v131, v224, v129, -v130
	v_sin_f32_e32 v130, v131
	v_cos_f32_e32 v170, v131
	v_mul_f32_e32 v131, v225, v129
	v_rndne_f32_e32 v131, v131
	v_fma_f32 v148, v225, v129, -v131
	v_sin_f32_e32 v131, v148
	v_cos_f32_e32 v171, v148
	v_cvt_pk_bf16_f32 v133, v142, v143
	v_lshl_add_u64 v[142:143], v[140:141], 0, s[26:27]
	v_pk_mul_f32 v[172:173], v[16:17], v[130:131]
	s_mov_b64 s[26:27], 0xa0000
	v_pk_fma_f32 v[172:173], v[80:81], v[170:171], v[172:173] neg_lo:[0,0,1] neg_hi:[0,0,1]
	v_pk_mul_f32 v[170:171], v[16:17], v[170:171]
	v_pk_mul_f32 v[172:173], v[128:129], v[172:173] op_sel_hi:[0,1]
	v_pk_fma_f32 v[130:131], v[80:81], v[130:131], v[170:171]
	s_nop 0
	v_pk_mul_f32 v[170:171], v[128:129], v[130:131] op_sel_hi:[0,1]
	v_mul_f32_e32 v130, v226, v129
	v_rndne_f32_e32 v130, v130
	v_fma_f32 v131, v226, v129, -v130
	v_sin_f32_e32 v130, v131
	v_cos_f32_e32 v174, v131
	v_mul_f32_e32 v131, v227, v129
	v_rndne_f32_e32 v131, v131
	v_fma_f32 v129, v227, v129, -v131
	v_sin_f32_e32 v131, v129
	v_cos_f32_e32 v175, v129
	v_pk_mul_f32 v[176:177], v[18:19], v[130:131]
	s_nop 0
	v_pk_fma_f32 v[176:177], v[82:83], v[174:175], v[176:177] neg_lo:[0,0,1] neg_hi:[0,0,1]
	v_pk_mul_f32 v[174:175], v[18:19], v[174:175]
	v_pk_mul_f32 v[176:177], v[128:129], v[176:177] op_sel_hi:[0,1]
	v_pk_fma_f32 v[130:131], v[82:83], v[130:131], v[174:175]
	s_nop 0
	v_pk_mul_f32 v[174:175], v[128:129], v[130:131] op_sel_hi:[0,1]
	v_cvt_pk_bf16_f32 v129, v168, v169
	v_add_co_u32_e32 v168, vcc, s5, v140
	v_cvt_pk_bf16_f32 v128, v134, v135
	v_cvt_pk_bf16_f32 v130, v172, v173
	v_cvt_pk_bf16_f32 v131, v176, v177
	v_addc_co_u32_e32 v169, vcc, 0, v141, vcc
	v_cvt_pk_bf16_f32 v134, v170, v171
	v_cvt_pk_bf16_f32 v135, v174, v175
	global_store_dwordx4 v[168:169], v[128:131], off
	global_store_dwordx4 v[142:143], v[132:135], off offset:256
	s_nop 1
	v_mov_b32_e32 v128, v242
	s_mov_b32 s5, 0xa0000
	s_waitcnt vmcnt(0)
	v_cvt_f32_i32_e32 v129, v128
	s_nop 1
	v_mov_b32_e32 v128, v251
	v_mul_f32_e32 v130, v220, v129
	v_rndne_f32_e32 v130, v130
	v_fma_f32 v131, v220, v129, -v130
	v_sin_f32_e32 v130, v131
	v_cos_f32_e32 v132, v131
	v_mul_f32_e32 v131, v221, v129
	v_rndne_f32_e32 v131, v131
	v_fma_f32 v133, v221, v129, -v131
	v_sin_f32_e32 v131, v133
	v_cos_f32_e32 v133, v133
	v_pk_mul_f32 v[134:135], v[12:13], v[130:131]
	v_pk_mul_f32 v[130:131], v[76:77], v[130:131]
	v_pk_fma_f32 v[134:135], v[76:77], v[132:133], v[134:135] neg_lo:[0,0,1] neg_hi:[0,0,1]
	v_pk_fma_f32 v[130:131], v[12:13], v[132:133], v[130:131]
	s_waitcnt vmcnt(0)
; DI unsigned pk(float lo, float hi) { f32x2 v = {lo, hi}; bf2_t b = __builtin_convertvector(v, bf2_t); return __builtin_bit_cast(unsigned, b); }
; DI void gemm_epilogue(const GemmDesc& g, f32x4 (&acc)[2][2][4][2], int brow, int bcol, int wr, int wc, int fr, int fq) {
;     ...
;           const int row = rowb + ai * HALF + m * 16;
;           const float pf = (float)gld<int>(g.pos + row);
;           const float scr = sc * gld<float>(g.rowscale + row);
;           float y1[8], y2[8];
; #pragma unroll
;           for (int n = 0; n < 2; ++n) {
;             const f32x4 x1 = acc[ai][0][m][n], x2 = acc[ai][1][m][n];
; #pragma unroll
;             for (int j = 0; j < 4; ++j) {
;               float rev = pf * fr_[4 * n + j]; rev = rev - rintf(rev);
;               const float sn = __builtin_amdgcn_sinf(rev), cs = __builtin_amdgcn_cosf(rev);
;               y1[4 * n + j] = (x1[j] * cs - x2[j] * sn) * scr; y2[4 * n + j] = (x2[j] * cs + x1[j] * sn) * scr;
;             }
;           }
;           u32x4 w1, w2;
;           w1.x = pk(y1[0], y1[1]); w1.y = pk(y1[2], y1[3]); w1.z = pk(y1[4], y1[5]); w1.w = pk(y1[6], y1[7]);
;           w2.x = pk(y2[0], y2[1]); w2.y = pk(y2[2], y2[3]); w2.z = pk(y2[4], y2[5]); w2.w = pk(y2[6], y2[7]);
;           bf16_t* op = g.o0 + (size_t)row * 2048 + bcol + d0;
;           gst<u32x4>(op, w1); gst<u32x4>(op + 128, w2);
	v_mul_f32_e32 v128, v165, v128
	v_pk_mul_f32 v[132:133], v[128:129], v[130:131] op_sel_hi:[0,1]
	v_mul_f32_e32 v130, v222, v129
	v_rndne_f32_e32 v130, v130
	v_fma_f32 v131, v222, v129, -v130
	v_sin_f32_e32 v130, v131
	v_cos_f32_e32 v142, v131
	v_mul_f32_e32 v131, v223, v129
	v_rndne_f32_e32 v131, v131
	v_fma_f32 v143, v223, v129, -v131
	v_sin_f32_e32 v131, v143
	v_cos_f32_e32 v143, v143
	v_pk_mul_f32 v[134:135], v[128:129], v[134:135] op_sel_hi:[0,1]
	v_cvt_pk_bf16_f32 v132, v132, v133
	v_pk_mul_f32 v[168:169], v[14:15], v[130:131]
	v_pk_mul_f32 v[130:131], v[78:79], v[130:131]
	v_pk_fma_f32 v[168:169], v[78:79], v[142:143], v[168:169] neg_lo:[0,0,1] neg_hi:[0,0,1]
	v_pk_fma_f32 v[130:131], v[14:15], v[142:143], v[130:131]
	v_pk_mul_f32 v[168:169], v[128:129], v[168:169] op_sel_hi:[0,1]
	v_pk_mul_f32 v[142:143], v[128:129], v[130:131] op_sel_hi:[0,1]
	v_mul_f32_e32 v130, v224, v129
	v_rndne_f32_e32 v130, v130
	v_fma_f32 v131, v224, v129, -v130
	v_sin_f32_e32 v130, v131
	v_cos_f32_e32 v170, v131
	v_mul_f32_e32 v131, v225, v129
	v_rndne_f32_e32 v131, v131
	v_fma_f32 v148, v225, v129, -v131
	v_sin_f32_e32 v131, v148
	v_cos_f32_e32 v171, v148
	v_cvt_pk_bf16_f32 v133, v142, v143
	v_lshl_add_u64 v[142:143], v[140:141], 0, s[26:27]
	v_pk_mul_f32 v[172:173], v[8:9], v[130:131]
	s_mov_b64 s[26:27], 0xb0000
	v_pk_fma_f32 v[172:173], v[72:73], v[170:171], v[172:173] neg_lo:[0,0,1] neg_hi:[0,0,1]
	v_pk_mul_f32 v[170:171], v[8:9], v[170:171]
	v_pk_mul_f32 v[172:173], v[128:129], v[172:173] op_sel_hi:[0,1]
	v_pk_fma_f32 v[130:131], v[72:73], v[130:131], v[170:171]
	s_nop 0
	v_pk_mul_f32 v[170:171], v[128:129], v[130:131] op_sel_hi:[0,1]
	v_mul_f32_e32 v130, v226, v129
	v_rndne_f32_e32 v130, v130
	v_fma_f32 v131, v226, v129, -v130
	v_sin_f32_e32 v130, v131
	v_cos_f32_e32 v174, v131
	v_mul_f32_e32 v131, v227, v129
	v_rndne_f32_e32 v131, v131
	v_fma_f32 v129, v227, v129, -v131
	v_sin_f32_e32 v131, v129
	v_cos_f32_e32 v175, v129
	v_pk_mul_f32 v[176:177], v[10:11], v[130:131]
	s_nop 0
	v_pk_fma_f32 v[176:177], v[74:75], v[174:175], v[176:177] neg_lo:[0,0,1] neg_hi:[0,0,1]
	v_pk_mul_f32 v[174:175], v[10:11], v[174:175]
	v_pk_mul_f32 v[176:177], v[128:129], v[176:177] op_sel_hi:[0,1]
	v_pk_fma_f32 v[130:131], v[74:75], v[130:131], v[174:175]
	s_nop 0
	v_pk_mul_f32 v[174:175], v[128:129], v[130:131] op_sel_hi:[0,1]
	v_cvt_pk_bf16_f32 v129, v168, v169
	v_add_co_u32_e32 v168, vcc, s5, v140
	v_cvt_pk_bf16_f32 v128, v134, v135
	v_cvt_pk_bf16_f32 v130, v172, v173
	v_cvt_pk_bf16_f32 v131, v176, v177
	v_addc_co_u32_e32 v169, vcc, 0, v141, vcc
	v_cvt_pk_bf16_f32 v134, v170, v171
	v_cvt_pk_bf16_f32 v135, v174, v175
	global_store_dwordx4 v[168:169], v[128:131], off
	global_store_dwordx4 v[142:143], v[132:135], off offset:256
	s_nop 1
	v_mov_b32_e32 v128, v243
	s_waitcnt vmcnt(0)
	v_cvt_f32_i32_e32 v129, v128
	s_nop 1
	v_mov_b32_e32 v128, v252
	v_mul_f32_e32 v130, v220, v129
	v_rndne_f32_e32 v130, v130
	v_fma_f32 v131, v220, v129, -v130
	v_sin_f32_e32 v130, v131
	v_cos_f32_e32 v132, v131
	v_mul_f32_e32 v131, v221, v129
	v_rndne_f32_e32 v131, v131
	v_fma_f32 v133, v221, v129, -v131
	v_sin_f32_e32 v131, v133
	v_cos_f32_e32 v133, v133
	v_pk_mul_f32 v[134:135], v[4:5], v[130:131]
	v_pk_mul_f32 v[130:131], v[68:69], v[130:131]
	v_pk_fma_f32 v[134:135], v[68:69], v[132:133], v[134:135] neg_lo:[0,0,1] neg_hi:[0,0,1]
	v_pk_fma_f32 v[130:131], v[4:5], v[132:133], v[130:131]
	s_waitcnt vmcnt(0)
	v_mul_f32_e32 v128, v165, v128
	v_pk_mul_f32 v[132:133], v[128:129], v[130:131] op_sel_hi:[0,1]
	v_mul_f32_e32 v130, v222, v129
	v_rndne_f32_e32 v130, v130
	v_fma_f32 v131, v222, v129, -v130
	v_sin_f32_e32 v130, v131
	v_cos_f32_e32 v136, v131
	v_mul_f32_e32 v131, v223, v129
	v_rndne_f32_e32 v131, v131
	v_fma_f32 v137, v223, v129, -v131
	v_sin_f32_e32 v131, v137
	v_cos_f32_e32 v137, v137
	v_pk_mul_f32 v[134:135], v[128:129], v[134:135] op_sel_hi:[0,1]
	v_cvt_pk_bf16_f32 v132, v132, v133
	v_pk_mul_f32 v[138:139], v[6:7], v[130:131]
	v_pk_mul_f32 v[130:131], v[70:71], v[130:131]
	v_pk_fma_f32 v[138:139], v[70:71], v[136:137], v[138:139] neg_lo:[0,0,1] neg_hi:[0,0,1]
	v_pk_fma_f32 v[130:131], v[6:7], v[136:137], v[130:131]
	v_pk_mul_f32 v[138:139], v[128:129], v[138:139] op_sel_hi:[0,1]
	v_pk_mul_f32 v[136:137], v[128:129], v[130:131] op_sel_hi:[0,1]
	v_mul_f32_e32 v130, v224, v129
	v_rndne_f32_e32 v130, v130
	v_fma_f32 v131, v224, v129, -v130
	v_sin_f32_e32 v130, v131
	v_cos_f32_e32 v142, v131
	v_mul_f32_e32 v131, v225, v129
	v_rndne_f32_e32 v131, v131
	v_fma_f32 v143, v225, v129, -v131
	v_sin_f32_e32 v131, v143
	v_cos_f32_e32 v143, v143
	v_cvt_pk_bf16_f32 v133, v136, v137
	v_lshl_add_u64 v[136:137], v[140:141], 0, s[26:27]
	v_pk_mul_f32 v[168:169], v[0:1], v[130:131]
	s_nop 0
	v_pk_fma_f32 v[168:169], v[64:65], v[142:143], v[168:169] neg_lo:[0,0,1] neg_hi:[0,0,1]
	v_pk_mul_f32 v[142:143], v[0:1], v[142:143]
	v_pk_mul_f32 v[168:169], v[128:129], v[168:169] op_sel_hi:[0,1]
	v_pk_fma_f32 v[130:131], v[64:65], v[130:131], v[142:143]
	s_nop 0
	v_pk_mul_f32 v[142:143], v[128:129], v[130:131] op_sel_hi:[0,1]
	v_mul_f32_e32 v130, v226, v129
	v_rndne_f32_e32 v130, v130
	v_fma_f32 v131, v226, v129, -v130
	v_sin_f32_e32 v130, v131
	v_cos_f32_e32 v170, v131
	v_mul_f32_e32 v131, v227, v129
	v_rndne_f32_e32 v131, v131
	v_fma_f32 v129, v227, v129, -v131
	v_sin_f32_e32 v131, v129
	v_cos_f32_e32 v171, v129
	v_pk_mul_f32 v[172:173], v[2:3], v[130:131]
	s_nop 0
	v_pk_fma_f32 v[172:173], v[66:67], v[170:171], v[172:173] neg_lo:[0,0,1] neg_hi:[0,0,1]
	v_pk_mul_f32 v[170:171], v[2:3], v[170:171]
	v_pk_mul_f32 v[172:173], v[128:129], v[172:173] op_sel_hi:[0,1]
	v_pk_fma_f32 v[130:131], v[66:67], v[130:131], v[170:171]
	s_nop 0
	v_pk_mul_f32 v[170:171], v[128:129], v[130:131] op_sel_hi:[0,1]
	v_cvt_pk_bf16_f32 v129, v138, v139
	v_add_co_u32_e32 v138, vcc, 0xb0000, v140
	v_cvt_pk_bf16_f32 v128, v134, v135
	v_cvt_pk_bf16_f32 v130, v168, v169
	v_cvt_pk_bf16_f32 v131, v172, v173
	v_addc_co_u32_e32 v139, vcc, 0, v141, vcc
	v_cvt_pk_bf16_f32 v134, v142, v143
	v_cvt_pk_bf16_f32 v135, v170, v171
	global_store_dwordx4 v[138:139], v[128:131], off
	global_store_dwordx4 v[136:137], v[132:135], off offset:256
	s_branch .LBB0_423
